# combo1 + all s_setprio removed from GEMM main loops
# baseline (speedup 1.0000x reference)
; #define PG8_STAGE(bufoff, gbase, voff) do { _Pragma("unroll") for (int _i = 0; _i < 2; ++_i) \
;         __builtin_amdgcn_global_load_lds((const unsigned*)((const char*)(gbase) + (voff)[_i]), (PG8_LAS unsigned*)(lds + (bufoff) + ldsw + _i * 8192), 16, 0, 0); } while (0)
; #define PG8_LDA(dst, b, h) do { _Pragma("unroll") for (int m = 0; m < 4; ++m) _Pragma("unroll") for (int k = 0; k < 2; ++k) dst[m][k] = *(const PG8_LAS bf16x8*)(lds + PG8_SA(b, h) + aoff + m * 2048 + k * 1024); } while (0)
; #define PG8_LDB(dst, b, h) do { _Pragma("unroll") for (int n = 0; n < 2; ++n) _Pragma("unroll") for (int k = 0; k < 2; ++k) dst[n][k] = *(const PG8_LAS bf16x8*)(lds + PG8_SB(b, h) + boff + n * 2048 + k * 1024); } while (0)
; #define PG8_MMA(ai, bj, At, Bt) do { __builtin_amdgcn_s_setprio(1); _Pragma("unroll") for (int m = 0; m < 4; ++m) _Pragma("unroll") for (int n = 0; n < 2; ++n) _Pragma("unroll") for (int k = 0; k < 2; ++k) \
;         acc[ai][bj][m][n] = __builtin_amdgcn_mfma_f32_16x16x32_bf16(Bt[n][k], At[m][k], acc[ai][bj][m][n], 0, 0, 0); __builtin_amdgcn_s_setprio(0); } while (0)
; #define PG8_WAIT_V(n) asm volatile("s_waitcnt vmcnt(" #n ")" ::: "memory")
; #define PG8_WAIT_L(n) asm volatile("s_waitcnt lgkmcnt(" #n ")" ::: "memory")
; #define PG8_BAR __builtin_amdgcn_s_barrier()
; #define PG8_SCHED __builtin_amdgcn_sched_barrier(0)
; template <class Epi, class Sched, bool ALIGN_EPI = false, bool SP2 = false>
; __device__ __forceinline__ void gemm_phase(PG8_LAS unsigned char* lds, const Gemm g, const Sched& S, const Epi& E) {
;     ...
;             PG8_LDB(B0, 0, 0); PG8_LDB(B1, 0, 1); PG8_SCHED; PG8_LDA(At, 0, 0); PG8_STAGE(PG8_SA(1, 1), a1 + hstepA, voffA);
;             PG8_WAIT_V(8); PG8_WAIT_L(0); PG8_BAR; PG8_MMA(0, 0, At, B0); PG8_MMA(0, 1, At, B1); PG8_BAR; PG8_SCHED;
;             PG8_LDA(At, 0, 1); PG8_STAGE(PG8_SB(0, 0), b2, voffB); PG8_STAGE(PG8_SB(0, 1), b2 + hstepB, voffB); PG8_STAGE(PG8_SA(0, 0), a2, voffA);
.LBB0_197:
	ds_read_b128 v[168:171], v163
	ds_read_b128 v[176:179], v163 offset:1024
	ds_read_b128 v[184:187], v163 offset:2048
	ds_read_b128 v[188:191], v163 offset:3072
	ds_read_b128 v[192:195], v165
	ds_read_b128 v[196:199], v165 offset:1024
	ds_read_b128 v[200:203], v165 offset:2048
	ds_read_b128 v[204:207], v165 offset:3072
	s_add_u32 s28, s26, 0xfffc0080
	s_addc_u32 s29, s27, -1
	s_cmp_eq_u32 s60, 12
	s_cselect_b32 s31, s1, s29
	s_cselect_b32 s30, s2, s28
	s_cselect_b32 s29, s5, s33
	s_cselect_b32 s28, s19, s21
	v_lshl_add_u64 v[158:159], s[26:27], 0, v[146:147]
	s_add_i32 m0, s40, 0xc000
	ds_read_b128 v[208:211], v167
	ds_read_b128 v[212:215], v167 offset:1024
	ds_read_b128 v[216:219], v167 offset:2048
	ds_read_b128 v[220:223], v167 offset:3072
	ds_read_b128 v[224:227], v167 offset:4096
	ds_read_b128 v[228:231], v167 offset:5120
	ds_read_b128 v[232:235], v167 offset:6144
	ds_read_b128 v[236:239], v167 offset:7168
	global_load_lds_dwordx4 v[158:159], off
	v_lshl_add_u64 v[158:159], s[26:27], 0, v[148:149]
	s_add_i32 m0, s40, 0xe000
	s_nop 0
	global_load_lds_dwordx4 v[158:159], off
	s_waitcnt vmcnt(8)
	s_waitcnt lgkmcnt(0)
	s_barrier
	s_waitcnt lgkmcnt(0)
	v_mfma_f32_16x16x32_bf16 v[126:129], v[168:171], v[208:211], v[126:129]
	v_mfma_f32_16x16x32_bf16 v[122:125], v[184:187], v[208:211], v[122:125]
	v_mfma_f32_16x16x32_bf16 v[110:113], v[168:171], v[216:219], v[110:113]
	v_mfma_f32_16x16x32_bf16 v[106:109], v[184:187], v[216:219], v[106:109]
	v_mfma_f32_16x16x32_bf16 v[94:97], v[168:171], v[224:227], v[94:97]
	v_mfma_f32_16x16x32_bf16 v[90:93], v[184:187], v[224:227], v[90:93]
	v_mfma_f32_16x16x32_bf16 v[78:81], v[168:171], v[232:235], v[78:81]
	v_mfma_f32_16x16x32_bf16 v[74:77], v[184:187], v[232:235], v[74:77]
	v_mfma_f32_16x16x32_bf16 v[126:129], v[176:179], v[212:215], v[126:129]
	v_mfma_f32_16x16x32_bf16 v[122:125], v[188:191], v[212:215], v[122:125]
	v_mfma_f32_16x16x32_bf16 v[110:113], v[176:179], v[220:223], v[110:113]
	v_mfma_f32_16x16x32_bf16 v[106:109], v[188:191], v[220:223], v[106:109]
	v_mfma_f32_16x16x32_bf16 v[94:97], v[176:179], v[228:231], v[94:97]
	v_mfma_f32_16x16x32_bf16 v[90:93], v[188:191], v[228:231], v[90:93]
	v_mfma_f32_16x16x32_bf16 v[78:81], v[176:179], v[236:239], v[78:81]
	v_mfma_f32_16x16x32_bf16 v[74:77], v[188:191], v[236:239], v[74:77]
	v_mfma_f32_16x16x32_bf16 v[118:121], v[192:195], v[208:211], v[118:121]
	v_mfma_f32_16x16x32_bf16 v[114:117], v[200:203], v[208:211], v[114:117]
	v_mfma_f32_16x16x32_bf16 v[102:105], v[192:195], v[216:219], v[102:105]
	v_mfma_f32_16x16x32_bf16 v[98:101], v[200:203], v[216:219], v[98:101]
	v_mfma_f32_16x16x32_bf16 v[86:89], v[192:195], v[224:227], v[86:89]
	v_mfma_f32_16x16x32_bf16 v[82:85], v[200:203], v[224:227], v[82:85]
	v_mfma_f32_16x16x32_bf16 v[70:73], v[192:195], v[232:235], v[70:73]
	v_mfma_f32_16x16x32_bf16 v[66:69], v[200:203], v[232:235], v[66:69]
	v_mfma_f32_16x16x32_bf16 v[118:121], v[196:199], v[212:215], v[118:121]
	v_mfma_f32_16x16x32_bf16 v[114:117], v[204:207], v[212:215], v[114:117]
	v_mfma_f32_16x16x32_bf16 v[102:105], v[196:199], v[220:223], v[102:105]
	v_mfma_f32_16x16x32_bf16 v[98:101], v[204:207], v[220:223], v[98:101]
	v_mfma_f32_16x16x32_bf16 v[86:89], v[196:199], v[228:231], v[86:89]
	v_mfma_f32_16x16x32_bf16 v[82:85], v[204:207], v[228:231], v[82:85]
	v_mfma_f32_16x16x32_bf16 v[70:73], v[196:199], v[236:239], v[70:73]
	v_mfma_f32_16x16x32_bf16 v[66:69], v[204:207], v[236:239], v[66:69]
	s_barrier
	s_add_i32 s61, s53, s37
	v_lshl_add_u64 v[158:159], s[28:29], 0, v[134:135]
	s_mov_b32 m0, s61
	ds_read_b128 v[208:211], v167 offset:16384
	ds_read_b128 v[212:215], v167 offset:17408
	ds_read_b128 v[216:219], v167 offset:18432
	ds_read_b128 v[220:223], v167 offset:19456
	ds_read_b128 v[224:227], v167 offset:20480
	ds_read_b128 v[228:231], v167 offset:21504
	ds_read_b128 v[232:235], v167 offset:22528
	ds_read_b128 v[236:239], v167 offset:23552
	global_load_lds_dwordx4 v[158:159], off
	s_add_i32 m0, s61, 0x2000
	s_add_u32 s62, s28, 0x40000
	v_lshl_add_u64 v[180:181], s[28:29], 0, v[130:131]
	s_addc_u32 s63, s29, 0
	s_add_i32 s61, s54, s37
	global_load_lds_dwordx4 v[180:181], off
	v_lshl_add_u64 v[240:241], s[62:63], 0, v[134:135]
	s_mov_b32 m0, s61
	v_lshl_add_u64 v[242:243], s[30:31], 0, v[132:133]
	global_load_lds_dwordx4 v[240:241], off
	v_lshl_add_u64 v[240:241], s[62:63], 0, v[130:131]
	s_add_i32 m0, s61, 0x2000
	s_nop 0
	global_load_lds_dwordx4 v[240:241], off
	v_lshl_add_u64 v[240:241], s[30:31], 0, v[136:137]
	s_mov_b32 m0, s40
	s_nop 0
	global_load_lds_dwordx4 v[240:241], off
	s_mov_b32 m0, s41
	s_nop 0
	global_load_lds_dwordx4 v[242:243], off
	s_waitcnt vmcnt(8)
	s_waitcnt lgkmcnt(0)
	s_barrier
; #define PG8_STAGE(bufoff, gbase, voff) do { _Pragma("unroll") for (int _i = 0; _i < 2; ++_i) \
;         __builtin_amdgcn_global_load_lds((const unsigned*)((const char*)(gbase) + (voff)[_i]), (PG8_LAS unsigned*)(lds + (bufoff) + ldsw + _i * 8192), 16, 0, 0); } while (0)
; #define PG8_LDA(dst, b, h) do { _Pragma("unroll") for (int m = 0; m < 4; ++m) _Pragma("unroll") for (int k = 0; k < 2; ++k) dst[m][k] = *(const PG8_LAS bf16x8*)(lds + PG8_SA(b, h) + aoff + m * 2048 + k * 1024); } while (0)
; #define PG8_LDB(dst, b, h) do { _Pragma("unroll") for (int n = 0; n < 2; ++n) _Pragma("unroll") for (int k = 0; k < 2; ++k) dst[n][k] = *(const PG8_LAS bf16x8*)(lds + PG8_SB(b, h) + boff + n * 2048 + k * 1024); } while (0)
; #define PG8_MMA(ai, bj, At, Bt) do { __builtin_amdgcn_s_setprio(1); _Pragma("unroll") for (int m = 0; m < 4; ++m) _Pragma("unroll") for (int n = 0; n < 2; ++n) _Pragma("unroll") for (int k = 0; k < 2; ++k) \
;         acc[ai][bj][m][n] = __builtin_amdgcn_mfma_f32_16x16x32_bf16(Bt[n][k], At[m][k], acc[ai][bj][m][n], 0, 0, 0); __builtin_amdgcn_s_setprio(0); } while (0)
; #define PG8_WAIT_V(n) asm volatile("s_waitcnt vmcnt(" #n ")" ::: "memory")
; #define PG8_WAIT_L(n) asm volatile("s_waitcnt lgkmcnt(" #n ")" ::: "memory")
; #define PG8_BAR __builtin_amdgcn_s_barrier()
; #define PG8_SCHED __builtin_amdgcn_sched_barrier(0)
; template <class Epi, class Sched, bool ALIGN_EPI = false, bool SP2 = false>
; __device__ __forceinline__ void gemm_phase(PG8_LAS unsigned char* lds, const Gemm g, const Sched& S, const Epi& E) {
;     ...
;             PG8_WAIT_V(8); PG8_WAIT_L(0); PG8_BAR; PG8_MMA(1, 0, At, B0); PG8_MMA(1, 1, At, B1); PG8_BAR; PG8_SCHED;
;             PG8_LDB(B0, 1, 0); PG8_LDB(B1, 1, 1); PG8_SCHED; PG8_LDA(At, 1, 0); PG8_STAGE(PG8_SA(0, 1), a2 + hstepA, voffA);
;             PG8_WAIT_V(8); PG8_WAIT_L(0); PG8_BAR; PG8_MMA(0, 0, At, B0); PG8_MMA(0, 1, At, B1); PG8_BAR; PG8_SCHED;
	s_waitcnt lgkmcnt(0)
	v_mfma_f32_16x16x32_bf16 v[62:65], v[168:171], v[208:211], v[62:65]
	v_mfma_f32_16x16x32_bf16 v[58:61], v[184:187], v[208:211], v[58:61]
	v_mfma_f32_16x16x32_bf16 v[46:49], v[168:171], v[216:219], v[46:49]
	v_mfma_f32_16x16x32_bf16 v[42:45], v[184:187], v[216:219], v[42:45]
	v_mfma_f32_16x16x32_bf16 v[30:33], v[168:171], v[224:227], v[30:33]
	v_mfma_f32_16x16x32_bf16 v[26:29], v[184:187], v[224:227], v[26:29]
	v_mfma_f32_16x16x32_bf16 v[14:17], v[168:171], v[232:235], v[14:17]
	v_mfma_f32_16x16x32_bf16 v[10:13], v[184:187], v[232:235], v[10:13]
	v_mfma_f32_16x16x32_bf16 v[62:65], v[176:179], v[212:215], v[62:65]
	v_mfma_f32_16x16x32_bf16 v[58:61], v[188:191], v[212:215], v[58:61]
	v_mfma_f32_16x16x32_bf16 v[46:49], v[176:179], v[220:223], v[46:49]
	v_mfma_f32_16x16x32_bf16 v[42:45], v[188:191], v[220:223], v[42:45]
	v_mfma_f32_16x16x32_bf16 v[30:33], v[176:179], v[228:231], v[30:33]
	v_mfma_f32_16x16x32_bf16 v[26:29], v[188:191], v[228:231], v[26:29]
	v_mfma_f32_16x16x32_bf16 v[14:17], v[176:179], v[236:239], v[14:17]
	v_mfma_f32_16x16x32_bf16 v[10:13], v[188:191], v[236:239], v[10:13]
	v_mfma_f32_16x16x32_bf16 v[54:57], v[192:195], v[208:211], v[54:57]
	v_mfma_f32_16x16x32_bf16 v[50:53], v[200:203], v[208:211], v[50:53]
	v_mfma_f32_16x16x32_bf16 v[38:41], v[192:195], v[216:219], v[38:41]
	v_mfma_f32_16x16x32_bf16 v[34:37], v[200:203], v[216:219], v[34:37]
	v_mfma_f32_16x16x32_bf16 v[22:25], v[192:195], v[224:227], v[22:25]
	v_mfma_f32_16x16x32_bf16 v[18:21], v[200:203], v[224:227], v[18:21]
	v_mfma_f32_16x16x32_bf16 v[6:9], v[192:195], v[232:235], v[6:9]
	v_mfma_f32_16x16x32_bf16 v[2:5], v[200:203], v[232:235], v[2:5]
	v_mfma_f32_16x16x32_bf16 v[54:57], v[196:199], v[212:215], v[54:57]
	v_mfma_f32_16x16x32_bf16 v[50:53], v[204:207], v[212:215], v[50:53]
	v_mfma_f32_16x16x32_bf16 v[38:41], v[196:199], v[220:223], v[38:41]
	v_mfma_f32_16x16x32_bf16 v[34:37], v[204:207], v[220:223], v[34:37]
	v_mfma_f32_16x16x32_bf16 v[22:25], v[196:199], v[228:231], v[22:25]
	v_mfma_f32_16x16x32_bf16 v[18:21], v[204:207], v[228:231], v[18:21]
	v_mfma_f32_16x16x32_bf16 v[6:9], v[196:199], v[236:239], v[6:9]
	v_mfma_f32_16x16x32_bf16 v[2:5], v[204:207], v[236:239], v[2:5]
	s_barrier
	s_add_i32 s61, 0, 0x18000
	v_add_u32_e32 v138, s61, v141
	s_add_i32 s62, 0, 0x1c000
	ds_read_b128 v[168:171], v138
	ds_read_b128 v[176:179], v138 offset:1024
	ds_read_b128 v[184:187], v138 offset:2048
	ds_read_b128 v[188:191], v138 offset:3072
	v_add_u32_e32 v138, s62, v141
	ds_read_b128 v[192:195], v138
	ds_read_b128 v[196:199], v138 offset:1024
	ds_read_b128 v[200:203], v138 offset:2048
	ds_read_b128 v[204:207], v138 offset:3072
	s_add_u32 s30, s30, 0x40000
	s_addc_u32 s31, s31, 0
	s_mov_b32 m0, s42
	v_lshl_add_u64 v[244:245], s[30:31], 0, v[136:137]
	ds_read_b128 v[208:211], v167 offset:32768
	ds_read_b128 v[212:215], v167 offset:33792
	ds_read_b128 v[216:219], v167 offset:34816
	ds_read_b128 v[220:223], v167 offset:35840
	ds_read_b128 v[224:227], v167 offset:36864
	ds_read_b128 v[228:231], v167 offset:37888
	ds_read_b128 v[232:235], v167 offset:38912
	ds_read_b128 v[236:239], v167 offset:39936
	global_load_lds_dwordx4 v[244:245], off
	v_lshl_add_u64 v[244:245], s[30:31], 0, v[132:133]
	s_mov_b32 m0, s43
	s_nop 0
	global_load_lds_dwordx4 v[244:245], off
	s_waitcnt vmcnt(8)
	s_waitcnt lgkmcnt(0)
	s_barrier
	s_waitcnt lgkmcnt(0)
	v_mfma_f32_16x16x32_bf16 v[126:129], v[168:171], v[208:211], v[126:129]
	v_mfma_f32_16x16x32_bf16 v[122:125], v[184:187], v[208:211], v[122:125]
	v_mfma_f32_16x16x32_bf16 v[110:113], v[168:171], v[216:219], v[110:113]
	v_mfma_f32_16x16x32_bf16 v[106:109], v[184:187], v[216:219], v[106:109]
	v_mfma_f32_16x16x32_bf16 v[94:97], v[168:171], v[224:227], v[94:97]
	v_mfma_f32_16x16x32_bf16 v[90:93], v[184:187], v[224:227], v[90:93]
	v_mfma_f32_16x16x32_bf16 v[78:81], v[168:171], v[232:235], v[78:81]
	v_mfma_f32_16x16x32_bf16 v[74:77], v[184:187], v[232:235], v[74:77]
	v_mfma_f32_16x16x32_bf16 v[126:129], v[176:179], v[212:215], v[126:129]
	v_mfma_f32_16x16x32_bf16 v[122:125], v[188:191], v[212:215], v[122:125]
	v_mfma_f32_16x16x32_bf16 v[110:113], v[176:179], v[220:223], v[110:113]
	v_mfma_f32_16x16x32_bf16 v[106:109], v[188:191], v[220:223], v[106:109]
	v_mfma_f32_16x16x32_bf16 v[94:97], v[176:179], v[228:231], v[94:97]
	v_mfma_f32_16x16x32_bf16 v[90:93], v[188:191], v[228:231], v[90:93]
	v_mfma_f32_16x16x32_bf16 v[78:81], v[176:179], v[236:239], v[78:81]
	v_mfma_f32_16x16x32_bf16 v[74:77], v[188:191], v[236:239], v[74:77]
	v_mfma_f32_16x16x32_bf16 v[118:121], v[192:195], v[208:211], v[118:121]
	v_mfma_f32_16x16x32_bf16 v[114:117], v[200:203], v[208:211], v[114:117]
	v_mfma_f32_16x16x32_bf16 v[102:105], v[192:195], v[216:219], v[102:105]
	v_mfma_f32_16x16x32_bf16 v[98:101], v[200:203], v[216:219], v[98:101]
	v_mfma_f32_16x16x32_bf16 v[86:89], v[192:195], v[224:227], v[86:89]
	v_mfma_f32_16x16x32_bf16 v[82:85], v[200:203], v[224:227], v[82:85]
	v_mfma_f32_16x16x32_bf16 v[70:73], v[192:195], v[232:235], v[70:73]
	v_mfma_f32_16x16x32_bf16 v[66:69], v[200:203], v[232:235], v[66:69]
	v_mfma_f32_16x16x32_bf16 v[118:121], v[196:199], v[212:215], v[118:121]
	v_mfma_f32_16x16x32_bf16 v[114:117], v[204:207], v[212:215], v[114:117]
	v_mfma_f32_16x16x32_bf16 v[102:105], v[196:199], v[220:223], v[102:105]
	v_mfma_f32_16x16x32_bf16 v[98:101], v[204:207], v[220:223], v[98:101]
	v_mfma_f32_16x16x32_bf16 v[86:89], v[196:199], v[228:231], v[86:89]
	v_mfma_f32_16x16x32_bf16 v[82:85], v[204:207], v[228:231], v[82:85]
	v_mfma_f32_16x16x32_bf16 v[70:73], v[196:199], v[236:239], v[70:73]
	v_mfma_f32_16x16x32_bf16 v[66:69], v[204:207], v[236:239], v[66:69]
	s_barrier
; #define PG8_STAGE(bufoff, gbase, voff) do { _Pragma("unroll") for (int _i = 0; _i < 2; ++_i) \
;         __builtin_amdgcn_global_load_lds((const unsigned*)((const char*)(gbase) + (voff)[_i]), (PG8_LAS unsigned*)(lds + (bufoff) + ldsw + _i * 8192), 16, 0, 0); } while (0)
; #define PG8_LDA(dst, b, h) do { _Pragma("unroll") for (int m = 0; m < 4; ++m) _Pragma("unroll") for (int k = 0; k < 2; ++k) dst[m][k] = *(const PG8_LAS bf16x8*)(lds + PG8_SA(b, h) + aoff + m * 2048 + k * 1024); } while (0)
; #define PG8_WAIT_V(n) asm volatile("s_waitcnt vmcnt(" #n ")" ::: "memory")
; template <class Epi, class Sched, bool ALIGN_EPI = false, bool SP2 = false>
; __device__ __forceinline__ void gemm_phase(PG8_LAS unsigned char* lds, const Gemm g, const Sched& S, const Epi& E) {
;     ...
;             PG8_LDA(At, 1, 1); PG8_STAGE(PG8_SB(1, 0), b3, voffB); PG8_STAGE(PG8_SB(1, 1), b3 + hstepB, voffB); PG8_STAGE(PG8_SA(1, 0), a3, voffA);
;             PG8_WAIT_V(8); PG8_WAIT_L(0); PG8_BAR; PG8_MMA(1, 0, At, B0); PG8_MMA(1, 1, At, B1); PG8_BAR; PG8_SCHED;
;             } else {
;             PG8_LDB(B0, 0, 0); PG8_SCHED; PG8_LDA(At, 0, 0); PG8_STAGE(PG8_SA(1, 1), a1 + hstepA, voffA);
;             PG8_WAIT_L(8); PG8_BAR; PG8_WAIT_L(0); PG8_MMA(0, 0, At, B0); PG8_BAR; PG8_SCHED;
;             PG8_LDB(B1, 0, 1); PG8_STAGE(PG8_SB(0, 0), b2, voffB);
;             PG8_BAR; PG8_WAIT_L(0); PG8_MMA(0, 1, At, B1); PG8_BAR;
;             PG8_LDA(At, 0, 1); PG8_STAGE(PG8_SA(0, 0), a2, voffA);
;             PG8_BAR; PG8_WAIT_L(0); PG8_MMA(1, 0, At, B0); PG8_BAR; PG8_SCHED;
;             PG8_STAGE(PG8_SB(0, 1), b2 + hstepB, voffB);
;             PG8_WAIT_V(6); PG8_BAR; PG8_MMA(1, 1, At, B1); PG8_BAR;
;             PG8_LDB(B0, 1, 0); PG8_SCHED; PG8_LDA(At, 1, 0); PG8_STAGE(PG8_SA(0, 1), a2 + hstepA, voffA);
;             PG8_WAIT_L(8); PG8_BAR; PG8_WAIT_L(0); PG8_MMA(0, 0, At, B0); PG8_BAR; PG8_SCHED;
;             PG8_LDB(B1, 1, 1); PG8_STAGE(PG8_SB(1, 0), b3, voffB);
;             PG8_BAR; PG8_WAIT_L(0); PG8_MMA(0, 1, At, B1); PG8_BAR;
;             PG8_LDA(At, 1, 1); PG8_STAGE(PG8_SA(1, 0), a3, voffA);
;             PG8_BAR; PG8_WAIT_L(0); PG8_MMA(1, 0, At, B0); PG8_BAR; PG8_SCHED;
;             PG8_STAGE(PG8_SB(1, 1), b3 + hstepB, voffB);
;             PG8_WAIT_V(6); PG8_BAR; PG8_MMA(1, 1, At, B1); PG8_BAR;
;             }
;         }
;         if constexpr (ALIGN_EPI) { if (wr == 0) PG8_BAR; }
	s_add_i32 s30, s61, s37
	v_lshl_add_u64 v[158:159], v[158:159], 0, s[14:15]
	s_mov_b32 m0, s30
	ds_read_b128 v[208:211], v167 offset:49152
	ds_read_b128 v[212:215], v167 offset:50176
	ds_read_b128 v[216:219], v167 offset:51200
	ds_read_b128 v[220:223], v167 offset:52224
	ds_read_b128 v[224:227], v167 offset:53248
	ds_read_b128 v[228:231], v167 offset:54272
	ds_read_b128 v[232:235], v167 offset:55296
	ds_read_b128 v[236:239], v167 offset:56320
	global_load_lds_dwordx4 v[158:159], off
	s_add_i32 m0, s30, 0x2000
	s_add_u32 s28, s28, 0x40080
	v_lshl_add_u64 v[158:159], v[180:181], 0, s[14:15]
	s_addc_u32 s29, s29, 0
	s_add_i32 s30, s62, s37
	global_load_lds_dwordx4 v[158:159], off
	v_lshl_add_u64 v[158:159], s[28:29], 0, v[134:135]
	s_mov_b32 m0, s30
	s_nop 0
	global_load_lds_dwordx4 v[158:159], off
	v_lshl_add_u64 v[158:159], s[28:29], 0, v[130:131]
	s_add_i32 m0, s30, 0x2000
	s_nop 0
	global_load_lds_dwordx4 v[158:159], off
	v_lshl_add_u64 v[158:159], v[240:241], 0, s[14:15]
	s_mov_b32 m0, s49
	s_nop 0
	global_load_lds_dwordx4 v[158:159], off
	v_lshl_add_u64 v[158:159], v[242:243], 0, s[14:15]
	s_mov_b32 m0, s50
	s_nop 0
	global_load_lds_dwordx4 v[158:159], off
	s_waitcnt vmcnt(8)
	s_waitcnt lgkmcnt(0)
	s_barrier
	s_waitcnt lgkmcnt(0)
	v_mfma_f32_16x16x32_bf16 v[62:65], v[168:171], v[208:211], v[62:65]
	v_mfma_f32_16x16x32_bf16 v[58:61], v[184:187], v[208:211], v[58:61]
	v_mfma_f32_16x16x32_bf16 v[46:49], v[168:171], v[216:219], v[46:49]
	v_mfma_f32_16x16x32_bf16 v[42:45], v[184:187], v[216:219], v[42:45]
	v_mfma_f32_16x16x32_bf16 v[30:33], v[168:171], v[224:227], v[30:33]
	v_mfma_f32_16x16x32_bf16 v[26:29], v[184:187], v[224:227], v[26:29]
	v_mfma_f32_16x16x32_bf16 v[14:17], v[168:171], v[232:235], v[14:17]
	v_mfma_f32_16x16x32_bf16 v[10:13], v[184:187], v[232:235], v[10:13]
	v_mfma_f32_16x16x32_bf16 v[62:65], v[176:179], v[212:215], v[62:65]
	v_mfma_f32_16x16x32_bf16 v[58:61], v[188:191], v[212:215], v[58:61]
	v_mfma_f32_16x16x32_bf16 v[46:49], v[176:179], v[220:223], v[46:49]
	v_mfma_f32_16x16x32_bf16 v[42:45], v[188:191], v[220:223], v[42:45]
	v_mfma_f32_16x16x32_bf16 v[30:33], v[176:179], v[228:231], v[30:33]
	v_mfma_f32_16x16x32_bf16 v[26:29], v[188:191], v[228:231], v[26:29]
	v_mfma_f32_16x16x32_bf16 v[14:17], v[176:179], v[236:239], v[14:17]
	v_mfma_f32_16x16x32_bf16 v[10:13], v[188:191], v[236:239], v[10:13]
	v_mfma_f32_16x16x32_bf16 v[54:57], v[192:195], v[208:211], v[54:57]
	v_mfma_f32_16x16x32_bf16 v[50:53], v[200:203], v[208:211], v[50:53]
	v_mfma_f32_16x16x32_bf16 v[38:41], v[192:195], v[216:219], v[38:41]
	v_mfma_f32_16x16x32_bf16 v[34:37], v[200:203], v[216:219], v[34:37]
	v_mfma_f32_16x16x32_bf16 v[22:25], v[192:195], v[224:227], v[22:25]
	v_mfma_f32_16x16x32_bf16 v[18:21], v[200:203], v[224:227], v[18:21]
	v_mfma_f32_16x16x32_bf16 v[6:9], v[192:195], v[232:235], v[6:9]
	v_mfma_f32_16x16x32_bf16 v[2:5], v[200:203], v[232:235], v[2:5]
	v_mfma_f32_16x16x32_bf16 v[54:57], v[196:199], v[212:215], v[54:57]
	v_mfma_f32_16x16x32_bf16 v[50:53], v[204:207], v[212:215], v[50:53]
	v_mfma_f32_16x16x32_bf16 v[38:41], v[196:199], v[220:223], v[38:41]
	v_mfma_f32_16x16x32_bf16 v[34:37], v[204:207], v[220:223], v[34:37]
	v_mfma_f32_16x16x32_bf16 v[22:25], v[196:199], v[228:231], v[22:25]
	v_mfma_f32_16x16x32_bf16 v[18:21], v[204:207], v[228:231], v[18:21]
	v_mfma_f32_16x16x32_bf16 v[6:9], v[196:199], v[236:239], v[6:9]
	v_mfma_f32_16x16x32_bf16 v[2:5], v[204:207], v[236:239], v[2:5]
	s_barrier
	s_add_i32 s60, s60, 2
	s_add_u32 s26, s26, 0x100
	s_addc_u32 s27, s27, 0
	s_add_u32 s21, s21, 0x100
	s_addc_u32 s33, s33, 0
	s_cmp_gt_u32 s60, 13
	s_cbranch_scc0 .LBB0_197
	s_and_b64 vcc, exec, s[16:17]
	s_cbranch_vccz .LBB0_200
	s_barrier

; #define PG8_STAGE(bufoff, gbase, voff) do { _Pragma("unroll") for (int _i = 0; _i < 2; ++_i) \
;         __builtin_amdgcn_global_load_lds((const unsigned*)((const char*)(gbase) + (voff)[_i]), (PG8_LAS unsigned*)(lds + (bufoff) + ldsw + _i * 8192), 16, 0, 0); } while (0)
; #define PG8_LDA(dst, b, h) do { _Pragma("unroll") for (int m = 0; m < 4; ++m) _Pragma("unroll") for (int k = 0; k < 2; ++k) dst[m][k] = *(const PG8_LAS bf16x8*)(lds + PG8_SA(b, h) + aoff + m * 2048 + k * 1024); } while (0)
; #define PG8_LDB(dst, b, h) do { _Pragma("unroll") for (int n = 0; n < 2; ++n) _Pragma("unroll") for (int k = 0; k < 2; ++k) dst[n][k] = *(const PG8_LAS bf16x8*)(lds + PG8_SB(b, h) + boff + n * 2048 + k * 1024); } while (0)
; #define PG8_MMA(ai, bj, At, Bt) do { __builtin_amdgcn_s_setprio(1); _Pragma("unroll") for (int m = 0; m < 4; ++m) _Pragma("unroll") for (int n = 0; n < 2; ++n) _Pragma("unroll") for (int k = 0; k < 2; ++k) \
;         acc[ai][bj][m][n] = __builtin_amdgcn_mfma_f32_16x16x32_bf16(Bt[n][k], At[m][k], acc[ai][bj][m][n], 0, 0, 0); __builtin_amdgcn_s_setprio(0); } while (0)
; #define PG8_WAIT_V(n) asm volatile("s_waitcnt vmcnt(" #n ")" ::: "memory")
; #define PG8_WAIT_L(n) asm volatile("s_waitcnt lgkmcnt(" #n ")" ::: "memory")
; #define PG8_BAR __builtin_amdgcn_s_barrier()
; #define PG8_SCHED __builtin_amdgcn_sched_barrier(0)
; template <class Epi, class Sched, bool ALIGN_EPI = false, bool SP2 = false>
; __device__ __forceinline__ void gemm_phase(PG8_LAS unsigned char* lds, const Gemm g, const Sched& S, const Epi& E) {
;     ...
;             PG8_LDB(B0, 0, 0); PG8_LDB(B1, 0, 1); PG8_SCHED; PG8_LDA(At, 0, 0); PG8_STAGE(PG8_SA(1, 1), a1 + hstepA, voffA);
;             PG8_WAIT_V(8); PG8_WAIT_L(0); PG8_BAR; PG8_MMA(0, 0, At, B0); PG8_MMA(0, 1, At, B1); PG8_BAR; PG8_SCHED;
;             PG8_LDA(At, 0, 1); PG8_STAGE(PG8_SB(0, 0), b2, voffB); PG8_STAGE(PG8_SB(0, 1), b2 + hstepB, voffB); PG8_STAGE(PG8_SA(0, 0), a2, voffA);
;             PG8_WAIT_V(8); PG8_WAIT_L(0); PG8_BAR; PG8_MMA(1, 0, At, B0); PG8_MMA(1, 1, At, B1); PG8_BAR; PG8_SCHED;
.LBB0_280:
	ds_read_b128 v[84:87], v81
	ds_read_b128 v[88:91], v81 offset:1024
	ds_read_b128 v[92:95], v81 offset:2048
	ds_read_b128 v[96:99], v81 offset:3072
	s_add_u32 s38, s36, 0x100
	s_addc_u32 s39, s37, 0
	s_cmp_eq_u32 s68, 4
	s_cselect_b32 s43, s31, s39
	s_cselect_b32 s42, s30, s38
	s_cselect_b32 s41, s9, s67
	s_cselect_b32 s40, s29, s66
	v_lshl_add_u64 v[132:133], s[36:37], 0, v[76:77]
	s_add_i32 m0, s45, 0xc000
	ds_read_b128 v[100:103], v82
	ds_read_b128 v[104:107], v82 offset:1024
	ds_read_b128 v[108:111], v82 offset:2048
	ds_read_b128 v[112:115], v82 offset:3072
	ds_read_b128 v[116:119], v82 offset:4096
	ds_read_b128 v[120:123], v82 offset:5120
	ds_read_b128 v[124:127], v82 offset:6144
	ds_read_b128 v[128:131], v82 offset:7168
	global_load_lds_dwordx4 v[132:133], off
	v_lshl_add_u64 v[132:133], s[36:37], 0, v[78:79]
	s_add_i32 m0, s45, 0xe000
	s_nop 0
	global_load_lds_dwordx4 v[132:133], off
	s_waitcnt vmcnt(8)
	s_waitcnt lgkmcnt(0)
	s_barrier
	s_waitcnt lgkmcnt(0)
	v_mfma_f32_16x16x32_bf16 v[62:65], v[84:87], v[100:103], v[62:65]
	v_mfma_f32_16x16x32_bf16 v[58:61], v[92:95], v[100:103], v[58:61]
	v_mfma_f32_16x16x32_bf16 v[54:57], v[84:87], v[108:111], v[54:57]
	v_mfma_f32_16x16x32_bf16 v[50:53], v[92:95], v[108:111], v[50:53]
	v_mfma_f32_16x16x32_bf16 v[46:49], v[84:87], v[116:119], v[46:49]
	v_mfma_f32_16x16x32_bf16 v[42:45], v[92:95], v[116:119], v[42:45]
	v_mfma_f32_16x16x32_bf16 v[38:41], v[84:87], v[124:127], v[38:41]
	v_mfma_f32_16x16x32_bf16 v[34:37], v[92:95], v[124:127], v[34:37]
	v_mfma_f32_16x16x32_bf16 v[62:65], v[88:91], v[104:107], v[62:65]
	v_mfma_f32_16x16x32_bf16 v[58:61], v[96:99], v[104:107], v[58:61]
	v_mfma_f32_16x16x32_bf16 v[54:57], v[88:91], v[112:115], v[54:57]
	v_mfma_f32_16x16x32_bf16 v[50:53], v[96:99], v[112:115], v[50:53]
	v_mfma_f32_16x16x32_bf16 v[46:49], v[88:91], v[120:123], v[46:49]
	v_mfma_f32_16x16x32_bf16 v[42:45], v[96:99], v[120:123], v[42:45]
	v_mfma_f32_16x16x32_bf16 v[38:41], v[88:91], v[128:131], v[38:41]
	v_mfma_f32_16x16x32_bf16 v[34:37], v[96:99], v[128:131], v[34:37]
	s_barrier
	s_add_i32 s36, s64, s1
	v_lshl_add_u64 v[132:133], s[40:41], 0, v[70:71]
	s_mov_b32 m0, s36
	ds_read_b128 v[100:103], v82 offset:16384
	ds_read_b128 v[104:107], v82 offset:17408
	ds_read_b128 v[108:111], v82 offset:18432
	ds_read_b128 v[112:115], v82 offset:19456
	ds_read_b128 v[116:119], v82 offset:20480
	ds_read_b128 v[120:123], v82 offset:21504
	ds_read_b128 v[124:127], v82 offset:22528
	ds_read_b128 v[128:131], v82 offset:23552
	global_load_lds_dwordx4 v[132:133], off
	s_add_i32 m0, s36, 0x2000
	s_add_u32 s36, s40, 0x20000
	v_lshl_add_u64 v[134:135], s[40:41], 0, v[66:67]
	s_addc_u32 s37, s41, 0
	global_load_lds_dwordx4 v[134:135], off
	v_lshl_add_u64 v[136:137], s[36:37], 0, v[70:71]
	s_mov_b32 m0, s46
	v_lshl_add_u64 v[138:139], s[42:43], 0, v[68:69]
	global_load_lds_dwordx4 v[136:137], off
	v_lshl_add_u64 v[136:137], s[36:37], 0, v[66:67]
	s_mov_b32 m0, s47
	s_nop 0
	global_load_lds_dwordx4 v[136:137], off
	v_lshl_add_u64 v[136:137], s[42:43], 0, v[72:73]
	s_mov_b32 m0, s45
	s_nop 0
	global_load_lds_dwordx4 v[136:137], off
	s_mov_b32 m0, s48
	s_nop 0
	global_load_lds_dwordx4 v[138:139], off
	s_waitcnt vmcnt(8)
	s_waitcnt lgkmcnt(0)
	s_barrier
	s_waitcnt lgkmcnt(0)
	v_mfma_f32_16x16x32_bf16 v[30:33], v[84:87], v[100:103], v[30:33]
	v_mfma_f32_16x16x32_bf16 v[26:29], v[92:95], v[100:103], v[26:29]
	v_mfma_f32_16x16x32_bf16 v[22:25], v[84:87], v[108:111], v[22:25]
	v_mfma_f32_16x16x32_bf16 v[18:21], v[92:95], v[108:111], v[18:21]
	v_mfma_f32_16x16x32_bf16 v[14:17], v[84:87], v[116:119], v[14:17]
	v_mfma_f32_16x16x32_bf16 v[10:13], v[92:95], v[116:119], v[10:13]
	v_mfma_f32_16x16x32_bf16 v[6:9], v[84:87], v[124:127], v[6:9]
	v_mfma_f32_16x16x32_bf16 v[2:5], v[92:95], v[124:127], v[2:5]
	v_mfma_f32_16x16x32_bf16 v[30:33], v[88:91], v[104:107], v[30:33]
	v_mfma_f32_16x16x32_bf16 v[26:29], v[96:99], v[104:107], v[26:29]
	v_mfma_f32_16x16x32_bf16 v[22:25], v[88:91], v[112:115], v[22:25]
	v_mfma_f32_16x16x32_bf16 v[18:21], v[96:99], v[112:115], v[18:21]
	v_mfma_f32_16x16x32_bf16 v[14:17], v[88:91], v[120:123], v[14:17]
	v_mfma_f32_16x16x32_bf16 v[10:13], v[96:99], v[120:123], v[10:13]
	v_mfma_f32_16x16x32_bf16 v[6:9], v[88:91], v[128:131], v[6:9]
	v_mfma_f32_16x16x32_bf16 v[2:5], v[96:99], v[128:131], v[2:5]
	s_barrier
; #define PG8_STAGE(bufoff, gbase, voff) do { _Pragma("unroll") for (int _i = 0; _i < 2; ++_i) \
;         __builtin_amdgcn_global_load_lds((const unsigned*)((const char*)(gbase) + (voff)[_i]), (PG8_LAS unsigned*)(lds + (bufoff) + ldsw + _i * 8192), 16, 0, 0); } while (0)
; #define PG8_LDA(dst, b, h) do { _Pragma("unroll") for (int m = 0; m < 4; ++m) _Pragma("unroll") for (int k = 0; k < 2; ++k) dst[m][k] = *(const PG8_LAS bf16x8*)(lds + PG8_SA(b, h) + aoff + m * 2048 + k * 1024); } while (0)
; #define PG8_LDB(dst, b, h) do { _Pragma("unroll") for (int n = 0; n < 2; ++n) _Pragma("unroll") for (int k = 0; k < 2; ++k) dst[n][k] = *(const PG8_LAS bf16x8*)(lds + PG8_SB(b, h) + boff + n * 2048 + k * 1024); } while (0)
; #define PG8_MMA(ai, bj, At, Bt) do { __builtin_amdgcn_s_setprio(1); _Pragma("unroll") for (int m = 0; m < 4; ++m) _Pragma("unroll") for (int n = 0; n < 2; ++n) _Pragma("unroll") for (int k = 0; k < 2; ++k) \
;         acc[ai][bj][m][n] = __builtin_amdgcn_mfma_f32_16x16x32_bf16(Bt[n][k], At[m][k], acc[ai][bj][m][n], 0, 0, 0); __builtin_amdgcn_s_setprio(0); } while (0)
; #define PG8_WAIT_V(n) asm volatile("s_waitcnt vmcnt(" #n ")" ::: "memory")
; #define PG8_WAIT_L(n) asm volatile("s_waitcnt lgkmcnt(" #n ")" ::: "memory")
; #define PG8_BAR __builtin_amdgcn_s_barrier()
; #define PG8_SCHED __builtin_amdgcn_sched_barrier(0)
; template <class Epi, class Sched, bool ALIGN_EPI = false, bool SP2 = false>
; __device__ __forceinline__ void gemm_phase(PG8_LAS unsigned char* lds, const Gemm g, const Sched& S, const Epi& E) {
;     ...
;             PG8_LDB(B0, 1, 0); PG8_LDB(B1, 1, 1); PG8_SCHED; PG8_LDA(At, 1, 0); PG8_STAGE(PG8_SA(0, 1), a2 + hstepA, voffA);
;             PG8_WAIT_V(8); PG8_WAIT_L(0); PG8_BAR; PG8_MMA(0, 0, At, B0); PG8_MMA(0, 1, At, B1); PG8_BAR; PG8_SCHED;
;             PG8_LDA(At, 1, 1); PG8_STAGE(PG8_SB(1, 0), b3, voffB); PG8_STAGE(PG8_SB(1, 1), b3 + hstepB, voffB); PG8_STAGE(PG8_SA(1, 0), a3, voffA);
;             PG8_WAIT_V(8); PG8_WAIT_L(0); PG8_BAR; PG8_MMA(1, 0, At, B0); PG8_MMA(1, 1, At, B1); PG8_BAR; PG8_SCHED;
	s_add_i32 s69, 0, 0x18000
	v_add_u32_e32 v83, s69, v80
	ds_read_b128 v[84:87], v83
	ds_read_b128 v[88:91], v83 offset:1024
	ds_read_b128 v[92:95], v83 offset:2048
	ds_read_b128 v[96:99], v83 offset:3072
	s_add_u32 s36, s42, 0x28000
	s_addc_u32 s37, s43, 0
	s_mov_b32 m0, s49
	v_lshl_add_u64 v[140:141], s[36:37], 0, v[72:73]
	ds_read_b128 v[100:103], v82 offset:32768
	ds_read_b128 v[104:107], v82 offset:33792
	ds_read_b128 v[108:111], v82 offset:34816
	ds_read_b128 v[112:115], v82 offset:35840
	ds_read_b128 v[116:119], v82 offset:36864
	ds_read_b128 v[120:123], v82 offset:37888
	ds_read_b128 v[124:127], v82 offset:38912
	ds_read_b128 v[128:131], v82 offset:39936
	global_load_lds_dwordx4 v[140:141], off
	v_lshl_add_u64 v[140:141], s[36:37], 0, v[68:69]
	s_mov_b32 m0, s50
	s_nop 0
	global_load_lds_dwordx4 v[140:141], off
	s_waitcnt vmcnt(8)
	s_waitcnt lgkmcnt(0)
	s_barrier
	s_waitcnt lgkmcnt(0)
	v_mfma_f32_16x16x32_bf16 v[62:65], v[84:87], v[100:103], v[62:65]
	v_mfma_f32_16x16x32_bf16 v[58:61], v[92:95], v[100:103], v[58:61]
	v_mfma_f32_16x16x32_bf16 v[54:57], v[84:87], v[108:111], v[54:57]
	v_mfma_f32_16x16x32_bf16 v[50:53], v[92:95], v[108:111], v[50:53]
	v_mfma_f32_16x16x32_bf16 v[46:49], v[84:87], v[116:119], v[46:49]
	v_mfma_f32_16x16x32_bf16 v[42:45], v[92:95], v[116:119], v[42:45]
	v_mfma_f32_16x16x32_bf16 v[38:41], v[84:87], v[124:127], v[38:41]
	v_mfma_f32_16x16x32_bf16 v[34:37], v[92:95], v[124:127], v[34:37]
	v_mfma_f32_16x16x32_bf16 v[62:65], v[88:91], v[104:107], v[62:65]
	v_mfma_f32_16x16x32_bf16 v[58:61], v[96:99], v[104:107], v[58:61]
	v_mfma_f32_16x16x32_bf16 v[54:57], v[88:91], v[112:115], v[54:57]
	v_mfma_f32_16x16x32_bf16 v[50:53], v[96:99], v[112:115], v[50:53]
	v_mfma_f32_16x16x32_bf16 v[46:49], v[88:91], v[120:123], v[46:49]
	v_mfma_f32_16x16x32_bf16 v[42:45], v[96:99], v[120:123], v[42:45]
	v_mfma_f32_16x16x32_bf16 v[38:41], v[88:91], v[128:131], v[38:41]
	v_mfma_f32_16x16x32_bf16 v[34:37], v[96:99], v[128:131], v[34:37]
	s_barrier
	s_add_i32 s36, s69, s1
	v_lshl_add_u64 v[132:133], v[132:133], 0, s[10:11]
	s_mov_b32 m0, s36
	ds_read_b128 v[100:103], v82 offset:49152
	ds_read_b128 v[104:107], v82 offset:50176
	ds_read_b128 v[108:111], v82 offset:51200
	ds_read_b128 v[112:115], v82 offset:52224
	ds_read_b128 v[116:119], v82 offset:53248
	ds_read_b128 v[120:123], v82 offset:54272
	ds_read_b128 v[124:127], v82 offset:55296
	ds_read_b128 v[128:131], v82 offset:56320
	global_load_lds_dwordx4 v[132:133], off
	s_add_i32 m0, s36, 0x2000
	s_add_u32 s36, s40, 0x20080
	v_lshl_add_u64 v[132:133], v[134:135], 0, s[10:11]
	s_addc_u32 s37, s41, 0
	global_load_lds_dwordx4 v[132:133], off
	v_lshl_add_u64 v[132:133], s[36:37], 0, v[70:71]
	s_mov_b32 m0, s62
	s_nop 0
	global_load_lds_dwordx4 v[132:133], off
	v_lshl_add_u64 v[132:133], s[36:37], 0, v[66:67]
	s_mov_b32 m0, s63
	s_nop 0
	global_load_lds_dwordx4 v[132:133], off
	v_lshl_add_u64 v[132:133], v[136:137], 0, s[10:11]
	s_mov_b32 m0, s60
	s_nop 0
	global_load_lds_dwordx4 v[132:133], off
	v_lshl_add_u64 v[132:133], v[138:139], 0, s[10:11]
	s_mov_b32 m0, s61
	s_nop 0
	global_load_lds_dwordx4 v[132:133], off
	s_waitcnt vmcnt(8)
	s_waitcnt lgkmcnt(0)
	s_barrier
	s_waitcnt lgkmcnt(0)
	v_mfma_f32_16x16x32_bf16 v[30:33], v[84:87], v[100:103], v[30:33]
	v_mfma_f32_16x16x32_bf16 v[26:29], v[92:95], v[100:103], v[26:29]
	v_mfma_f32_16x16x32_bf16 v[22:25], v[84:87], v[108:111], v[22:25]
	v_mfma_f32_16x16x32_bf16 v[18:21], v[92:95], v[108:111], v[18:21]
	v_mfma_f32_16x16x32_bf16 v[14:17], v[84:87], v[116:119], v[14:17]
	v_mfma_f32_16x16x32_bf16 v[10:13], v[92:95], v[116:119], v[10:13]
	v_mfma_f32_16x16x32_bf16 v[6:9], v[84:87], v[124:127], v[6:9]
	v_mfma_f32_16x16x32_bf16 v[2:5], v[92:95], v[124:127], v[2:5]
	v_mfma_f32_16x16x32_bf16 v[30:33], v[88:91], v[104:107], v[30:33]
	v_mfma_f32_16x16x32_bf16 v[26:29], v[96:99], v[104:107], v[26:29]
	v_mfma_f32_16x16x32_bf16 v[22:25], v[88:91], v[112:115], v[22:25]
	v_mfma_f32_16x16x32_bf16 v[18:21], v[96:99], v[112:115], v[18:21]
	v_mfma_f32_16x16x32_bf16 v[14:17], v[88:91], v[120:123], v[14:17]
	v_mfma_f32_16x16x32_bf16 v[10:13], v[96:99], v[120:123], v[10:13]
	v_mfma_f32_16x16x32_bf16 v[6:9], v[88:91], v[128:131], v[6:9]
	v_mfma_f32_16x16x32_bf16 v[2:5], v[96:99], v[128:131], v[2:5]
	s_barrier
	s_add_i32 s68, s68, 2
	s_add_u32 s66, s66, 0x100
	s_addc_u32 s67, s67, 0
	s_cmp_gt_u32 s68, 5
	s_mov_b64 s[36:37], s[38:39]
	s_cbranch_scc0 .LBB0_280
	s_and_b64 vcc, exec, s[12:13]
	s_cbranch_vccz .LBB0_283
	s_barrier

; #define PG8_STAGE(bufoff, gbase, voff) do { _Pragma("unroll") for (int _i = 0; _i < 2; ++_i) \
;         __builtin_amdgcn_global_load_lds((const unsigned*)((const char*)(gbase) + (voff)[_i]), (PG8_LAS unsigned*)(lds + (bufoff) + ldsw + _i * 8192), 16, 0, 0); } while (0)
; #define PG8_LDA(dst, b, h) do { _Pragma("unroll") for (int m = 0; m < 4; ++m) _Pragma("unroll") for (int k = 0; k < 2; ++k) dst[m][k] = *(const PG8_LAS bf16x8*)(lds + PG8_SA(b, h) + aoff + m * 2048 + k * 1024); } while (0)
; #define PG8_LDB(dst, b, h) do { _Pragma("unroll") for (int n = 0; n < 2; ++n) _Pragma("unroll") for (int k = 0; k < 2; ++k) dst[n][k] = *(const PG8_LAS bf16x8*)(lds + PG8_SB(b, h) + boff + n * 2048 + k * 1024); } while (0)
; #define PG8_MMA(ai, bj, At, Bt) do { __builtin_amdgcn_s_setprio(1); _Pragma("unroll") for (int m = 0; m < 4; ++m) _Pragma("unroll") for (int n = 0; n < 2; ++n) _Pragma("unroll") for (int k = 0; k < 2; ++k) \
;         acc[ai][bj][m][n] = __builtin_amdgcn_mfma_f32_16x16x32_bf16(Bt[n][k], At[m][k], acc[ai][bj][m][n], 0, 0, 0); __builtin_amdgcn_s_setprio(0); } while (0)
; #define PG8_WAIT_V(n) asm volatile("s_waitcnt vmcnt(" #n ")" ::: "memory")
; #define PG8_WAIT_L(n) asm volatile("s_waitcnt lgkmcnt(" #n ")" ::: "memory")
; #define PG8_BAR __builtin_amdgcn_s_barrier()
; #define PG8_SCHED __builtin_amdgcn_sched_barrier(0)
; template <class Epi, class Sched, bool ALIGN_EPI = false, bool SP2 = false>
; __device__ __forceinline__ void gemm_phase(PG8_LAS unsigned char* lds, const Gemm g, const Sched& S, const Epi& E) {
;     ...
;             PG8_LDB(B0, 0, 0); PG8_LDB(B1, 0, 1); PG8_SCHED; PG8_LDA(At, 0, 0); PG8_STAGE(PG8_SA(1, 1), a1 + hstepA, voffA);
;             PG8_WAIT_V(8); PG8_WAIT_L(0); PG8_BAR; PG8_MMA(0, 0, At, B0); PG8_MMA(0, 1, At, B1); PG8_BAR; PG8_SCHED;
;             PG8_LDA(At, 0, 1); PG8_STAGE(PG8_SB(0, 0), b2, voffB); PG8_STAGE(PG8_SB(0, 1), b2 + hstepB, voffB); PG8_STAGE(PG8_SA(0, 0), a2, voffA);
.LBB0_430:
	ds_read_b128 v[62:65], v168
	ds_read_b128 v[66:69], v168 offset:1024
	ds_read_b128 v[138:141], v168 offset:2048
	ds_read_b128 v[142:145], v168 offset:3072
	ds_read_b128 v[162:165], v169
	ds_read_b128 v[172:175], v169 offset:1024
	ds_read_b128 v[176:179], v169 offset:2048
	ds_read_b128 v[180:183], v169 offset:3072
	s_add_u32 s42, s40, 0x100
	s_addc_u32 s43, s41, 0
	s_cmp_eq_u32 s33, 6
	s_cselect_b32 s47, s37, s43
	s_cselect_b32 s46, s36, s42
	s_cselect_b32 s45, s39, s5
	s_cselect_b32 s44, s38, s2
	v_lshl_add_u64 v[216:217], s[40:41], 0, v[158:159]
	s_add_i32 m0, s51, 0xc000
	ds_read_b128 v[184:187], v170
	ds_read_b128 v[188:191], v170 offset:1024
	ds_read_b128 v[192:195], v170 offset:2048
	ds_read_b128 v[196:199], v170 offset:3072
	ds_read_b128 v[200:203], v170 offset:4096
	ds_read_b128 v[204:207], v170 offset:5120
	ds_read_b128 v[208:211], v170 offset:6144
	ds_read_b128 v[212:215], v170 offset:7168
	global_load_lds_dwordx4 v[216:217], off
	v_lshl_add_u64 v[216:217], s[40:41], 0, v[160:161]
	s_add_i32 m0, s51, 0xe000
	s_nop 0
	global_load_lds_dwordx4 v[216:217], off
	s_waitcnt vmcnt(8)
	s_waitcnt lgkmcnt(0)
	s_barrier
	s_waitcnt lgkmcnt(0)
	v_mfma_f32_16x16x32_bf16 v[134:137], v[62:65], v[184:187], v[134:137]
	v_mfma_f32_16x16x32_bf16 v[130:133], v[138:141], v[184:187], v[130:133]
	v_mfma_f32_16x16x32_bf16 v[118:121], v[62:65], v[192:195], v[118:121]
	v_mfma_f32_16x16x32_bf16 v[114:117], v[138:141], v[192:195], v[114:117]
	v_mfma_f32_16x16x32_bf16 v[102:105], v[62:65], v[200:203], v[102:105]
	v_mfma_f32_16x16x32_bf16 v[98:101], v[138:141], v[200:203], v[98:101]
	v_mfma_f32_16x16x32_bf16 v[86:89], v[62:65], v[208:211], v[86:89]
	v_mfma_f32_16x16x32_bf16 v[82:85], v[138:141], v[208:211], v[82:85]
	v_mfma_f32_16x16x32_bf16 v[134:137], v[66:69], v[188:191], v[134:137]
	v_mfma_f32_16x16x32_bf16 v[130:133], v[142:145], v[188:191], v[130:133]
	v_mfma_f32_16x16x32_bf16 v[118:121], v[66:69], v[196:199], v[118:121]
	v_mfma_f32_16x16x32_bf16 v[114:117], v[142:145], v[196:199], v[114:117]
	v_mfma_f32_16x16x32_bf16 v[102:105], v[66:69], v[204:207], v[102:105]
	v_mfma_f32_16x16x32_bf16 v[98:101], v[142:145], v[204:207], v[98:101]
	v_mfma_f32_16x16x32_bf16 v[86:89], v[66:69], v[212:215], v[86:89]
	v_mfma_f32_16x16x32_bf16 v[82:85], v[142:145], v[212:215], v[82:85]
	v_mfma_f32_16x16x32_bf16 v[126:129], v[162:165], v[184:187], v[126:129]
	v_mfma_f32_16x16x32_bf16 v[122:125], v[176:179], v[184:187], v[122:125]
	v_mfma_f32_16x16x32_bf16 v[110:113], v[162:165], v[192:195], v[110:113]
	v_mfma_f32_16x16x32_bf16 v[106:109], v[176:179], v[192:195], v[106:109]
	v_mfma_f32_16x16x32_bf16 v[94:97], v[162:165], v[200:203], v[94:97]
	v_mfma_f32_16x16x32_bf16 v[90:93], v[176:179], v[200:203], v[90:93]
	v_mfma_f32_16x16x32_bf16 v[78:81], v[162:165], v[208:211], v[78:81]
	v_mfma_f32_16x16x32_bf16 v[74:77], v[176:179], v[208:211], v[74:77]
	v_mfma_f32_16x16x32_bf16 v[126:129], v[172:175], v[188:191], v[126:129]
	v_mfma_f32_16x16x32_bf16 v[122:125], v[180:183], v[188:191], v[122:125]
	v_mfma_f32_16x16x32_bf16 v[110:113], v[172:175], v[196:199], v[110:113]
	v_mfma_f32_16x16x32_bf16 v[106:109], v[180:183], v[196:199], v[106:109]
	v_mfma_f32_16x16x32_bf16 v[94:97], v[172:175], v[204:207], v[94:97]
	v_mfma_f32_16x16x32_bf16 v[90:93], v[180:183], v[204:207], v[90:93]
	v_mfma_f32_16x16x32_bf16 v[78:81], v[172:175], v[212:215], v[78:81]
	v_mfma_f32_16x16x32_bf16 v[74:77], v[180:183], v[212:215], v[74:77]
	s_barrier
	s_add_i32 s40, s59, s48
	v_lshl_add_u64 v[216:217], s[44:45], 0, v[150:151]
	s_mov_b32 m0, s40
	ds_read_b128 v[184:187], v170 offset:16384
	ds_read_b128 v[188:191], v170 offset:17408
	ds_read_b128 v[192:195], v170 offset:18432
	ds_read_b128 v[196:199], v170 offset:19456
	ds_read_b128 v[200:203], v170 offset:20480
	ds_read_b128 v[204:207], v170 offset:21504
	ds_read_b128 v[208:211], v170 offset:22528
	ds_read_b128 v[212:215], v170 offset:23552
	global_load_lds_dwordx4 v[216:217], off
	s_add_i32 m0, s40, 0x2000
	s_add_u32 s40, s44, 0x28000
	v_lshl_add_u64 v[218:219], s[44:45], 0, v[146:147]
	s_addc_u32 s41, s45, 0
	s_add_i32 s71, s60, s48
	global_load_lds_dwordx4 v[218:219], off
	v_lshl_add_u64 v[220:221], s[40:41], 0, v[150:151]
	s_mov_b32 m0, s71
	v_lshl_add_u64 v[222:223], s[46:47], 0, v[148:149]
	global_load_lds_dwordx4 v[220:221], off
	v_lshl_add_u64 v[220:221], s[40:41], 0, v[146:147]
	s_add_i32 m0, s71, 0x2000
	s_nop 0
	global_load_lds_dwordx4 v[220:221], off
	v_lshl_add_u64 v[220:221], s[46:47], 0, v[152:153]
	s_mov_b32 m0, s51
	s_nop 0
	global_load_lds_dwordx4 v[220:221], off
	s_mov_b32 m0, s52
	s_nop 0
	global_load_lds_dwordx4 v[222:223], off
	s_waitcnt vmcnt(8)
	s_waitcnt lgkmcnt(0)
	s_barrier
; #define PG8_STAGE(bufoff, gbase, voff) do { _Pragma("unroll") for (int _i = 0; _i < 2; ++_i) \
;         __builtin_amdgcn_global_load_lds((const unsigned*)((const char*)(gbase) + (voff)[_i]), (PG8_LAS unsigned*)(lds + (bufoff) + ldsw + _i * 8192), 16, 0, 0); } while (0)
; #define PG8_LDA(dst, b, h) do { _Pragma("unroll") for (int m = 0; m < 4; ++m) _Pragma("unroll") for (int k = 0; k < 2; ++k) dst[m][k] = *(const PG8_LAS bf16x8*)(lds + PG8_SA(b, h) + aoff + m * 2048 + k * 1024); } while (0)
; #define PG8_LDB(dst, b, h) do { _Pragma("unroll") for (int n = 0; n < 2; ++n) _Pragma("unroll") for (int k = 0; k < 2; ++k) dst[n][k] = *(const PG8_LAS bf16x8*)(lds + PG8_SB(b, h) + boff + n * 2048 + k * 1024); } while (0)
; #define PG8_MMA(ai, bj, At, Bt) do { __builtin_amdgcn_s_setprio(1); _Pragma("unroll") for (int m = 0; m < 4; ++m) _Pragma("unroll") for (int n = 0; n < 2; ++n) _Pragma("unroll") for (int k = 0; k < 2; ++k) \
;         acc[ai][bj][m][n] = __builtin_amdgcn_mfma_f32_16x16x32_bf16(Bt[n][k], At[m][k], acc[ai][bj][m][n], 0, 0, 0); __builtin_amdgcn_s_setprio(0); } while (0)
; #define PG8_WAIT_V(n) asm volatile("s_waitcnt vmcnt(" #n ")" ::: "memory")
; #define PG8_WAIT_L(n) asm volatile("s_waitcnt lgkmcnt(" #n ")" ::: "memory")
; #define PG8_BAR __builtin_amdgcn_s_barrier()
; #define PG8_SCHED __builtin_amdgcn_sched_barrier(0)
; template <class Epi, class Sched, bool ALIGN_EPI = false, bool SP2 = false>
; __device__ __forceinline__ void gemm_phase(PG8_LAS unsigned char* lds, const Gemm g, const Sched& S, const Epi& E) {
;     ...
;             PG8_WAIT_V(8); PG8_WAIT_L(0); PG8_BAR; PG8_MMA(1, 0, At, B0); PG8_MMA(1, 1, At, B1); PG8_BAR; PG8_SCHED;
;             PG8_LDB(B0, 1, 0); PG8_LDB(B1, 1, 1); PG8_SCHED; PG8_LDA(At, 1, 0); PG8_STAGE(PG8_SA(0, 1), a2 + hstepA, voffA);
;             PG8_WAIT_V(8); PG8_WAIT_L(0); PG8_BAR; PG8_MMA(0, 0, At, B0); PG8_MMA(0, 1, At, B1); PG8_BAR; PG8_SCHED;
	s_waitcnt lgkmcnt(0)
	v_mfma_f32_16x16x32_bf16 v[70:73], v[62:65], v[184:187], v[70:73]
	v_mfma_f32_16x16x32_bf16 v[58:61], v[138:141], v[184:187], v[58:61]
	v_mfma_f32_16x16x32_bf16 v[46:49], v[62:65], v[192:195], v[46:49]
	v_mfma_f32_16x16x32_bf16 v[42:45], v[138:141], v[192:195], v[42:45]
	v_mfma_f32_16x16x32_bf16 v[30:33], v[62:65], v[200:203], v[30:33]
	v_mfma_f32_16x16x32_bf16 v[26:29], v[138:141], v[200:203], v[26:29]
	v_mfma_f32_16x16x32_bf16 v[14:17], v[62:65], v[208:211], v[14:17]
	v_mfma_f32_16x16x32_bf16 v[10:13], v[138:141], v[208:211], v[10:13]
	v_mfma_f32_16x16x32_bf16 v[70:73], v[66:69], v[188:191], v[70:73]
	v_mfma_f32_16x16x32_bf16 v[58:61], v[142:145], v[188:191], v[58:61]
	v_mfma_f32_16x16x32_bf16 v[46:49], v[66:69], v[196:199], v[46:49]
	v_mfma_f32_16x16x32_bf16 v[42:45], v[142:145], v[196:199], v[42:45]
	v_mfma_f32_16x16x32_bf16 v[30:33], v[66:69], v[204:207], v[30:33]
	v_mfma_f32_16x16x32_bf16 v[26:29], v[142:145], v[204:207], v[26:29]
	v_mfma_f32_16x16x32_bf16 v[14:17], v[66:69], v[212:215], v[14:17]
	v_mfma_f32_16x16x32_bf16 v[10:13], v[142:145], v[212:215], v[10:13]
	v_mfma_f32_16x16x32_bf16 v[54:57], v[162:165], v[184:187], v[54:57]
	v_mfma_f32_16x16x32_bf16 v[50:53], v[176:179], v[184:187], v[50:53]
	v_mfma_f32_16x16x32_bf16 v[38:41], v[162:165], v[192:195], v[38:41]
	v_mfma_f32_16x16x32_bf16 v[34:37], v[176:179], v[192:195], v[34:37]
	v_mfma_f32_16x16x32_bf16 v[22:25], v[162:165], v[200:203], v[22:25]
	v_mfma_f32_16x16x32_bf16 v[18:21], v[176:179], v[200:203], v[18:21]
	v_mfma_f32_16x16x32_bf16 v[6:9], v[162:165], v[208:211], v[6:9]
	v_mfma_f32_16x16x32_bf16 v[2:5], v[176:179], v[208:211], v[2:5]
	v_mfma_f32_16x16x32_bf16 v[54:57], v[172:175], v[188:191], v[54:57]
	v_mfma_f32_16x16x32_bf16 v[50:53], v[180:183], v[188:191], v[50:53]
	v_mfma_f32_16x16x32_bf16 v[38:41], v[172:175], v[196:199], v[38:41]
	v_mfma_f32_16x16x32_bf16 v[34:37], v[180:183], v[196:199], v[34:37]
	v_mfma_f32_16x16x32_bf16 v[22:25], v[172:175], v[204:207], v[22:25]
	v_mfma_f32_16x16x32_bf16 v[18:21], v[180:183], v[204:207], v[18:21]
	v_mfma_f32_16x16x32_bf16 v[6:9], v[172:175], v[212:215], v[6:9]
	v_mfma_f32_16x16x32_bf16 v[2:5], v[180:183], v[212:215], v[2:5]
	s_barrier
	s_add_i32 s71, 0, 0x18000
	s_add_i32 s72, 0, 0x1c000
	v_add_u32_e32 v142, s71, v166
	v_add_u32_e32 v180, s72, v166
	ds_read_b128 v[62:65], v142
	ds_read_b128 v[66:69], v142 offset:1024
	ds_read_b128 v[138:141], v142 offset:2048
	ds_read_b128 v[142:145], v142 offset:3072
	ds_read_b128 v[162:165], v180
	ds_read_b128 v[172:175], v180 offset:1024
	ds_read_b128 v[176:179], v180 offset:2048
	ds_read_b128 v[180:183], v180 offset:3072
	s_add_u32 s40, s46, 0x28000
	s_addc_u32 s41, s47, 0
	s_mov_b32 m0, s53
	v_lshl_add_u64 v[224:225], s[40:41], 0, v[152:153]
	ds_read_b128 v[184:187], v170 offset:32768
	ds_read_b128 v[188:191], v170 offset:33792
	ds_read_b128 v[192:195], v170 offset:34816
	ds_read_b128 v[196:199], v170 offset:35840
	ds_read_b128 v[200:203], v170 offset:36864
	ds_read_b128 v[204:207], v170 offset:37888
	ds_read_b128 v[208:211], v170 offset:38912
	ds_read_b128 v[212:215], v170 offset:39936
	global_load_lds_dwordx4 v[224:225], off
	v_lshl_add_u64 v[224:225], s[40:41], 0, v[148:149]
	s_mov_b32 m0, s54
	s_nop 0
	global_load_lds_dwordx4 v[224:225], off
	s_waitcnt vmcnt(8)
	s_waitcnt lgkmcnt(0)
	s_barrier
	s_waitcnt lgkmcnt(0)
	v_mfma_f32_16x16x32_bf16 v[134:137], v[62:65], v[184:187], v[134:137]
	v_mfma_f32_16x16x32_bf16 v[130:133], v[138:141], v[184:187], v[130:133]
	v_mfma_f32_16x16x32_bf16 v[118:121], v[62:65], v[192:195], v[118:121]
	v_mfma_f32_16x16x32_bf16 v[114:117], v[138:141], v[192:195], v[114:117]
	v_mfma_f32_16x16x32_bf16 v[102:105], v[62:65], v[200:203], v[102:105]
	v_mfma_f32_16x16x32_bf16 v[98:101], v[138:141], v[200:203], v[98:101]
	v_mfma_f32_16x16x32_bf16 v[86:89], v[62:65], v[208:211], v[86:89]
	v_mfma_f32_16x16x32_bf16 v[82:85], v[138:141], v[208:211], v[82:85]
	v_mfma_f32_16x16x32_bf16 v[134:137], v[66:69], v[188:191], v[134:137]
	v_mfma_f32_16x16x32_bf16 v[130:133], v[142:145], v[188:191], v[130:133]
	v_mfma_f32_16x16x32_bf16 v[118:121], v[66:69], v[196:199], v[118:121]
	v_mfma_f32_16x16x32_bf16 v[114:117], v[142:145], v[196:199], v[114:117]
	v_mfma_f32_16x16x32_bf16 v[102:105], v[66:69], v[204:207], v[102:105]
	v_mfma_f32_16x16x32_bf16 v[98:101], v[142:145], v[204:207], v[98:101]
	v_mfma_f32_16x16x32_bf16 v[86:89], v[66:69], v[212:215], v[86:89]
	v_mfma_f32_16x16x32_bf16 v[82:85], v[142:145], v[212:215], v[82:85]
	v_mfma_f32_16x16x32_bf16 v[126:129], v[162:165], v[184:187], v[126:129]
	v_mfma_f32_16x16x32_bf16 v[122:125], v[176:179], v[184:187], v[122:125]
	v_mfma_f32_16x16x32_bf16 v[110:113], v[162:165], v[192:195], v[110:113]
	v_mfma_f32_16x16x32_bf16 v[106:109], v[176:179], v[192:195], v[106:109]
	v_mfma_f32_16x16x32_bf16 v[94:97], v[162:165], v[200:203], v[94:97]
	v_mfma_f32_16x16x32_bf16 v[90:93], v[176:179], v[200:203], v[90:93]
	v_mfma_f32_16x16x32_bf16 v[78:81], v[162:165], v[208:211], v[78:81]
	v_mfma_f32_16x16x32_bf16 v[74:77], v[176:179], v[208:211], v[74:77]
	v_mfma_f32_16x16x32_bf16 v[126:129], v[172:175], v[188:191], v[126:129]
	v_mfma_f32_16x16x32_bf16 v[122:125], v[180:183], v[188:191], v[122:125]
	v_mfma_f32_16x16x32_bf16 v[110:113], v[172:175], v[196:199], v[110:113]
	v_mfma_f32_16x16x32_bf16 v[106:109], v[180:183], v[196:199], v[106:109]
	v_mfma_f32_16x16x32_bf16 v[94:97], v[172:175], v[204:207], v[94:97]
	v_mfma_f32_16x16x32_bf16 v[90:93], v[180:183], v[204:207], v[90:93]
	v_mfma_f32_16x16x32_bf16 v[78:81], v[172:175], v[212:215], v[78:81]
	v_mfma_f32_16x16x32_bf16 v[74:77], v[180:183], v[212:215], v[74:77]
	s_barrier
; #define PG8_STAGE(bufoff, gbase, voff) do { _Pragma("unroll") for (int _i = 0; _i < 2; ++_i) \
;         __builtin_amdgcn_global_load_lds((const unsigned*)((const char*)(gbase) + (voff)[_i]), (PG8_LAS unsigned*)(lds + (bufoff) + ldsw + _i * 8192), 16, 0, 0); } while (0)
; #define PG8_LDA(dst, b, h) do { _Pragma("unroll") for (int m = 0; m < 4; ++m) _Pragma("unroll") for (int k = 0; k < 2; ++k) dst[m][k] = *(const PG8_LAS bf16x8*)(lds + PG8_SA(b, h) + aoff + m * 2048 + k * 1024); } while (0)
; #define PG8_WAIT_V(n) asm volatile("s_waitcnt vmcnt(" #n ")" ::: "memory")
; template <class Epi, class Sched, bool ALIGN_EPI = false, bool SP2 = false>
; __device__ __forceinline__ void gemm_phase(PG8_LAS unsigned char* lds, const Gemm g, const Sched& S, const Epi& E) {
;     ...
;             PG8_LDA(At, 1, 1); PG8_STAGE(PG8_SB(1, 0), b3, voffB); PG8_STAGE(PG8_SB(1, 1), b3 + hstepB, voffB); PG8_STAGE(PG8_SA(1, 0), a3, voffA);
;             PG8_WAIT_V(8); PG8_WAIT_L(0); PG8_BAR; PG8_MMA(1, 0, At, B0); PG8_MMA(1, 1, At, B1); PG8_BAR; PG8_SCHED;
;             } else {
;             PG8_LDB(B0, 0, 0); PG8_SCHED; PG8_LDA(At, 0, 0); PG8_STAGE(PG8_SA(1, 1), a1 + hstepA, voffA);
;             PG8_WAIT_L(8); PG8_BAR; PG8_WAIT_L(0); PG8_MMA(0, 0, At, B0); PG8_BAR; PG8_SCHED;
;             PG8_LDB(B1, 0, 1); PG8_STAGE(PG8_SB(0, 0), b2, voffB);
;             PG8_BAR; PG8_WAIT_L(0); PG8_MMA(0, 1, At, B1); PG8_BAR;
;             PG8_LDA(At, 0, 1); PG8_STAGE(PG8_SA(0, 0), a2, voffA);
;             PG8_BAR; PG8_WAIT_L(0); PG8_MMA(1, 0, At, B0); PG8_BAR; PG8_SCHED;
;             PG8_STAGE(PG8_SB(0, 1), b2 + hstepB, voffB);
;             PG8_WAIT_V(6); PG8_BAR; PG8_MMA(1, 1, At, B1); PG8_BAR;
;             PG8_LDB(B0, 1, 0); PG8_SCHED; PG8_LDA(At, 1, 0); PG8_STAGE(PG8_SA(0, 1), a2 + hstepA, voffA);
;             PG8_WAIT_L(8); PG8_BAR; PG8_WAIT_L(0); PG8_MMA(0, 0, At, B0); PG8_BAR; PG8_SCHED;
;             PG8_LDB(B1, 1, 1); PG8_STAGE(PG8_SB(1, 0), b3, voffB);
;             PG8_BAR; PG8_WAIT_L(0); PG8_MMA(0, 1, At, B1); PG8_BAR;
;             PG8_LDA(At, 1, 1); PG8_STAGE(PG8_SA(1, 0), a3, voffA);
;             PG8_BAR; PG8_WAIT_L(0); PG8_MMA(1, 0, At, B0); PG8_BAR; PG8_SCHED;
;             PG8_STAGE(PG8_SB(1, 1), b3 + hstepB, voffB);
;             PG8_WAIT_V(6); PG8_BAR; PG8_MMA(1, 1, At, B1); PG8_BAR;
;             }
;         }
;         if constexpr (ALIGN_EPI) { if (wr == 0) PG8_BAR; }
	s_add_i32 s40, s71, s48
	v_lshl_add_u64 v[216:217], v[216:217], 0, s[16:17]
	s_mov_b32 m0, s40
	ds_read_b128 v[184:187], v170 offset:49152
	ds_read_b128 v[188:191], v170 offset:50176
	ds_read_b128 v[192:195], v170 offset:51200
	ds_read_b128 v[196:199], v170 offset:52224
	ds_read_b128 v[200:203], v170 offset:53248
	ds_read_b128 v[204:207], v170 offset:54272
	ds_read_b128 v[208:211], v170 offset:55296
	ds_read_b128 v[212:215], v170 offset:56320
	global_load_lds_dwordx4 v[216:217], off
	s_add_i32 m0, s40, 0x2000
	s_add_u32 s40, s44, 0x28080
	v_lshl_add_u64 v[216:217], v[218:219], 0, s[16:17]
	s_addc_u32 s41, s45, 0
	s_add_i32 s44, s72, s48
	global_load_lds_dwordx4 v[216:217], off
	v_lshl_add_u64 v[216:217], s[40:41], 0, v[150:151]
	s_mov_b32 m0, s44
	s_nop 0
	global_load_lds_dwordx4 v[216:217], off
	v_lshl_add_u64 v[216:217], s[40:41], 0, v[146:147]
	s_add_i32 m0, s44, 0x2000
	s_nop 0
	global_load_lds_dwordx4 v[216:217], off
	v_lshl_add_u64 v[216:217], v[220:221], 0, s[16:17]
	s_mov_b32 m0, s56
	s_nop 0
	global_load_lds_dwordx4 v[216:217], off
	v_lshl_add_u64 v[216:217], v[222:223], 0, s[16:17]
	s_mov_b32 m0, s57
	s_nop 0
	global_load_lds_dwordx4 v[216:217], off
	s_waitcnt vmcnt(8)
	s_waitcnt lgkmcnt(0)
	s_barrier
	s_waitcnt lgkmcnt(0)
	v_mfma_f32_16x16x32_bf16 v[70:73], v[62:65], v[184:187], v[70:73]
	v_mfma_f32_16x16x32_bf16 v[58:61], v[138:141], v[184:187], v[58:61]
	v_mfma_f32_16x16x32_bf16 v[46:49], v[62:65], v[192:195], v[46:49]
	v_mfma_f32_16x16x32_bf16 v[42:45], v[138:141], v[192:195], v[42:45]
	v_mfma_f32_16x16x32_bf16 v[30:33], v[62:65], v[200:203], v[30:33]
	v_mfma_f32_16x16x32_bf16 v[26:29], v[138:141], v[200:203], v[26:29]
	v_mfma_f32_16x16x32_bf16 v[14:17], v[62:65], v[208:211], v[14:17]
	v_mfma_f32_16x16x32_bf16 v[10:13], v[138:141], v[208:211], v[10:13]
	v_mfma_f32_16x16x32_bf16 v[70:73], v[66:69], v[188:191], v[70:73]
	v_mfma_f32_16x16x32_bf16 v[58:61], v[142:145], v[188:191], v[58:61]
	v_mfma_f32_16x16x32_bf16 v[46:49], v[66:69], v[196:199], v[46:49]
	v_mfma_f32_16x16x32_bf16 v[42:45], v[142:145], v[196:199], v[42:45]
	v_mfma_f32_16x16x32_bf16 v[30:33], v[66:69], v[204:207], v[30:33]
	v_mfma_f32_16x16x32_bf16 v[26:29], v[142:145], v[204:207], v[26:29]
	v_mfma_f32_16x16x32_bf16 v[14:17], v[66:69], v[212:215], v[14:17]
	v_mfma_f32_16x16x32_bf16 v[10:13], v[142:145], v[212:215], v[10:13]
	v_mfma_f32_16x16x32_bf16 v[54:57], v[162:165], v[184:187], v[54:57]
	v_mfma_f32_16x16x32_bf16 v[50:53], v[176:179], v[184:187], v[50:53]
	v_mfma_f32_16x16x32_bf16 v[38:41], v[162:165], v[192:195], v[38:41]
	v_mfma_f32_16x16x32_bf16 v[34:37], v[176:179], v[192:195], v[34:37]
	v_mfma_f32_16x16x32_bf16 v[22:25], v[162:165], v[200:203], v[22:25]
	v_mfma_f32_16x16x32_bf16 v[18:21], v[176:179], v[200:203], v[18:21]
	v_mfma_f32_16x16x32_bf16 v[6:9], v[162:165], v[208:211], v[6:9]
	v_mfma_f32_16x16x32_bf16 v[2:5], v[176:179], v[208:211], v[2:5]
	v_mfma_f32_16x16x32_bf16 v[54:57], v[172:175], v[188:191], v[54:57]
	v_mfma_f32_16x16x32_bf16 v[50:53], v[180:183], v[188:191], v[50:53]
	v_mfma_f32_16x16x32_bf16 v[38:41], v[172:175], v[196:199], v[38:41]
	v_mfma_f32_16x16x32_bf16 v[34:37], v[180:183], v[196:199], v[34:37]
	v_mfma_f32_16x16x32_bf16 v[22:25], v[172:175], v[204:207], v[22:25]
	v_mfma_f32_16x16x32_bf16 v[18:21], v[180:183], v[204:207], v[18:21]
	v_mfma_f32_16x16x32_bf16 v[6:9], v[172:175], v[212:215], v[6:9]
	v_mfma_f32_16x16x32_bf16 v[2:5], v[180:183], v[212:215], v[2:5]
	s_barrier
	s_add_i32 s33, s33, 2
	s_add_u32 s2, s2, 0x100
	s_addc_u32 s5, s5, 0
	s_cmp_gt_u32 s33, 7
	s_mov_b64 s[40:41], s[42:43]
	s_cbranch_scc0 .LBB0_430
	s_and_b64 vcc, exec, s[18:19]
	s_cbranch_vccz .LBB0_433
	s_barrier

; #define PG8_STAGE(bufoff, gbase, voff) do { _Pragma("unroll") for (int _i = 0; _i < 2; ++_i) \
;         __builtin_amdgcn_global_load_lds((const unsigned*)((const char*)(gbase) + (voff)[_i]), (PG8_LAS unsigned*)(lds + (bufoff) + ldsw + _i * 8192), 16, 0, 0); } while (0)
; #define PG8_LDA(dst, b, h) do { _Pragma("unroll") for (int m = 0; m < 4; ++m) _Pragma("unroll") for (int k = 0; k < 2; ++k) dst[m][k] = *(const PG8_LAS bf16x8*)(lds + PG8_SA(b, h) + aoff + m * 2048 + k * 1024); } while (0)
; #define PG8_LDB(dst, b, h) do { _Pragma("unroll") for (int n = 0; n < 2; ++n) _Pragma("unroll") for (int k = 0; k < 2; ++k) dst[n][k] = *(const PG8_LAS bf16x8*)(lds + PG8_SB(b, h) + boff + n * 2048 + k * 1024); } while (0)
; #define PG8_MMA(ai, bj, At, Bt) do { __builtin_amdgcn_s_setprio(1); _Pragma("unroll") for (int m = 0; m < 4; ++m) _Pragma("unroll") for (int n = 0; n < 2; ++n) _Pragma("unroll") for (int k = 0; k < 2; ++k) \
;         acc[ai][bj][m][n] = __builtin_amdgcn_mfma_f32_16x16x32_bf16(Bt[n][k], At[m][k], acc[ai][bj][m][n], 0, 0, 0); __builtin_amdgcn_s_setprio(0); } while (0)
; #define PG8_WAIT_V(n) asm volatile("s_waitcnt vmcnt(" #n ")" ::: "memory")
; #define PG8_WAIT_L(n) asm volatile("s_waitcnt lgkmcnt(" #n ")" ::: "memory")
; #define PG8_BAR __builtin_amdgcn_s_barrier()
; #define PG8_SCHED __builtin_amdgcn_sched_barrier(0)
; template <class Epi, class Sched, bool ALIGN_EPI = false, bool SP2 = false>
; __device__ __forceinline__ void gemm_phase(PG8_LAS unsigned char* lds, const Gemm g, const Sched& S, const Epi& E) {
;     ...
;             PG8_LDB(B0, 0, 0); PG8_LDB(B1, 0, 1); PG8_SCHED; PG8_LDA(At, 0, 0); PG8_STAGE(PG8_SA(1, 1), a1 + hstepA, voffA);
;             PG8_WAIT_V(8); PG8_WAIT_L(0); PG8_BAR; PG8_MMA(0, 0, At, B0); PG8_MMA(0, 1, At, B1); PG8_BAR; PG8_SCHED;
;             PG8_LDA(At, 0, 1); PG8_STAGE(PG8_SB(0, 0), b2, voffB); PG8_STAGE(PG8_SB(0, 1), b2 + hstepB, voffB); PG8_STAGE(PG8_SA(0, 0), a2, voffA);
.LBB0_523:
	ds_read_b128 v[146:149], v152
	ds_read_b128 v[156:159], v152 offset:1024
	ds_read_b128 v[160:163], v152 offset:2048
	ds_read_b128 v[164:167], v152 offset:3072
	ds_read_b128 v[168:171], v153
	ds_read_b128 v[172:175], v153 offset:1024
	ds_read_b128 v[176:179], v153 offset:2048
	ds_read_b128 v[180:183], v153 offset:3072
	s_add_u32 s28, s26, 0xfffe0080
	s_addc_u32 s29, s27, -1
	s_cmp_eq_u32 s48, 4
	s_cselect_b32 s31, s19, s29
	s_cselect_b32 s30, s44, s28
	s_cselect_b32 s29, s17, s47
	s_cselect_b32 s28, s45, s46
	v_lshl_add_u64 v[216:217], s[26:27], 0, v[138:139]
	s_add_i32 m0, s25, 0xc000
	ds_read_b128 v[184:187], v154
	ds_read_b128 v[188:191], v154 offset:1024
	ds_read_b128 v[192:195], v154 offset:2048
	ds_read_b128 v[196:199], v154 offset:3072
	ds_read_b128 v[200:203], v154 offset:4096
	ds_read_b128 v[204:207], v154 offset:5120
	ds_read_b128 v[208:211], v154 offset:6144
	ds_read_b128 v[212:215], v154 offset:7168
	global_load_lds_dwordx4 v[216:217], off
	v_lshl_add_u64 v[216:217], s[26:27], 0, v[140:141]
	s_add_i32 m0, s25, 0xe000
	s_nop 0
	global_load_lds_dwordx4 v[216:217], off
	s_waitcnt vmcnt(8)
	s_waitcnt lgkmcnt(0)
	s_barrier
	s_waitcnt lgkmcnt(0)
	v_mfma_f32_16x16x32_bf16 v[126:129], v[146:149], v[184:187], v[126:129]
	v_mfma_f32_16x16x32_bf16 v[122:125], v[160:163], v[184:187], v[122:125]
	v_mfma_f32_16x16x32_bf16 v[110:113], v[146:149], v[192:195], v[110:113]
	v_mfma_f32_16x16x32_bf16 v[106:109], v[160:163], v[192:195], v[106:109]
	v_mfma_f32_16x16x32_bf16 v[94:97], v[146:149], v[200:203], v[94:97]
	v_mfma_f32_16x16x32_bf16 v[90:93], v[160:163], v[200:203], v[90:93]
	v_mfma_f32_16x16x32_bf16 v[78:81], v[146:149], v[208:211], v[78:81]
	v_mfma_f32_16x16x32_bf16 v[74:77], v[160:163], v[208:211], v[74:77]
	v_mfma_f32_16x16x32_bf16 v[126:129], v[156:159], v[188:191], v[126:129]
	v_mfma_f32_16x16x32_bf16 v[122:125], v[164:167], v[188:191], v[122:125]
	v_mfma_f32_16x16x32_bf16 v[110:113], v[156:159], v[196:199], v[110:113]
	v_mfma_f32_16x16x32_bf16 v[106:109], v[164:167], v[196:199], v[106:109]
	v_mfma_f32_16x16x32_bf16 v[94:97], v[156:159], v[204:207], v[94:97]
	v_mfma_f32_16x16x32_bf16 v[90:93], v[164:167], v[204:207], v[90:93]
	v_mfma_f32_16x16x32_bf16 v[78:81], v[156:159], v[212:215], v[78:81]
	v_mfma_f32_16x16x32_bf16 v[74:77], v[164:167], v[212:215], v[74:77]
	v_mfma_f32_16x16x32_bf16 v[118:121], v[168:171], v[184:187], v[118:121]
	v_mfma_f32_16x16x32_bf16 v[114:117], v[176:179], v[184:187], v[114:117]
	v_mfma_f32_16x16x32_bf16 v[102:105], v[168:171], v[192:195], v[102:105]
	v_mfma_f32_16x16x32_bf16 v[98:101], v[176:179], v[192:195], v[98:101]
	v_mfma_f32_16x16x32_bf16 v[86:89], v[168:171], v[200:203], v[86:89]
	v_mfma_f32_16x16x32_bf16 v[82:85], v[176:179], v[200:203], v[82:85]
	v_mfma_f32_16x16x32_bf16 v[70:73], v[168:171], v[208:211], v[70:73]
	v_mfma_f32_16x16x32_bf16 v[66:69], v[176:179], v[208:211], v[66:69]
	v_mfma_f32_16x16x32_bf16 v[118:121], v[172:175], v[188:191], v[118:121]
	v_mfma_f32_16x16x32_bf16 v[114:117], v[180:183], v[188:191], v[114:117]
	v_mfma_f32_16x16x32_bf16 v[102:105], v[172:175], v[196:199], v[102:105]
	v_mfma_f32_16x16x32_bf16 v[98:101], v[180:183], v[196:199], v[98:101]
	v_mfma_f32_16x16x32_bf16 v[86:89], v[172:175], v[204:207], v[86:89]
	v_mfma_f32_16x16x32_bf16 v[82:85], v[180:183], v[204:207], v[82:85]
	v_mfma_f32_16x16x32_bf16 v[70:73], v[172:175], v[212:215], v[70:73]
	v_mfma_f32_16x16x32_bf16 v[66:69], v[180:183], v[212:215], v[66:69]
	s_barrier
	s_add_i32 s49, s41, s2
	v_lshl_add_u64 v[216:217], s[28:29], 0, v[132:133]
	s_mov_b32 m0, s49
	ds_read_b128 v[184:187], v154 offset:16384
	ds_read_b128 v[188:191], v154 offset:17408
	ds_read_b128 v[192:195], v154 offset:18432
	ds_read_b128 v[196:199], v154 offset:19456
	ds_read_b128 v[200:203], v154 offset:20480
	ds_read_b128 v[204:207], v154 offset:21504
	ds_read_b128 v[208:211], v154 offset:22528
	ds_read_b128 v[212:215], v154 offset:23552
	global_load_lds_dwordx4 v[216:217], off
	s_add_i32 m0, s49, 0x2000
	s_add_u32 s50, s28, 0x20000
	v_lshl_add_u64 v[218:219], s[28:29], 0, v[136:137]
	s_addc_u32 s51, s29, 0
	s_add_i32 s49, s42, s2
	global_load_lds_dwordx4 v[218:219], off
	v_lshl_add_u64 v[220:221], s[50:51], 0, v[132:133]
	s_mov_b32 m0, s49
	v_lshl_add_u64 v[222:223], s[30:31], 0, v[134:135]
	global_load_lds_dwordx4 v[220:221], off
	v_lshl_add_u64 v[220:221], s[50:51], 0, v[136:137]
	s_add_i32 m0, s49, 0x2000
	s_nop 0
	global_load_lds_dwordx4 v[220:221], off
	v_lshl_add_u64 v[220:221], s[30:31], 0, v[130:131]
	s_mov_b32 m0, s25
	s_nop 0
	global_load_lds_dwordx4 v[220:221], off
	s_mov_b32 m0, s35
	s_nop 0
	global_load_lds_dwordx4 v[222:223], off
	s_waitcnt vmcnt(8)
	s_waitcnt lgkmcnt(0)
	s_barrier
; #define PG8_STAGE(bufoff, gbase, voff) do { _Pragma("unroll") for (int _i = 0; _i < 2; ++_i) \
;         __builtin_amdgcn_global_load_lds((const unsigned*)((const char*)(gbase) + (voff)[_i]), (PG8_LAS unsigned*)(lds + (bufoff) + ldsw + _i * 8192), 16, 0, 0); } while (0)
; #define PG8_LDA(dst, b, h) do { _Pragma("unroll") for (int m = 0; m < 4; ++m) _Pragma("unroll") for (int k = 0; k < 2; ++k) dst[m][k] = *(const PG8_LAS bf16x8*)(lds + PG8_SA(b, h) + aoff + m * 2048 + k * 1024); } while (0)
; #define PG8_LDB(dst, b, h) do { _Pragma("unroll") for (int n = 0; n < 2; ++n) _Pragma("unroll") for (int k = 0; k < 2; ++k) dst[n][k] = *(const PG8_LAS bf16x8*)(lds + PG8_SB(b, h) + boff + n * 2048 + k * 1024); } while (0)
; #define PG8_MMA(ai, bj, At, Bt) do { __builtin_amdgcn_s_setprio(1); _Pragma("unroll") for (int m = 0; m < 4; ++m) _Pragma("unroll") for (int n = 0; n < 2; ++n) _Pragma("unroll") for (int k = 0; k < 2; ++k) \
;         acc[ai][bj][m][n] = __builtin_amdgcn_mfma_f32_16x16x32_bf16(Bt[n][k], At[m][k], acc[ai][bj][m][n], 0, 0, 0); __builtin_amdgcn_s_setprio(0); } while (0)
; #define PG8_WAIT_V(n) asm volatile("s_waitcnt vmcnt(" #n ")" ::: "memory")
; #define PG8_WAIT_L(n) asm volatile("s_waitcnt lgkmcnt(" #n ")" ::: "memory")
; #define PG8_BAR __builtin_amdgcn_s_barrier()
; #define PG8_SCHED __builtin_amdgcn_sched_barrier(0)
; template <class Epi, class Sched, bool ALIGN_EPI = false, bool SP2 = false>
; __device__ __forceinline__ void gemm_phase(PG8_LAS unsigned char* lds, const Gemm g, const Sched& S, const Epi& E) {
;     ...
;             PG8_WAIT_V(8); PG8_WAIT_L(0); PG8_BAR; PG8_MMA(1, 0, At, B0); PG8_MMA(1, 1, At, B1); PG8_BAR; PG8_SCHED;
;             PG8_LDB(B0, 1, 0); PG8_LDB(B1, 1, 1); PG8_SCHED; PG8_LDA(At, 1, 0); PG8_STAGE(PG8_SA(0, 1), a2 + hstepA, voffA);
;             PG8_WAIT_V(8); PG8_WAIT_L(0); PG8_BAR; PG8_MMA(0, 0, At, B0); PG8_MMA(0, 1, At, B1); PG8_BAR; PG8_SCHED;
	s_waitcnt lgkmcnt(0)
	v_mfma_f32_16x16x32_bf16 v[62:65], v[146:149], v[184:187], v[62:65]
	v_mfma_f32_16x16x32_bf16 v[58:61], v[160:163], v[184:187], v[58:61]
	v_mfma_f32_16x16x32_bf16 v[46:49], v[146:149], v[192:195], v[46:49]
	v_mfma_f32_16x16x32_bf16 v[42:45], v[160:163], v[192:195], v[42:45]
	v_mfma_f32_16x16x32_bf16 v[30:33], v[146:149], v[200:203], v[30:33]
	v_mfma_f32_16x16x32_bf16 v[26:29], v[160:163], v[200:203], v[26:29]
	v_mfma_f32_16x16x32_bf16 v[14:17], v[146:149], v[208:211], v[14:17]
	v_mfma_f32_16x16x32_bf16 v[10:13], v[160:163], v[208:211], v[10:13]
	v_mfma_f32_16x16x32_bf16 v[62:65], v[156:159], v[188:191], v[62:65]
	v_mfma_f32_16x16x32_bf16 v[58:61], v[164:167], v[188:191], v[58:61]
	v_mfma_f32_16x16x32_bf16 v[46:49], v[156:159], v[196:199], v[46:49]
	v_mfma_f32_16x16x32_bf16 v[42:45], v[164:167], v[196:199], v[42:45]
	v_mfma_f32_16x16x32_bf16 v[30:33], v[156:159], v[204:207], v[30:33]
	v_mfma_f32_16x16x32_bf16 v[26:29], v[164:167], v[204:207], v[26:29]
	v_mfma_f32_16x16x32_bf16 v[14:17], v[156:159], v[212:215], v[14:17]
	v_mfma_f32_16x16x32_bf16 v[10:13], v[164:167], v[212:215], v[10:13]
	v_mfma_f32_16x16x32_bf16 v[54:57], v[168:171], v[184:187], v[54:57]
	v_mfma_f32_16x16x32_bf16 v[50:53], v[176:179], v[184:187], v[50:53]
	v_mfma_f32_16x16x32_bf16 v[38:41], v[168:171], v[192:195], v[38:41]
	v_mfma_f32_16x16x32_bf16 v[34:37], v[176:179], v[192:195], v[34:37]
	v_mfma_f32_16x16x32_bf16 v[22:25], v[168:171], v[200:203], v[22:25]
	v_mfma_f32_16x16x32_bf16 v[18:21], v[176:179], v[200:203], v[18:21]
	v_mfma_f32_16x16x32_bf16 v[6:9], v[168:171], v[208:211], v[6:9]
	v_mfma_f32_16x16x32_bf16 v[2:5], v[176:179], v[208:211], v[2:5]
	v_mfma_f32_16x16x32_bf16 v[54:57], v[172:175], v[188:191], v[54:57]
	v_mfma_f32_16x16x32_bf16 v[50:53], v[180:183], v[188:191], v[50:53]
	v_mfma_f32_16x16x32_bf16 v[38:41], v[172:175], v[196:199], v[38:41]
	v_mfma_f32_16x16x32_bf16 v[34:37], v[180:183], v[196:199], v[34:37]
	v_mfma_f32_16x16x32_bf16 v[22:25], v[172:175], v[204:207], v[22:25]
	v_mfma_f32_16x16x32_bf16 v[18:21], v[180:183], v[204:207], v[18:21]
	v_mfma_f32_16x16x32_bf16 v[6:9], v[172:175], v[212:215], v[6:9]
	v_mfma_f32_16x16x32_bf16 v[2:5], v[180:183], v[212:215], v[2:5]
	s_barrier
	s_add_i32 s49, 0, 0x18000
	v_add_u32_e32 v155, s49, v150
	s_add_i32 s50, 0, 0x1c000
	ds_read_b128 v[146:149], v155
	ds_read_b128 v[156:159], v155 offset:1024
	ds_read_b128 v[160:163], v155 offset:2048
	ds_read_b128 v[164:167], v155 offset:3072
	v_add_u32_e32 v155, s50, v150
	ds_read_b128 v[168:171], v155
	ds_read_b128 v[172:175], v155 offset:1024
	ds_read_b128 v[176:179], v155 offset:2048
	ds_read_b128 v[180:183], v155 offset:3072
	s_add_u32 s30, s30, 0x20000
	s_addc_u32 s31, s31, 0
	s_mov_b32 m0, s36
	v_lshl_add_u64 v[224:225], s[30:31], 0, v[130:131]
	ds_read_b128 v[184:187], v154 offset:32768
	ds_read_b128 v[188:191], v154 offset:33792
	ds_read_b128 v[192:195], v154 offset:34816
	ds_read_b128 v[196:199], v154 offset:35840
	ds_read_b128 v[200:203], v154 offset:36864
	ds_read_b128 v[204:207], v154 offset:37888
	ds_read_b128 v[208:211], v154 offset:38912
	ds_read_b128 v[212:215], v154 offset:39936
	global_load_lds_dwordx4 v[224:225], off
	v_lshl_add_u64 v[224:225], s[30:31], 0, v[134:135]
	s_mov_b32 m0, s37
	s_nop 0
	global_load_lds_dwordx4 v[224:225], off
	s_waitcnt vmcnt(8)
	s_waitcnt lgkmcnt(0)
	s_barrier
	s_waitcnt lgkmcnt(0)
	v_mfma_f32_16x16x32_bf16 v[126:129], v[146:149], v[184:187], v[126:129]
	v_mfma_f32_16x16x32_bf16 v[122:125], v[160:163], v[184:187], v[122:125]
	v_mfma_f32_16x16x32_bf16 v[110:113], v[146:149], v[192:195], v[110:113]
	v_mfma_f32_16x16x32_bf16 v[106:109], v[160:163], v[192:195], v[106:109]
	v_mfma_f32_16x16x32_bf16 v[94:97], v[146:149], v[200:203], v[94:97]
	v_mfma_f32_16x16x32_bf16 v[90:93], v[160:163], v[200:203], v[90:93]
	v_mfma_f32_16x16x32_bf16 v[78:81], v[146:149], v[208:211], v[78:81]
	v_mfma_f32_16x16x32_bf16 v[74:77], v[160:163], v[208:211], v[74:77]
	v_mfma_f32_16x16x32_bf16 v[126:129], v[156:159], v[188:191], v[126:129]
	v_mfma_f32_16x16x32_bf16 v[122:125], v[164:167], v[188:191], v[122:125]
	v_mfma_f32_16x16x32_bf16 v[110:113], v[156:159], v[196:199], v[110:113]
	v_mfma_f32_16x16x32_bf16 v[106:109], v[164:167], v[196:199], v[106:109]
	v_mfma_f32_16x16x32_bf16 v[94:97], v[156:159], v[204:207], v[94:97]
	v_mfma_f32_16x16x32_bf16 v[90:93], v[164:167], v[204:207], v[90:93]
	v_mfma_f32_16x16x32_bf16 v[78:81], v[156:159], v[212:215], v[78:81]
	v_mfma_f32_16x16x32_bf16 v[74:77], v[164:167], v[212:215], v[74:77]
	v_mfma_f32_16x16x32_bf16 v[118:121], v[168:171], v[184:187], v[118:121]
	v_mfma_f32_16x16x32_bf16 v[114:117], v[176:179], v[184:187], v[114:117]
	v_mfma_f32_16x16x32_bf16 v[102:105], v[168:171], v[192:195], v[102:105]
	v_mfma_f32_16x16x32_bf16 v[98:101], v[176:179], v[192:195], v[98:101]
	v_mfma_f32_16x16x32_bf16 v[86:89], v[168:171], v[200:203], v[86:89]
	v_mfma_f32_16x16x32_bf16 v[82:85], v[176:179], v[200:203], v[82:85]
	v_mfma_f32_16x16x32_bf16 v[70:73], v[168:171], v[208:211], v[70:73]
	v_mfma_f32_16x16x32_bf16 v[66:69], v[176:179], v[208:211], v[66:69]
	v_mfma_f32_16x16x32_bf16 v[118:121], v[172:175], v[188:191], v[118:121]
	v_mfma_f32_16x16x32_bf16 v[114:117], v[180:183], v[188:191], v[114:117]
	v_mfma_f32_16x16x32_bf16 v[102:105], v[172:175], v[196:199], v[102:105]
	v_mfma_f32_16x16x32_bf16 v[98:101], v[180:183], v[196:199], v[98:101]
	v_mfma_f32_16x16x32_bf16 v[86:89], v[172:175], v[204:207], v[86:89]
	v_mfma_f32_16x16x32_bf16 v[82:85], v[180:183], v[204:207], v[82:85]
	v_mfma_f32_16x16x32_bf16 v[70:73], v[172:175], v[212:215], v[70:73]
	v_mfma_f32_16x16x32_bf16 v[66:69], v[180:183], v[212:215], v[66:69]
	s_barrier
; #define PG8_STAGE(bufoff, gbase, voff) do { _Pragma("unroll") for (int _i = 0; _i < 2; ++_i) \
;         __builtin_amdgcn_global_load_lds((const unsigned*)((const char*)(gbase) + (voff)[_i]), (PG8_LAS unsigned*)(lds + (bufoff) + ldsw + _i * 8192), 16, 0, 0); } while (0)
; #define PG8_LDA(dst, b, h) do { _Pragma("unroll") for (int m = 0; m < 4; ++m) _Pragma("unroll") for (int k = 0; k < 2; ++k) dst[m][k] = *(const PG8_LAS bf16x8*)(lds + PG8_SA(b, h) + aoff + m * 2048 + k * 1024); } while (0)
; #define PG8_WAIT_V(n) asm volatile("s_waitcnt vmcnt(" #n ")" ::: "memory")
; template <class Epi, class Sched, bool ALIGN_EPI = false, bool SP2 = false>
; __device__ __forceinline__ void gemm_phase(PG8_LAS unsigned char* lds, const Gemm g, const Sched& S, const Epi& E) {
;     ...
;             PG8_LDA(At, 1, 1); PG8_STAGE(PG8_SB(1, 0), b3, voffB); PG8_STAGE(PG8_SB(1, 1), b3 + hstepB, voffB); PG8_STAGE(PG8_SA(1, 0), a3, voffA);
;             PG8_WAIT_V(8); PG8_WAIT_L(0); PG8_BAR; PG8_MMA(1, 0, At, B0); PG8_MMA(1, 1, At, B1); PG8_BAR; PG8_SCHED;
;             } else {
;             PG8_LDB(B0, 0, 0); PG8_SCHED; PG8_LDA(At, 0, 0); PG8_STAGE(PG8_SA(1, 1), a1 + hstepA, voffA);
;             PG8_WAIT_L(8); PG8_BAR; PG8_WAIT_L(0); PG8_MMA(0, 0, At, B0); PG8_BAR; PG8_SCHED;
;             PG8_LDB(B1, 0, 1); PG8_STAGE(PG8_SB(0, 0), b2, voffB);
;             PG8_BAR; PG8_WAIT_L(0); PG8_MMA(0, 1, At, B1); PG8_BAR;
;             PG8_LDA(At, 0, 1); PG8_STAGE(PG8_SA(0, 0), a2, voffA);
;             PG8_BAR; PG8_WAIT_L(0); PG8_MMA(1, 0, At, B0); PG8_BAR; PG8_SCHED;
;             PG8_STAGE(PG8_SB(0, 1), b2 + hstepB, voffB);
;             PG8_WAIT_V(6); PG8_BAR; PG8_MMA(1, 1, At, B1); PG8_BAR;
;             PG8_LDB(B0, 1, 0); PG8_SCHED; PG8_LDA(At, 1, 0); PG8_STAGE(PG8_SA(0, 1), a2 + hstepA, voffA);
;             PG8_WAIT_L(8); PG8_BAR; PG8_WAIT_L(0); PG8_MMA(0, 0, At, B0); PG8_BAR; PG8_SCHED;
;             PG8_LDB(B1, 1, 1); PG8_STAGE(PG8_SB(1, 0), b3, voffB);
;             PG8_BAR; PG8_WAIT_L(0); PG8_MMA(0, 1, At, B1); PG8_BAR;
;             PG8_LDA(At, 1, 1); PG8_STAGE(PG8_SA(1, 0), a3, voffA);
;             PG8_BAR; PG8_WAIT_L(0); PG8_MMA(1, 0, At, B0); PG8_BAR; PG8_SCHED;
;             PG8_STAGE(PG8_SB(1, 1), b3 + hstepB, voffB);
;             PG8_WAIT_V(6); PG8_BAR; PG8_MMA(1, 1, At, B1); PG8_BAR;
;             }
;         }
;         if constexpr (ALIGN_EPI) { if (wr == 0) PG8_BAR; }
	s_add_i32 s30, s49, s2
	v_lshl_add_u64 v[216:217], v[216:217], 0, s[14:15]
	s_mov_b32 m0, s30
	ds_read_b128 v[184:187], v154 offset:49152
	ds_read_b128 v[188:191], v154 offset:50176
	ds_read_b128 v[192:195], v154 offset:51200
	ds_read_b128 v[196:199], v154 offset:52224
	ds_read_b128 v[200:203], v154 offset:53248
	ds_read_b128 v[204:207], v154 offset:54272
	ds_read_b128 v[208:211], v154 offset:55296
	ds_read_b128 v[212:215], v154 offset:56320
	global_load_lds_dwordx4 v[216:217], off
	s_add_i32 m0, s30, 0x2000
	s_add_u32 s28, s28, 0x20080
	v_lshl_add_u64 v[216:217], v[218:219], 0, s[14:15]
	s_addc_u32 s29, s29, 0
	s_add_i32 s30, s50, s2
	global_load_lds_dwordx4 v[216:217], off
	v_lshl_add_u64 v[216:217], s[28:29], 0, v[132:133]
	s_mov_b32 m0, s30
	s_nop 0
	global_load_lds_dwordx4 v[216:217], off
	v_lshl_add_u64 v[216:217], s[28:29], 0, v[136:137]
	s_add_i32 m0, s30, 0x2000
	s_nop 0
	global_load_lds_dwordx4 v[216:217], off
	v_lshl_add_u64 v[216:217], v[220:221], 0, s[14:15]
	s_mov_b32 m0, s39
	s_nop 0
	global_load_lds_dwordx4 v[216:217], off
	v_lshl_add_u64 v[216:217], v[222:223], 0, s[14:15]
	s_mov_b32 m0, s40
	s_nop 0
	global_load_lds_dwordx4 v[216:217], off
	s_waitcnt vmcnt(8)
	s_waitcnt lgkmcnt(0)
	s_barrier
	s_waitcnt lgkmcnt(0)
	v_mfma_f32_16x16x32_bf16 v[62:65], v[146:149], v[184:187], v[62:65]
	v_mfma_f32_16x16x32_bf16 v[58:61], v[160:163], v[184:187], v[58:61]
	v_mfma_f32_16x16x32_bf16 v[46:49], v[146:149], v[192:195], v[46:49]
	v_mfma_f32_16x16x32_bf16 v[42:45], v[160:163], v[192:195], v[42:45]
	v_mfma_f32_16x16x32_bf16 v[30:33], v[146:149], v[200:203], v[30:33]
	v_mfma_f32_16x16x32_bf16 v[26:29], v[160:163], v[200:203], v[26:29]
	v_mfma_f32_16x16x32_bf16 v[14:17], v[146:149], v[208:211], v[14:17]
	v_mfma_f32_16x16x32_bf16 v[10:13], v[160:163], v[208:211], v[10:13]
	v_mfma_f32_16x16x32_bf16 v[62:65], v[156:159], v[188:191], v[62:65]
	v_mfma_f32_16x16x32_bf16 v[58:61], v[164:167], v[188:191], v[58:61]
	v_mfma_f32_16x16x32_bf16 v[46:49], v[156:159], v[196:199], v[46:49]
	v_mfma_f32_16x16x32_bf16 v[42:45], v[164:167], v[196:199], v[42:45]
	v_mfma_f32_16x16x32_bf16 v[30:33], v[156:159], v[204:207], v[30:33]
	v_mfma_f32_16x16x32_bf16 v[26:29], v[164:167], v[204:207], v[26:29]
	v_mfma_f32_16x16x32_bf16 v[14:17], v[156:159], v[212:215], v[14:17]
	v_mfma_f32_16x16x32_bf16 v[10:13], v[164:167], v[212:215], v[10:13]
	v_mfma_f32_16x16x32_bf16 v[54:57], v[168:171], v[184:187], v[54:57]
	v_mfma_f32_16x16x32_bf16 v[50:53], v[176:179], v[184:187], v[50:53]
	v_mfma_f32_16x16x32_bf16 v[38:41], v[168:171], v[192:195], v[38:41]
	v_mfma_f32_16x16x32_bf16 v[34:37], v[176:179], v[192:195], v[34:37]
	v_mfma_f32_16x16x32_bf16 v[22:25], v[168:171], v[200:203], v[22:25]
	v_mfma_f32_16x16x32_bf16 v[18:21], v[176:179], v[200:203], v[18:21]
	v_mfma_f32_16x16x32_bf16 v[6:9], v[168:171], v[208:211], v[6:9]
	v_mfma_f32_16x16x32_bf16 v[2:5], v[176:179], v[208:211], v[2:5]
	v_mfma_f32_16x16x32_bf16 v[54:57], v[172:175], v[188:191], v[54:57]
	v_mfma_f32_16x16x32_bf16 v[50:53], v[180:183], v[188:191], v[50:53]
	v_mfma_f32_16x16x32_bf16 v[38:41], v[172:175], v[196:199], v[38:41]
	v_mfma_f32_16x16x32_bf16 v[34:37], v[180:183], v[196:199], v[34:37]
	v_mfma_f32_16x16x32_bf16 v[22:25], v[172:175], v[204:207], v[22:25]
	v_mfma_f32_16x16x32_bf16 v[18:21], v[180:183], v[204:207], v[18:21]
	v_mfma_f32_16x16x32_bf16 v[6:9], v[172:175], v[212:215], v[6:9]
	v_mfma_f32_16x16x32_bf16 v[2:5], v[180:183], v[212:215], v[2:5]
	s_barrier
	s_add_i32 s48, s48, 2
	s_add_u32 s26, s26, 0x100
	s_addc_u32 s27, s27, 0
	s_add_u32 s46, s46, 0x100
	s_addc_u32 s47, s47, 0
	s_cmp_gt_u32 s48, 5
	s_cbranch_scc0 .LBB0_523
	s_and_b64 vcc, exec, s[4:5]
	s_cbranch_vccz .LBB0_526
	s_barrier

; #define PG8_STAGE(bufoff, gbase, voff) do { _Pragma("unroll") for (int _i = 0; _i < 2; ++_i) \
;         __builtin_amdgcn_global_load_lds((const unsigned*)((const char*)(gbase) + (voff)[_i]), (PG8_LAS unsigned*)(lds + (bufoff) + ldsw + _i * 8192), 16, 0, 0); } while (0)
; #define PG8_LDA(dst, b, h) do { _Pragma("unroll") for (int m = 0; m < 4; ++m) _Pragma("unroll") for (int k = 0; k < 2; ++k) dst[m][k] = *(const PG8_LAS bf16x8*)(lds + PG8_SA(b, h) + aoff + m * 2048 + k * 1024); } while (0)
; #define PG8_LDB(dst, b, h) do { _Pragma("unroll") for (int n = 0; n < 2; ++n) _Pragma("unroll") for (int k = 0; k < 2; ++k) dst[n][k] = *(const PG8_LAS bf16x8*)(lds + PG8_SB(b, h) + boff + n * 2048 + k * 1024); } while (0)
; #define PG8_MMA(ai, bj, At, Bt) do { __builtin_amdgcn_s_setprio(1); _Pragma("unroll") for (int m = 0; m < 4; ++m) _Pragma("unroll") for (int n = 0; n < 2; ++n) _Pragma("unroll") for (int k = 0; k < 2; ++k) \
;         acc[ai][bj][m][n] = __builtin_amdgcn_mfma_f32_16x16x32_bf16(Bt[n][k], At[m][k], acc[ai][bj][m][n], 0, 0, 0); __builtin_amdgcn_s_setprio(0); } while (0)
; #define PG8_WAIT_V(n) asm volatile("s_waitcnt vmcnt(" #n ")" ::: "memory")
; #define PG8_WAIT_L(n) asm volatile("s_waitcnt lgkmcnt(" #n ")" ::: "memory")
; #define PG8_BAR __builtin_amdgcn_s_barrier()
; #define PG8_SCHED __builtin_amdgcn_sched_barrier(0)
; template <class Epi, class Sched, bool ALIGN_EPI = false, bool SP2 = false>
; __device__ __forceinline__ void gemm_phase(PG8_LAS unsigned char* lds, const Gemm g, const Sched& S, const Epi& E) {
;     ...
;             PG8_LDB(B0, 0, 0); PG8_LDB(B1, 0, 1); PG8_SCHED; PG8_LDA(At, 0, 0); PG8_STAGE(PG8_SA(1, 1), a1 + hstepA, voffA);
;             PG8_WAIT_V(8); PG8_WAIT_L(0); PG8_BAR; PG8_MMA(0, 0, At, B0); PG8_MMA(0, 1, At, B1); PG8_BAR; PG8_SCHED;
;             PG8_LDA(At, 0, 1); PG8_STAGE(PG8_SB(0, 0), b2, voffB); PG8_STAGE(PG8_SB(0, 1), b2 + hstepB, voffB); PG8_STAGE(PG8_SA(0, 0), a2, voffA);
.LBB0_605:
	ds_read_b128 v[130:133], v172
	ds_read_b128 v[134:137], v172 offset:1024
	ds_read_b128 v[138:141], v172 offset:2048
	ds_read_b128 v[142:145], v172 offset:3072
	ds_read_b128 v[162:165], v173
	ds_read_b128 v[166:169], v173 offset:1024
	ds_read_b128 v[176:179], v173 offset:2048
	ds_read_b128 v[180:183], v173 offset:3072
	s_add_u32 s36, s34, 0xfffc0080
	s_addc_u32 s37, s35, -1
	s_cmp_eq_u32 s56, 12
	s_cselect_b32 s39, s25, s37
	s_cselect_b32 s38, s31, s36
	s_cselect_b32 s37, s23, s55
	s_cselect_b32 s36, s53, s54
	v_lshl_add_u64 v[216:217], s[34:35], 0, v[154:155]
	s_add_i32 m0, s40, 0xc000
	ds_read_b128 v[184:187], v174
	ds_read_b128 v[188:191], v174 offset:1024
	ds_read_b128 v[192:195], v174 offset:2048
	ds_read_b128 v[196:199], v174 offset:3072
	ds_read_b128 v[200:203], v174 offset:4096
	ds_read_b128 v[204:207], v174 offset:5120
	ds_read_b128 v[208:211], v174 offset:6144
	ds_read_b128 v[212:215], v174 offset:7168
	global_load_lds_dwordx4 v[216:217], off
	v_lshl_add_u64 v[216:217], s[34:35], 0, v[156:157]
	s_add_i32 m0, s40, 0xe000
	s_nop 0
	global_load_lds_dwordx4 v[216:217], off
	s_waitcnt vmcnt(8)
	s_waitcnt lgkmcnt(0)
	s_barrier
	s_waitcnt lgkmcnt(0)
	v_mfma_f32_16x16x32_bf16 v[126:129], v[130:133], v[184:187], v[126:129]
	v_mfma_f32_16x16x32_bf16 v[122:125], v[138:141], v[184:187], v[122:125]
	v_mfma_f32_16x16x32_bf16 v[110:113], v[130:133], v[192:195], v[110:113]
	v_mfma_f32_16x16x32_bf16 v[106:109], v[138:141], v[192:195], v[106:109]
	v_mfma_f32_16x16x32_bf16 v[94:97], v[130:133], v[200:203], v[94:97]
	v_mfma_f32_16x16x32_bf16 v[90:93], v[138:141], v[200:203], v[90:93]
	v_mfma_f32_16x16x32_bf16 v[78:81], v[130:133], v[208:211], v[78:81]
	v_mfma_f32_16x16x32_bf16 v[74:77], v[138:141], v[208:211], v[74:77]
	v_mfma_f32_16x16x32_bf16 v[126:129], v[134:137], v[188:191], v[126:129]
	v_mfma_f32_16x16x32_bf16 v[122:125], v[142:145], v[188:191], v[122:125]
	v_mfma_f32_16x16x32_bf16 v[110:113], v[134:137], v[196:199], v[110:113]
	v_mfma_f32_16x16x32_bf16 v[106:109], v[142:145], v[196:199], v[106:109]
	v_mfma_f32_16x16x32_bf16 v[94:97], v[134:137], v[204:207], v[94:97]
	v_mfma_f32_16x16x32_bf16 v[90:93], v[142:145], v[204:207], v[90:93]
	v_mfma_f32_16x16x32_bf16 v[78:81], v[134:137], v[212:215], v[78:81]
	v_mfma_f32_16x16x32_bf16 v[74:77], v[142:145], v[212:215], v[74:77]
	v_mfma_f32_16x16x32_bf16 v[118:121], v[162:165], v[184:187], v[118:121]
	v_mfma_f32_16x16x32_bf16 v[114:117], v[176:179], v[184:187], v[114:117]
	v_mfma_f32_16x16x32_bf16 v[102:105], v[162:165], v[192:195], v[102:105]
	v_mfma_f32_16x16x32_bf16 v[98:101], v[176:179], v[192:195], v[98:101]
	v_mfma_f32_16x16x32_bf16 v[86:89], v[162:165], v[200:203], v[86:89]
	v_mfma_f32_16x16x32_bf16 v[82:85], v[176:179], v[200:203], v[82:85]
	v_mfma_f32_16x16x32_bf16 v[70:73], v[162:165], v[208:211], v[70:73]
	v_mfma_f32_16x16x32_bf16 v[66:69], v[176:179], v[208:211], v[66:69]
	v_mfma_f32_16x16x32_bf16 v[118:121], v[166:169], v[188:191], v[118:121]
	v_mfma_f32_16x16x32_bf16 v[114:117], v[180:183], v[188:191], v[114:117]
	v_mfma_f32_16x16x32_bf16 v[102:105], v[166:169], v[196:199], v[102:105]
	v_mfma_f32_16x16x32_bf16 v[98:101], v[180:183], v[196:199], v[98:101]
	v_mfma_f32_16x16x32_bf16 v[86:89], v[166:169], v[204:207], v[86:89]
	v_mfma_f32_16x16x32_bf16 v[82:85], v[180:183], v[204:207], v[82:85]
	v_mfma_f32_16x16x32_bf16 v[70:73], v[166:169], v[212:215], v[70:73]
	v_mfma_f32_16x16x32_bf16 v[66:69], v[180:183], v[212:215], v[66:69]
	s_barrier
	s_add_i32 s57, s50, s33
	v_lshl_add_u64 v[216:217], s[36:37], 0, v[148:149]
	s_mov_b32 m0, s57
	ds_read_b128 v[184:187], v174 offset:16384
	ds_read_b128 v[188:191], v174 offset:17408
	ds_read_b128 v[192:195], v174 offset:18432
	ds_read_b128 v[196:199], v174 offset:19456
	ds_read_b128 v[200:203], v174 offset:20480
	ds_read_b128 v[204:207], v174 offset:21504
	ds_read_b128 v[208:211], v174 offset:22528
	ds_read_b128 v[212:215], v174 offset:23552
	global_load_lds_dwordx4 v[216:217], off
	s_add_i32 m0, s57, 0x2000
	s_add_u32 s58, s36, 0x40000
	v_lshl_add_u64 v[218:219], s[36:37], 0, v[152:153]
	s_addc_u32 s59, s37, 0
	s_add_i32 s57, s51, s33
	global_load_lds_dwordx4 v[218:219], off
	v_lshl_add_u64 v[220:221], s[58:59], 0, v[148:149]
	s_mov_b32 m0, s57
	v_lshl_add_u64 v[222:223], s[38:39], 0, v[150:151]
	global_load_lds_dwordx4 v[220:221], off
	v_lshl_add_u64 v[220:221], s[58:59], 0, v[152:153]
	s_add_i32 m0, s57, 0x2000
	s_nop 0
	global_load_lds_dwordx4 v[220:221], off
	v_lshl_add_u64 v[220:221], s[38:39], 0, v[146:147]
	s_mov_b32 m0, s40
	s_nop 0
	global_load_lds_dwordx4 v[220:221], off
	s_mov_b32 m0, s41
	s_nop 0
	global_load_lds_dwordx4 v[222:223], off
	s_waitcnt vmcnt(8)
	s_waitcnt lgkmcnt(0)
	s_barrier
; #define PG8_STAGE(bufoff, gbase, voff) do { _Pragma("unroll") for (int _i = 0; _i < 2; ++_i) \
;         __builtin_amdgcn_global_load_lds((const unsigned*)((const char*)(gbase) + (voff)[_i]), (PG8_LAS unsigned*)(lds + (bufoff) + ldsw + _i * 8192), 16, 0, 0); } while (0)
; #define PG8_LDA(dst, b, h) do { _Pragma("unroll") for (int m = 0; m < 4; ++m) _Pragma("unroll") for (int k = 0; k < 2; ++k) dst[m][k] = *(const PG8_LAS bf16x8*)(lds + PG8_SA(b, h) + aoff + m * 2048 + k * 1024); } while (0)
; #define PG8_LDB(dst, b, h) do { _Pragma("unroll") for (int n = 0; n < 2; ++n) _Pragma("unroll") for (int k = 0; k < 2; ++k) dst[n][k] = *(const PG8_LAS bf16x8*)(lds + PG8_SB(b, h) + boff + n * 2048 + k * 1024); } while (0)
; #define PG8_MMA(ai, bj, At, Bt) do { __builtin_amdgcn_s_setprio(1); _Pragma("unroll") for (int m = 0; m < 4; ++m) _Pragma("unroll") for (int n = 0; n < 2; ++n) _Pragma("unroll") for (int k = 0; k < 2; ++k) \
;         acc[ai][bj][m][n] = __builtin_amdgcn_mfma_f32_16x16x32_bf16(Bt[n][k], At[m][k], acc[ai][bj][m][n], 0, 0, 0); __builtin_amdgcn_s_setprio(0); } while (0)
; #define PG8_WAIT_V(n) asm volatile("s_waitcnt vmcnt(" #n ")" ::: "memory")
; #define PG8_WAIT_L(n) asm volatile("s_waitcnt lgkmcnt(" #n ")" ::: "memory")
; #define PG8_BAR __builtin_amdgcn_s_barrier()
; #define PG8_SCHED __builtin_amdgcn_sched_barrier(0)
; template <class Epi, class Sched, bool ALIGN_EPI = false, bool SP2 = false>
; __device__ __forceinline__ void gemm_phase(PG8_LAS unsigned char* lds, const Gemm g, const Sched& S, const Epi& E) {
;     ...
;             PG8_WAIT_V(8); PG8_WAIT_L(0); PG8_BAR; PG8_MMA(1, 0, At, B0); PG8_MMA(1, 1, At, B1); PG8_BAR; PG8_SCHED;
;             PG8_LDB(B0, 1, 0); PG8_LDB(B1, 1, 1); PG8_SCHED; PG8_LDA(At, 1, 0); PG8_STAGE(PG8_SA(0, 1), a2 + hstepA, voffA);
;             PG8_WAIT_V(8); PG8_WAIT_L(0); PG8_BAR; PG8_MMA(0, 0, At, B0); PG8_MMA(0, 1, At, B1); PG8_BAR; PG8_SCHED;
	s_waitcnt lgkmcnt(0)
	v_mfma_f32_16x16x32_bf16 v[62:65], v[130:133], v[184:187], v[62:65]
	v_mfma_f32_16x16x32_bf16 v[58:61], v[138:141], v[184:187], v[58:61]
	v_mfma_f32_16x16x32_bf16 v[46:49], v[130:133], v[192:195], v[46:49]
	v_mfma_f32_16x16x32_bf16 v[42:45], v[138:141], v[192:195], v[42:45]
	v_mfma_f32_16x16x32_bf16 v[30:33], v[130:133], v[200:203], v[30:33]
	v_mfma_f32_16x16x32_bf16 v[26:29], v[138:141], v[200:203], v[26:29]
	v_mfma_f32_16x16x32_bf16 v[14:17], v[130:133], v[208:211], v[14:17]
	v_mfma_f32_16x16x32_bf16 v[10:13], v[138:141], v[208:211], v[10:13]
	v_mfma_f32_16x16x32_bf16 v[62:65], v[134:137], v[188:191], v[62:65]
	v_mfma_f32_16x16x32_bf16 v[58:61], v[142:145], v[188:191], v[58:61]
	v_mfma_f32_16x16x32_bf16 v[46:49], v[134:137], v[196:199], v[46:49]
	v_mfma_f32_16x16x32_bf16 v[42:45], v[142:145], v[196:199], v[42:45]
	v_mfma_f32_16x16x32_bf16 v[30:33], v[134:137], v[204:207], v[30:33]
	v_mfma_f32_16x16x32_bf16 v[26:29], v[142:145], v[204:207], v[26:29]
	v_mfma_f32_16x16x32_bf16 v[14:17], v[134:137], v[212:215], v[14:17]
	v_mfma_f32_16x16x32_bf16 v[10:13], v[142:145], v[212:215], v[10:13]
	v_mfma_f32_16x16x32_bf16 v[54:57], v[162:165], v[184:187], v[54:57]
	v_mfma_f32_16x16x32_bf16 v[50:53], v[176:179], v[184:187], v[50:53]
	v_mfma_f32_16x16x32_bf16 v[38:41], v[162:165], v[192:195], v[38:41]
	v_mfma_f32_16x16x32_bf16 v[34:37], v[176:179], v[192:195], v[34:37]
	v_mfma_f32_16x16x32_bf16 v[22:25], v[162:165], v[200:203], v[22:25]
	v_mfma_f32_16x16x32_bf16 v[18:21], v[176:179], v[200:203], v[18:21]
	v_mfma_f32_16x16x32_bf16 v[6:9], v[162:165], v[208:211], v[6:9]
	v_mfma_f32_16x16x32_bf16 v[2:5], v[176:179], v[208:211], v[2:5]
	v_mfma_f32_16x16x32_bf16 v[54:57], v[166:169], v[188:191], v[54:57]
	v_mfma_f32_16x16x32_bf16 v[50:53], v[180:183], v[188:191], v[50:53]
	v_mfma_f32_16x16x32_bf16 v[38:41], v[166:169], v[196:199], v[38:41]
	v_mfma_f32_16x16x32_bf16 v[34:37], v[180:183], v[196:199], v[34:37]
	v_mfma_f32_16x16x32_bf16 v[22:25], v[166:169], v[204:207], v[22:25]
	v_mfma_f32_16x16x32_bf16 v[18:21], v[180:183], v[204:207], v[18:21]
	v_mfma_f32_16x16x32_bf16 v[6:9], v[166:169], v[212:215], v[6:9]
	v_mfma_f32_16x16x32_bf16 v[2:5], v[180:183], v[212:215], v[2:5]
	s_barrier
	s_add_i32 s57, 0, 0x18000
	s_add_i32 s58, 0, 0x1c000
	v_add_u32_e32 v142, s57, v170
	v_add_u32_e32 v180, s58, v170
	ds_read_b128 v[130:133], v142
	ds_read_b128 v[134:137], v142 offset:1024
	ds_read_b128 v[138:141], v142 offset:2048
	ds_read_b128 v[142:145], v142 offset:3072
	ds_read_b128 v[162:165], v180
	ds_read_b128 v[166:169], v180 offset:1024
	ds_read_b128 v[176:179], v180 offset:2048
	ds_read_b128 v[180:183], v180 offset:3072
	s_add_u32 s38, s38, 0x40000
	s_addc_u32 s39, s39, 0
	s_mov_b32 m0, s42
	v_lshl_add_u64 v[224:225], s[38:39], 0, v[146:147]
	ds_read_b128 v[184:187], v174 offset:32768
	ds_read_b128 v[188:191], v174 offset:33792
	ds_read_b128 v[192:195], v174 offset:34816
	ds_read_b128 v[196:199], v174 offset:35840
	ds_read_b128 v[200:203], v174 offset:36864
	ds_read_b128 v[204:207], v174 offset:37888
	ds_read_b128 v[208:211], v174 offset:38912
	ds_read_b128 v[212:215], v174 offset:39936
	global_load_lds_dwordx4 v[224:225], off
	v_lshl_add_u64 v[224:225], s[38:39], 0, v[150:151]
	s_mov_b32 m0, s43
	s_nop 0
	global_load_lds_dwordx4 v[224:225], off
	s_waitcnt vmcnt(8)
	s_waitcnt lgkmcnt(0)
	s_barrier
	s_waitcnt lgkmcnt(0)
	v_mfma_f32_16x16x32_bf16 v[126:129], v[130:133], v[184:187], v[126:129]
	v_mfma_f32_16x16x32_bf16 v[122:125], v[138:141], v[184:187], v[122:125]
	v_mfma_f32_16x16x32_bf16 v[110:113], v[130:133], v[192:195], v[110:113]
	v_mfma_f32_16x16x32_bf16 v[106:109], v[138:141], v[192:195], v[106:109]
	v_mfma_f32_16x16x32_bf16 v[94:97], v[130:133], v[200:203], v[94:97]
	v_mfma_f32_16x16x32_bf16 v[90:93], v[138:141], v[200:203], v[90:93]
	v_mfma_f32_16x16x32_bf16 v[78:81], v[130:133], v[208:211], v[78:81]
	v_mfma_f32_16x16x32_bf16 v[74:77], v[138:141], v[208:211], v[74:77]
	v_mfma_f32_16x16x32_bf16 v[126:129], v[134:137], v[188:191], v[126:129]
	v_mfma_f32_16x16x32_bf16 v[122:125], v[142:145], v[188:191], v[122:125]
	v_mfma_f32_16x16x32_bf16 v[110:113], v[134:137], v[196:199], v[110:113]
	v_mfma_f32_16x16x32_bf16 v[106:109], v[142:145], v[196:199], v[106:109]
	v_mfma_f32_16x16x32_bf16 v[94:97], v[134:137], v[204:207], v[94:97]
	v_mfma_f32_16x16x32_bf16 v[90:93], v[142:145], v[204:207], v[90:93]
	v_mfma_f32_16x16x32_bf16 v[78:81], v[134:137], v[212:215], v[78:81]
	v_mfma_f32_16x16x32_bf16 v[74:77], v[142:145], v[212:215], v[74:77]
	v_mfma_f32_16x16x32_bf16 v[118:121], v[162:165], v[184:187], v[118:121]
	v_mfma_f32_16x16x32_bf16 v[114:117], v[176:179], v[184:187], v[114:117]
	v_mfma_f32_16x16x32_bf16 v[102:105], v[162:165], v[192:195], v[102:105]
	v_mfma_f32_16x16x32_bf16 v[98:101], v[176:179], v[192:195], v[98:101]
	v_mfma_f32_16x16x32_bf16 v[86:89], v[162:165], v[200:203], v[86:89]
	v_mfma_f32_16x16x32_bf16 v[82:85], v[176:179], v[200:203], v[82:85]
	v_mfma_f32_16x16x32_bf16 v[70:73], v[162:165], v[208:211], v[70:73]
	v_mfma_f32_16x16x32_bf16 v[66:69], v[176:179], v[208:211], v[66:69]
	v_mfma_f32_16x16x32_bf16 v[118:121], v[166:169], v[188:191], v[118:121]
	v_mfma_f32_16x16x32_bf16 v[114:117], v[180:183], v[188:191], v[114:117]
	v_mfma_f32_16x16x32_bf16 v[102:105], v[166:169], v[196:199], v[102:105]
	v_mfma_f32_16x16x32_bf16 v[98:101], v[180:183], v[196:199], v[98:101]
	v_mfma_f32_16x16x32_bf16 v[86:89], v[166:169], v[204:207], v[86:89]
	v_mfma_f32_16x16x32_bf16 v[82:85], v[180:183], v[204:207], v[82:85]
	v_mfma_f32_16x16x32_bf16 v[70:73], v[166:169], v[212:215], v[70:73]
	v_mfma_f32_16x16x32_bf16 v[66:69], v[180:183], v[212:215], v[66:69]
	s_barrier
; #define PG8_STAGE(bufoff, gbase, voff) do { _Pragma("unroll") for (int _i = 0; _i < 2; ++_i) \
;         __builtin_amdgcn_global_load_lds((const unsigned*)((const char*)(gbase) + (voff)[_i]), (PG8_LAS unsigned*)(lds + (bufoff) + ldsw + _i * 8192), 16, 0, 0); } while (0)
; #define PG8_LDA(dst, b, h) do { _Pragma("unroll") for (int m = 0; m < 4; ++m) _Pragma("unroll") for (int k = 0; k < 2; ++k) dst[m][k] = *(const PG8_LAS bf16x8*)(lds + PG8_SA(b, h) + aoff + m * 2048 + k * 1024); } while (0)
; #define PG8_WAIT_V(n) asm volatile("s_waitcnt vmcnt(" #n ")" ::: "memory")
; template <class Epi, class Sched, bool ALIGN_EPI = false, bool SP2 = false>
; __device__ __forceinline__ void gemm_phase(PG8_LAS unsigned char* lds, const Gemm g, const Sched& S, const Epi& E) {
;     ...
;             PG8_LDA(At, 1, 1); PG8_STAGE(PG8_SB(1, 0), b3, voffB); PG8_STAGE(PG8_SB(1, 1), b3 + hstepB, voffB); PG8_STAGE(PG8_SA(1, 0), a3, voffA);
;             PG8_WAIT_V(8); PG8_WAIT_L(0); PG8_BAR; PG8_MMA(1, 0, At, B0); PG8_MMA(1, 1, At, B1); PG8_BAR; PG8_SCHED;
;             } else {
;             PG8_LDB(B0, 0, 0); PG8_SCHED; PG8_LDA(At, 0, 0); PG8_STAGE(PG8_SA(1, 1), a1 + hstepA, voffA);
;             PG8_WAIT_L(8); PG8_BAR; PG8_WAIT_L(0); PG8_MMA(0, 0, At, B0); PG8_BAR; PG8_SCHED;
;             PG8_LDB(B1, 0, 1); PG8_STAGE(PG8_SB(0, 0), b2, voffB);
;             PG8_BAR; PG8_WAIT_L(0); PG8_MMA(0, 1, At, B1); PG8_BAR;
;             PG8_LDA(At, 0, 1); PG8_STAGE(PG8_SA(0, 0), a2, voffA);
;             PG8_BAR; PG8_WAIT_L(0); PG8_MMA(1, 0, At, B0); PG8_BAR; PG8_SCHED;
;             PG8_STAGE(PG8_SB(0, 1), b2 + hstepB, voffB);
;             PG8_WAIT_V(6); PG8_BAR; PG8_MMA(1, 1, At, B1); PG8_BAR;
;             PG8_LDB(B0, 1, 0); PG8_SCHED; PG8_LDA(At, 1, 0); PG8_STAGE(PG8_SA(0, 1), a2 + hstepA, voffA);
;             PG8_WAIT_L(8); PG8_BAR; PG8_WAIT_L(0); PG8_MMA(0, 0, At, B0); PG8_BAR; PG8_SCHED;
;             PG8_LDB(B1, 1, 1); PG8_STAGE(PG8_SB(1, 0), b3, voffB);
;             PG8_BAR; PG8_WAIT_L(0); PG8_MMA(0, 1, At, B1); PG8_BAR;
;             PG8_LDA(At, 1, 1); PG8_STAGE(PG8_SA(1, 0), a3, voffA);
;             PG8_BAR; PG8_WAIT_L(0); PG8_MMA(1, 0, At, B0); PG8_BAR; PG8_SCHED;
;             PG8_STAGE(PG8_SB(1, 1), b3 + hstepB, voffB);
;             PG8_WAIT_V(6); PG8_BAR; PG8_MMA(1, 1, At, B1); PG8_BAR;
;             }
;         }
;         if constexpr (ALIGN_EPI) { if (wr == 0) PG8_BAR; }
	s_add_i32 s38, s57, s33
	v_lshl_add_u64 v[216:217], v[216:217], 0, s[18:19]
	s_mov_b32 m0, s38
	ds_read_b128 v[184:187], v174 offset:49152
	ds_read_b128 v[188:191], v174 offset:50176
	ds_read_b128 v[192:195], v174 offset:51200
	ds_read_b128 v[196:199], v174 offset:52224
	ds_read_b128 v[200:203], v174 offset:53248
	ds_read_b128 v[204:207], v174 offset:54272
	ds_read_b128 v[208:211], v174 offset:55296
	ds_read_b128 v[212:215], v174 offset:56320
	global_load_lds_dwordx4 v[216:217], off
	s_add_i32 m0, s38, 0x2000
	s_add_u32 s36, s36, 0x40080
	v_lshl_add_u64 v[216:217], v[218:219], 0, s[18:19]
	s_addc_u32 s37, s37, 0
	s_add_i32 s38, s58, s33
	global_load_lds_dwordx4 v[216:217], off
	v_lshl_add_u64 v[216:217], s[36:37], 0, v[148:149]
	s_mov_b32 m0, s38
	s_nop 0
	global_load_lds_dwordx4 v[216:217], off
	v_lshl_add_u64 v[216:217], s[36:37], 0, v[152:153]
	s_add_i32 m0, s38, 0x2000
	s_nop 0
	global_load_lds_dwordx4 v[216:217], off
	v_lshl_add_u64 v[216:217], v[220:221], 0, s[18:19]
	s_mov_b32 m0, s45
	s_nop 0
	global_load_lds_dwordx4 v[216:217], off
	v_lshl_add_u64 v[216:217], v[222:223], 0, s[18:19]
	s_mov_b32 m0, s46
	s_nop 0
	global_load_lds_dwordx4 v[216:217], off
	s_waitcnt vmcnt(8)
	s_waitcnt lgkmcnt(0)
	s_barrier
	s_waitcnt lgkmcnt(0)
	v_mfma_f32_16x16x32_bf16 v[62:65], v[130:133], v[184:187], v[62:65]
	v_mfma_f32_16x16x32_bf16 v[58:61], v[138:141], v[184:187], v[58:61]
	v_mfma_f32_16x16x32_bf16 v[46:49], v[130:133], v[192:195], v[46:49]
	v_mfma_f32_16x16x32_bf16 v[42:45], v[138:141], v[192:195], v[42:45]
	v_mfma_f32_16x16x32_bf16 v[30:33], v[130:133], v[200:203], v[30:33]
	v_mfma_f32_16x16x32_bf16 v[26:29], v[138:141], v[200:203], v[26:29]
	v_mfma_f32_16x16x32_bf16 v[14:17], v[130:133], v[208:211], v[14:17]
	v_mfma_f32_16x16x32_bf16 v[10:13], v[138:141], v[208:211], v[10:13]
	v_mfma_f32_16x16x32_bf16 v[62:65], v[134:137], v[188:191], v[62:65]
	v_mfma_f32_16x16x32_bf16 v[58:61], v[142:145], v[188:191], v[58:61]
	v_mfma_f32_16x16x32_bf16 v[46:49], v[134:137], v[196:199], v[46:49]
	v_mfma_f32_16x16x32_bf16 v[42:45], v[142:145], v[196:199], v[42:45]
	v_mfma_f32_16x16x32_bf16 v[30:33], v[134:137], v[204:207], v[30:33]
	v_mfma_f32_16x16x32_bf16 v[26:29], v[142:145], v[204:207], v[26:29]
	v_mfma_f32_16x16x32_bf16 v[14:17], v[134:137], v[212:215], v[14:17]
	v_mfma_f32_16x16x32_bf16 v[10:13], v[142:145], v[212:215], v[10:13]
	v_mfma_f32_16x16x32_bf16 v[54:57], v[162:165], v[184:187], v[54:57]
	v_mfma_f32_16x16x32_bf16 v[50:53], v[176:179], v[184:187], v[50:53]
	v_mfma_f32_16x16x32_bf16 v[38:41], v[162:165], v[192:195], v[38:41]
	v_mfma_f32_16x16x32_bf16 v[34:37], v[176:179], v[192:195], v[34:37]
	v_mfma_f32_16x16x32_bf16 v[22:25], v[162:165], v[200:203], v[22:25]
	v_mfma_f32_16x16x32_bf16 v[18:21], v[176:179], v[200:203], v[18:21]
	v_mfma_f32_16x16x32_bf16 v[6:9], v[162:165], v[208:211], v[6:9]
	v_mfma_f32_16x16x32_bf16 v[2:5], v[176:179], v[208:211], v[2:5]
	v_mfma_f32_16x16x32_bf16 v[54:57], v[166:169], v[188:191], v[54:57]
	v_mfma_f32_16x16x32_bf16 v[50:53], v[180:183], v[188:191], v[50:53]
	v_mfma_f32_16x16x32_bf16 v[38:41], v[166:169], v[196:199], v[38:41]
	v_mfma_f32_16x16x32_bf16 v[34:37], v[180:183], v[196:199], v[34:37]
	v_mfma_f32_16x16x32_bf16 v[22:25], v[166:169], v[204:207], v[22:25]
	v_mfma_f32_16x16x32_bf16 v[18:21], v[180:183], v[204:207], v[18:21]
	v_mfma_f32_16x16x32_bf16 v[6:9], v[166:169], v[212:215], v[6:9]
	v_mfma_f32_16x16x32_bf16 v[2:5], v[180:183], v[212:215], v[2:5]
	s_barrier
	s_add_i32 s56, s56, 2
	s_add_u32 s34, s34, 0x100
	s_addc_u32 s35, s35, 0
	s_add_u32 s54, s54, 0x100
	s_addc_u32 s55, s55, 0
	s_cmp_gt_u32 s56, 13
	s_cbranch_scc0 .LBB0_605
	s_and_b64 vcc, exec, s[20:21]
	s_cbranch_vccz .LBB0_608
	s_barrier

; #define PG8_STAGE(bufoff, gbase, voff) do { _Pragma("unroll") for (int _i = 0; _i < 2; ++_i) \
;         __builtin_amdgcn_global_load_lds((const unsigned*)((const char*)(gbase) + (voff)[_i]), (PG8_LAS unsigned*)(lds + (bufoff) + ldsw + _i * 8192), 16, 0, 0); } while (0)
; #define PG8_LDA(dst, b, h) do { _Pragma("unroll") for (int m = 0; m < 4; ++m) _Pragma("unroll") for (int k = 0; k < 2; ++k) dst[m][k] = *(const PG8_LAS bf16x8*)(lds + PG8_SA(b, h) + aoff + m * 2048 + k * 1024); } while (0)
; #define PG8_LDB(dst, b, h) do { _Pragma("unroll") for (int n = 0; n < 2; ++n) _Pragma("unroll") for (int k = 0; k < 2; ++k) dst[n][k] = *(const PG8_LAS bf16x8*)(lds + PG8_SB(b, h) + boff + n * 2048 + k * 1024); } while (0)
; #define PG8_MMA(ai, bj, At, Bt) do { __builtin_amdgcn_s_setprio(1); _Pragma("unroll") for (int m = 0; m < 4; ++m) _Pragma("unroll") for (int n = 0; n < 2; ++n) _Pragma("unroll") for (int k = 0; k < 2; ++k) \
;         acc[ai][bj][m][n] = __builtin_amdgcn_mfma_f32_16x16x32_bf16(Bt[n][k], At[m][k], acc[ai][bj][m][n], 0, 0, 0); __builtin_amdgcn_s_setprio(0); } while (0)
; #define PG8_WAIT_V(n) asm volatile("s_waitcnt vmcnt(" #n ")" ::: "memory")
; #define PG8_WAIT_L(n) asm volatile("s_waitcnt lgkmcnt(" #n ")" ::: "memory")
; #define PG8_BAR __builtin_amdgcn_s_barrier()
; #define PG8_SCHED __builtin_amdgcn_sched_barrier(0)
; template <class Epi, class Sched, bool ALIGN_EPI = false, bool SP2 = false>
; __device__ __forceinline__ void gemm_phase(PG8_LAS unsigned char* lds, const Gemm g, const Sched& S, const Epi& E) {
;     ...
;             PG8_LDB(B0, 0, 0); PG8_LDB(B1, 0, 1); PG8_SCHED; PG8_LDA(At, 0, 0); PG8_STAGE(PG8_SA(1, 1), a1 + hstepA, voffA);
;             PG8_WAIT_V(8); PG8_WAIT_L(0); PG8_BAR; PG8_MMA(0, 0, At, B0); PG8_MMA(0, 1, At, B1); PG8_BAR; PG8_SCHED;
;             PG8_LDA(At, 0, 1); PG8_STAGE(PG8_SB(0, 0), b2, voffB); PG8_STAGE(PG8_SB(0, 1), b2 + hstepB, voffB); PG8_STAGE(PG8_SA(0, 0), a2, voffA);
.LBB0_691:
	ds_read_b128 v[148:151], v168
	ds_read_b128 v[152:155], v168 offset:1024
	ds_read_b128 v[156:159], v168 offset:2048
	ds_read_b128 v[160:163], v168 offset:3072
	ds_read_b128 v[174:177], v169
	ds_read_b128 v[178:181], v169 offset:1024
	ds_read_b128 v[182:185], v169 offset:2048
	ds_read_b128 v[186:189], v169 offset:3072
	s_add_u32 s26, s24, 0xfffc0080
	s_addc_u32 s27, s25, -1
	s_cmp_eq_u32 s50, 12
	s_cselect_b32 s29, s17, s27
	s_cselect_b32 s28, s46, s26
	s_cselect_b32 s27, s15, s49
	s_cselect_b32 s26, s47, s48
	v_lshl_add_u64 v[164:165], s[24:25], 0, v[140:141]
	s_add_i32 m0, s23, 0xc000
	ds_read_b128 v[190:193], v170
	ds_read_b128 v[194:197], v170 offset:1024
	ds_read_b128 v[198:201], v170 offset:2048
	ds_read_b128 v[202:205], v170 offset:3072
	ds_read_b128 v[206:209], v170 offset:4096
	ds_read_b128 v[210:213], v170 offset:5120
	ds_read_b128 v[214:217], v170 offset:6144
	ds_read_b128 v[218:221], v170 offset:7168
	global_load_lds_dwordx4 v[164:165], off
	v_lshl_add_u64 v[164:165], s[24:25], 0, v[142:143]
	s_add_i32 m0, s23, 0xe000
	s_nop 0
	global_load_lds_dwordx4 v[164:165], off
	s_waitcnt vmcnt(8)
	s_waitcnt lgkmcnt(0)
	s_barrier
	s_waitcnt lgkmcnt(0)
	v_mfma_f32_16x16x32_bf16 v[126:129], v[148:151], v[190:193], v[126:129]
	v_mfma_f32_16x16x32_bf16 v[118:121], v[156:159], v[190:193], v[118:121]
	v_mfma_f32_16x16x32_bf16 v[110:113], v[148:151], v[198:201], v[110:113]
	v_mfma_f32_16x16x32_bf16 v[102:105], v[156:159], v[198:201], v[102:105]
	v_mfma_f32_16x16x32_bf16 v[94:97], v[148:151], v[206:209], v[94:97]
	v_mfma_f32_16x16x32_bf16 v[86:89], v[156:159], v[206:209], v[86:89]
	v_mfma_f32_16x16x32_bf16 v[78:81], v[148:151], v[214:217], v[78:81]
	v_mfma_f32_16x16x32_bf16 v[70:73], v[156:159], v[214:217], v[70:73]
	v_mfma_f32_16x16x32_bf16 v[126:129], v[152:155], v[194:197], v[126:129]
	v_mfma_f32_16x16x32_bf16 v[118:121], v[160:163], v[194:197], v[118:121]
	v_mfma_f32_16x16x32_bf16 v[110:113], v[152:155], v[202:205], v[110:113]
	v_mfma_f32_16x16x32_bf16 v[102:105], v[160:163], v[202:205], v[102:105]
	v_mfma_f32_16x16x32_bf16 v[94:97], v[152:155], v[210:213], v[94:97]
	v_mfma_f32_16x16x32_bf16 v[86:89], v[160:163], v[210:213], v[86:89]
	v_mfma_f32_16x16x32_bf16 v[78:81], v[152:155], v[218:221], v[78:81]
	v_mfma_f32_16x16x32_bf16 v[70:73], v[160:163], v[218:221], v[70:73]
	v_mfma_f32_16x16x32_bf16 v[122:125], v[174:177], v[190:193], v[122:125]
	v_mfma_f32_16x16x32_bf16 v[114:117], v[182:185], v[190:193], v[114:117]
	v_mfma_f32_16x16x32_bf16 v[106:109], v[174:177], v[198:201], v[106:109]
	v_mfma_f32_16x16x32_bf16 v[98:101], v[182:185], v[198:201], v[98:101]
	v_mfma_f32_16x16x32_bf16 v[90:93], v[174:177], v[206:209], v[90:93]
	v_mfma_f32_16x16x32_bf16 v[82:85], v[182:185], v[206:209], v[82:85]
	v_mfma_f32_16x16x32_bf16 v[74:77], v[174:177], v[214:217], v[74:77]
	v_mfma_f32_16x16x32_bf16 v[66:69], v[182:185], v[214:217], v[66:69]
	v_mfma_f32_16x16x32_bf16 v[122:125], v[178:181], v[194:197], v[122:125]
	v_mfma_f32_16x16x32_bf16 v[114:117], v[186:189], v[194:197], v[114:117]
	v_mfma_f32_16x16x32_bf16 v[106:109], v[178:181], v[202:205], v[106:109]
	v_mfma_f32_16x16x32_bf16 v[98:101], v[186:189], v[202:205], v[98:101]
	v_mfma_f32_16x16x32_bf16 v[90:93], v[178:181], v[210:213], v[90:93]
	v_mfma_f32_16x16x32_bf16 v[82:85], v[186:189], v[210:213], v[82:85]
	v_mfma_f32_16x16x32_bf16 v[74:77], v[178:181], v[218:221], v[74:77]
	v_mfma_f32_16x16x32_bf16 v[66:69], v[186:189], v[218:221], v[66:69]
	s_barrier
	s_add_i32 s51, s42, s30
	v_lshl_add_u64 v[164:165], s[26:27], 0, v[134:135]
	s_mov_b32 m0, s51
	ds_read_b128 v[190:193], v170 offset:16384
	ds_read_b128 v[194:197], v170 offset:17408
	ds_read_b128 v[198:201], v170 offset:18432
	ds_read_b128 v[202:205], v170 offset:19456
	ds_read_b128 v[206:209], v170 offset:20480
	ds_read_b128 v[210:213], v170 offset:21504
	ds_read_b128 v[214:217], v170 offset:22528
	ds_read_b128 v[218:221], v170 offset:23552
	global_load_lds_dwordx4 v[164:165], off
	s_add_i32 m0, s51, 0x2000
	s_add_u32 s52, s26, 0x40000
	v_lshl_add_u64 v[222:223], s[26:27], 0, v[130:131]
	s_addc_u32 s53, s27, 0
	s_add_i32 s51, s43, s30
	global_load_lds_dwordx4 v[222:223], off
	v_lshl_add_u64 v[224:225], s[52:53], 0, v[134:135]
	s_mov_b32 m0, s51
	v_lshl_add_u64 v[226:227], s[28:29], 0, v[132:133]
	global_load_lds_dwordx4 v[224:225], off
	v_lshl_add_u64 v[224:225], s[52:53], 0, v[130:131]
	s_add_i32 m0, s51, 0x2000
	s_nop 0
	global_load_lds_dwordx4 v[224:225], off
	v_lshl_add_u64 v[224:225], s[28:29], 0, v[136:137]
	s_mov_b32 m0, s23
	s_nop 0
	global_load_lds_dwordx4 v[224:225], off
	s_mov_b32 m0, s34
	s_nop 0
	global_load_lds_dwordx4 v[226:227], off
	s_waitcnt vmcnt(8)
	s_waitcnt lgkmcnt(0)
	s_barrier
; #define PG8_STAGE(bufoff, gbase, voff) do { _Pragma("unroll") for (int _i = 0; _i < 2; ++_i) \
;         __builtin_amdgcn_global_load_lds((const unsigned*)((const char*)(gbase) + (voff)[_i]), (PG8_LAS unsigned*)(lds + (bufoff) + ldsw + _i * 8192), 16, 0, 0); } while (0)
; #define PG8_LDA(dst, b, h) do { _Pragma("unroll") for (int m = 0; m < 4; ++m) _Pragma("unroll") for (int k = 0; k < 2; ++k) dst[m][k] = *(const PG8_LAS bf16x8*)(lds + PG8_SA(b, h) + aoff + m * 2048 + k * 1024); } while (0)
; #define PG8_LDB(dst, b, h) do { _Pragma("unroll") for (int n = 0; n < 2; ++n) _Pragma("unroll") for (int k = 0; k < 2; ++k) dst[n][k] = *(const PG8_LAS bf16x8*)(lds + PG8_SB(b, h) + boff + n * 2048 + k * 1024); } while (0)
; #define PG8_MMA(ai, bj, At, Bt) do { __builtin_amdgcn_s_setprio(1); _Pragma("unroll") for (int m = 0; m < 4; ++m) _Pragma("unroll") for (int n = 0; n < 2; ++n) _Pragma("unroll") for (int k = 0; k < 2; ++k) \
;         acc[ai][bj][m][n] = __builtin_amdgcn_mfma_f32_16x16x32_bf16(Bt[n][k], At[m][k], acc[ai][bj][m][n], 0, 0, 0); __builtin_amdgcn_s_setprio(0); } while (0)
; #define PG8_WAIT_V(n) asm volatile("s_waitcnt vmcnt(" #n ")" ::: "memory")
; #define PG8_WAIT_L(n) asm volatile("s_waitcnt lgkmcnt(" #n ")" ::: "memory")
; #define PG8_BAR __builtin_amdgcn_s_barrier()
; #define PG8_SCHED __builtin_amdgcn_sched_barrier(0)
; template <class Epi, class Sched, bool ALIGN_EPI = false, bool SP2 = false>
; __device__ __forceinline__ void gemm_phase(PG8_LAS unsigned char* lds, const Gemm g, const Sched& S, const Epi& E) {
;     ...
;             PG8_WAIT_V(8); PG8_WAIT_L(0); PG8_BAR; PG8_MMA(1, 0, At, B0); PG8_MMA(1, 1, At, B1); PG8_BAR; PG8_SCHED;
;             PG8_LDB(B0, 1, 0); PG8_LDB(B1, 1, 1); PG8_SCHED; PG8_LDA(At, 1, 0); PG8_STAGE(PG8_SA(0, 1), a2 + hstepA, voffA);
;             PG8_WAIT_V(8); PG8_WAIT_L(0); PG8_BAR; PG8_MMA(0, 0, At, B0); PG8_MMA(0, 1, At, B1); PG8_BAR; PG8_SCHED;
	s_waitcnt lgkmcnt(0)
	v_mfma_f32_16x16x32_bf16 v[62:65], v[148:151], v[190:193], v[62:65]
	v_mfma_f32_16x16x32_bf16 v[54:57], v[156:159], v[190:193], v[54:57]
	v_mfma_f32_16x16x32_bf16 v[46:49], v[148:151], v[198:201], v[46:49]
	v_mfma_f32_16x16x32_bf16 v[38:41], v[156:159], v[198:201], v[38:41]
	v_mfma_f32_16x16x32_bf16 v[30:33], v[148:151], v[206:209], v[30:33]
	v_mfma_f32_16x16x32_bf16 v[22:25], v[156:159], v[206:209], v[22:25]
	v_mfma_f32_16x16x32_bf16 v[14:17], v[148:151], v[214:217], v[14:17]
	v_mfma_f32_16x16x32_bf16 v[6:9], v[156:159], v[214:217], v[6:9]
	v_mfma_f32_16x16x32_bf16 v[62:65], v[152:155], v[194:197], v[62:65]
	v_mfma_f32_16x16x32_bf16 v[54:57], v[160:163], v[194:197], v[54:57]
	v_mfma_f32_16x16x32_bf16 v[46:49], v[152:155], v[202:205], v[46:49]
	v_mfma_f32_16x16x32_bf16 v[38:41], v[160:163], v[202:205], v[38:41]
	v_mfma_f32_16x16x32_bf16 v[30:33], v[152:155], v[210:213], v[30:33]
	v_mfma_f32_16x16x32_bf16 v[22:25], v[160:163], v[210:213], v[22:25]
	v_mfma_f32_16x16x32_bf16 v[14:17], v[152:155], v[218:221], v[14:17]
	v_mfma_f32_16x16x32_bf16 v[6:9], v[160:163], v[218:221], v[6:9]
	v_mfma_f32_16x16x32_bf16 v[58:61], v[174:177], v[190:193], v[58:61]
	v_mfma_f32_16x16x32_bf16 v[50:53], v[182:185], v[190:193], v[50:53]
	v_mfma_f32_16x16x32_bf16 v[42:45], v[174:177], v[198:201], v[42:45]
	v_mfma_f32_16x16x32_bf16 v[34:37], v[182:185], v[198:201], v[34:37]
	v_mfma_f32_16x16x32_bf16 v[26:29], v[174:177], v[206:209], v[26:29]
	v_mfma_f32_16x16x32_bf16 v[18:21], v[182:185], v[206:209], v[18:21]
	v_mfma_f32_16x16x32_bf16 v[10:13], v[174:177], v[214:217], v[10:13]
	v_mfma_f32_16x16x32_bf16 v[2:5], v[182:185], v[214:217], v[2:5]
	v_mfma_f32_16x16x32_bf16 v[58:61], v[178:181], v[194:197], v[58:61]
	v_mfma_f32_16x16x32_bf16 v[50:53], v[186:189], v[194:197], v[50:53]
	v_mfma_f32_16x16x32_bf16 v[42:45], v[178:181], v[202:205], v[42:45]
	v_mfma_f32_16x16x32_bf16 v[34:37], v[186:189], v[202:205], v[34:37]
	v_mfma_f32_16x16x32_bf16 v[26:29], v[178:181], v[210:213], v[26:29]
	v_mfma_f32_16x16x32_bf16 v[18:21], v[186:189], v[210:213], v[18:21]
	v_mfma_f32_16x16x32_bf16 v[10:13], v[178:181], v[218:221], v[10:13]
	v_mfma_f32_16x16x32_bf16 v[2:5], v[186:189], v[218:221], v[2:5]
	s_barrier
	s_add_i32 s51, 0, 0x18000
	s_add_i32 s52, 0, 0x1c000
	v_add_u32_e32 v160, s51, v166
	v_add_u32_e32 v173, s52, v166
	ds_read_b128 v[148:151], v160
	ds_read_b128 v[152:155], v160 offset:1024
	ds_read_b128 v[156:159], v160 offset:2048
	ds_read_b128 v[160:163], v160 offset:3072
	ds_read_b128 v[174:177], v173
	ds_read_b128 v[178:181], v173 offset:1024
	ds_read_b128 v[182:185], v173 offset:2048
	ds_read_b128 v[186:189], v173 offset:3072
	s_add_u32 s28, s28, 0x40000
	s_addc_u32 s29, s29, 0
	s_mov_b32 m0, s35
	v_lshl_add_u64 v[228:229], s[28:29], 0, v[136:137]
	ds_read_b128 v[190:193], v170 offset:32768
	ds_read_b128 v[194:197], v170 offset:33792
	ds_read_b128 v[198:201], v170 offset:34816
	ds_read_b128 v[202:205], v170 offset:35840
	ds_read_b128 v[206:209], v170 offset:36864
	ds_read_b128 v[210:213], v170 offset:37888
	ds_read_b128 v[214:217], v170 offset:38912
	ds_read_b128 v[218:221], v170 offset:39936
	global_load_lds_dwordx4 v[228:229], off
	v_lshl_add_u64 v[228:229], s[28:29], 0, v[132:133]
	s_mov_b32 m0, s36
	s_nop 0
	global_load_lds_dwordx4 v[228:229], off
	s_waitcnt vmcnt(8)
	s_waitcnt lgkmcnt(0)
	s_barrier
	s_waitcnt lgkmcnt(0)
	v_mfma_f32_16x16x32_bf16 v[126:129], v[148:151], v[190:193], v[126:129]
	v_mfma_f32_16x16x32_bf16 v[118:121], v[156:159], v[190:193], v[118:121]
	v_mfma_f32_16x16x32_bf16 v[110:113], v[148:151], v[198:201], v[110:113]
	v_mfma_f32_16x16x32_bf16 v[102:105], v[156:159], v[198:201], v[102:105]
	v_mfma_f32_16x16x32_bf16 v[94:97], v[148:151], v[206:209], v[94:97]
	v_mfma_f32_16x16x32_bf16 v[86:89], v[156:159], v[206:209], v[86:89]
	v_mfma_f32_16x16x32_bf16 v[78:81], v[148:151], v[214:217], v[78:81]
	v_mfma_f32_16x16x32_bf16 v[70:73], v[156:159], v[214:217], v[70:73]
	v_mfma_f32_16x16x32_bf16 v[126:129], v[152:155], v[194:197], v[126:129]
	v_mfma_f32_16x16x32_bf16 v[118:121], v[160:163], v[194:197], v[118:121]
	v_mfma_f32_16x16x32_bf16 v[110:113], v[152:155], v[202:205], v[110:113]
	v_mfma_f32_16x16x32_bf16 v[102:105], v[160:163], v[202:205], v[102:105]
	v_mfma_f32_16x16x32_bf16 v[94:97], v[152:155], v[210:213], v[94:97]
	v_mfma_f32_16x16x32_bf16 v[86:89], v[160:163], v[210:213], v[86:89]
	v_mfma_f32_16x16x32_bf16 v[78:81], v[152:155], v[218:221], v[78:81]
	v_mfma_f32_16x16x32_bf16 v[70:73], v[160:163], v[218:221], v[70:73]
	v_mfma_f32_16x16x32_bf16 v[122:125], v[174:177], v[190:193], v[122:125]
	v_mfma_f32_16x16x32_bf16 v[114:117], v[182:185], v[190:193], v[114:117]
	v_mfma_f32_16x16x32_bf16 v[106:109], v[174:177], v[198:201], v[106:109]
	v_mfma_f32_16x16x32_bf16 v[98:101], v[182:185], v[198:201], v[98:101]
	v_mfma_f32_16x16x32_bf16 v[90:93], v[174:177], v[206:209], v[90:93]
	v_mfma_f32_16x16x32_bf16 v[82:85], v[182:185], v[206:209], v[82:85]
	v_mfma_f32_16x16x32_bf16 v[74:77], v[174:177], v[214:217], v[74:77]
	v_mfma_f32_16x16x32_bf16 v[66:69], v[182:185], v[214:217], v[66:69]
	v_mfma_f32_16x16x32_bf16 v[122:125], v[178:181], v[194:197], v[122:125]
	v_mfma_f32_16x16x32_bf16 v[114:117], v[186:189], v[194:197], v[114:117]
	v_mfma_f32_16x16x32_bf16 v[106:109], v[178:181], v[202:205], v[106:109]
	v_mfma_f32_16x16x32_bf16 v[98:101], v[186:189], v[202:205], v[98:101]
	v_mfma_f32_16x16x32_bf16 v[90:93], v[178:181], v[210:213], v[90:93]
	v_mfma_f32_16x16x32_bf16 v[82:85], v[186:189], v[210:213], v[82:85]
	v_mfma_f32_16x16x32_bf16 v[74:77], v[178:181], v[218:221], v[74:77]
	v_mfma_f32_16x16x32_bf16 v[66:69], v[186:189], v[218:221], v[66:69]
	s_barrier
; #define PG8_STAGE(bufoff, gbase, voff) do { _Pragma("unroll") for (int _i = 0; _i < 2; ++_i) \
;         __builtin_amdgcn_global_load_lds((const unsigned*)((const char*)(gbase) + (voff)[_i]), (PG8_LAS unsigned*)(lds + (bufoff) + ldsw + _i * 8192), 16, 0, 0); } while (0)
; #define PG8_LDA(dst, b, h) do { _Pragma("unroll") for (int m = 0; m < 4; ++m) _Pragma("unroll") for (int k = 0; k < 2; ++k) dst[m][k] = *(const PG8_LAS bf16x8*)(lds + PG8_SA(b, h) + aoff + m * 2048 + k * 1024); } while (0)
; #define PG8_WAIT_V(n) asm volatile("s_waitcnt vmcnt(" #n ")" ::: "memory")
; template <class Epi, class Sched, bool ALIGN_EPI = false, bool SP2 = false>
; __device__ __forceinline__ void gemm_phase(PG8_LAS unsigned char* lds, const Gemm g, const Sched& S, const Epi& E) {
;     ...
;             PG8_LDA(At, 1, 1); PG8_STAGE(PG8_SB(1, 0), b3, voffB); PG8_STAGE(PG8_SB(1, 1), b3 + hstepB, voffB); PG8_STAGE(PG8_SA(1, 0), a3, voffA);
;             PG8_WAIT_V(8); PG8_WAIT_L(0); PG8_BAR; PG8_MMA(1, 0, At, B0); PG8_MMA(1, 1, At, B1); PG8_BAR; PG8_SCHED;
;             } else {
;             PG8_LDB(B0, 0, 0); PG8_SCHED; PG8_LDA(At, 0, 0); PG8_STAGE(PG8_SA(1, 1), a1 + hstepA, voffA);
;             PG8_WAIT_L(8); PG8_BAR; PG8_WAIT_L(0); PG8_MMA(0, 0, At, B0); PG8_BAR; PG8_SCHED;
;             PG8_LDB(B1, 0, 1); PG8_STAGE(PG8_SB(0, 0), b2, voffB);
;             PG8_BAR; PG8_WAIT_L(0); PG8_MMA(0, 1, At, B1); PG8_BAR;
;             PG8_LDA(At, 0, 1); PG8_STAGE(PG8_SA(0, 0), a2, voffA);
;             PG8_BAR; PG8_WAIT_L(0); PG8_MMA(1, 0, At, B0); PG8_BAR; PG8_SCHED;
;             PG8_STAGE(PG8_SB(0, 1), b2 + hstepB, voffB);
;             PG8_WAIT_V(6); PG8_BAR; PG8_MMA(1, 1, At, B1); PG8_BAR;
;             PG8_LDB(B0, 1, 0); PG8_SCHED; PG8_LDA(At, 1, 0); PG8_STAGE(PG8_SA(0, 1), a2 + hstepA, voffA);
;             PG8_WAIT_L(8); PG8_BAR; PG8_WAIT_L(0); PG8_MMA(0, 0, At, B0); PG8_BAR; PG8_SCHED;
;             PG8_LDB(B1, 1, 1); PG8_STAGE(PG8_SB(1, 0), b3, voffB);
;             PG8_BAR; PG8_WAIT_L(0); PG8_MMA(0, 1, At, B1); PG8_BAR;
;             PG8_LDA(At, 1, 1); PG8_STAGE(PG8_SA(1, 0), a3, voffA);
;             PG8_BAR; PG8_WAIT_L(0); PG8_MMA(1, 0, At, B0); PG8_BAR; PG8_SCHED;
;             PG8_STAGE(PG8_SB(1, 1), b3 + hstepB, voffB);
;             PG8_WAIT_V(6); PG8_BAR; PG8_MMA(1, 1, At, B1); PG8_BAR;
;             }
;         }
;         if constexpr (ALIGN_EPI) { if (wr == 0) PG8_BAR; }
	s_add_i32 s28, s51, s30
	v_lshl_add_u64 v[164:165], v[164:165], 0, s[10:11]
	s_mov_b32 m0, s28
	ds_read_b128 v[190:193], v170 offset:49152
	ds_read_b128 v[194:197], v170 offset:50176
	ds_read_b128 v[198:201], v170 offset:51200
	ds_read_b128 v[202:205], v170 offset:52224
	ds_read_b128 v[206:209], v170 offset:53248
	ds_read_b128 v[210:213], v170 offset:54272
	ds_read_b128 v[214:217], v170 offset:55296
	ds_read_b128 v[218:221], v170 offset:56320
	global_load_lds_dwordx4 v[164:165], off
	s_add_i32 m0, s28, 0x2000
	s_add_u32 s26, s26, 0x40080
	v_lshl_add_u64 v[164:165], v[222:223], 0, s[10:11]
	s_addc_u32 s27, s27, 0
	s_add_i32 s28, s52, s30
	global_load_lds_dwordx4 v[164:165], off
	v_lshl_add_u64 v[164:165], s[26:27], 0, v[134:135]
	s_mov_b32 m0, s28
	s_nop 0
	global_load_lds_dwordx4 v[164:165], off
	v_lshl_add_u64 v[164:165], s[26:27], 0, v[130:131]
	s_add_i32 m0, s28, 0x2000
	s_nop 0
	global_load_lds_dwordx4 v[164:165], off
	v_lshl_add_u64 v[164:165], v[224:225], 0, s[10:11]
	s_mov_b32 m0, s38
	s_nop 0
	global_load_lds_dwordx4 v[164:165], off
	v_lshl_add_u64 v[164:165], v[226:227], 0, s[10:11]
	s_mov_b32 m0, s39
	s_nop 0
	global_load_lds_dwordx4 v[164:165], off
	s_waitcnt vmcnt(8)
	s_waitcnt lgkmcnt(0)
	s_barrier
	s_waitcnt lgkmcnt(0)
	v_mfma_f32_16x16x32_bf16 v[62:65], v[148:151], v[190:193], v[62:65]
	v_mfma_f32_16x16x32_bf16 v[54:57], v[156:159], v[190:193], v[54:57]
	v_mfma_f32_16x16x32_bf16 v[46:49], v[148:151], v[198:201], v[46:49]
	v_mfma_f32_16x16x32_bf16 v[38:41], v[156:159], v[198:201], v[38:41]
	v_mfma_f32_16x16x32_bf16 v[30:33], v[148:151], v[206:209], v[30:33]
	v_mfma_f32_16x16x32_bf16 v[22:25], v[156:159], v[206:209], v[22:25]
	v_mfma_f32_16x16x32_bf16 v[14:17], v[148:151], v[214:217], v[14:17]
	v_mfma_f32_16x16x32_bf16 v[6:9], v[156:159], v[214:217], v[6:9]
	v_mfma_f32_16x16x32_bf16 v[62:65], v[152:155], v[194:197], v[62:65]
	v_mfma_f32_16x16x32_bf16 v[54:57], v[160:163], v[194:197], v[54:57]
	v_mfma_f32_16x16x32_bf16 v[46:49], v[152:155], v[202:205], v[46:49]
	v_mfma_f32_16x16x32_bf16 v[38:41], v[160:163], v[202:205], v[38:41]
	v_mfma_f32_16x16x32_bf16 v[30:33], v[152:155], v[210:213], v[30:33]
	v_mfma_f32_16x16x32_bf16 v[22:25], v[160:163], v[210:213], v[22:25]
	v_mfma_f32_16x16x32_bf16 v[14:17], v[152:155], v[218:221], v[14:17]
	v_mfma_f32_16x16x32_bf16 v[6:9], v[160:163], v[218:221], v[6:9]
	v_mfma_f32_16x16x32_bf16 v[58:61], v[174:177], v[190:193], v[58:61]
	v_mfma_f32_16x16x32_bf16 v[50:53], v[182:185], v[190:193], v[50:53]
	v_mfma_f32_16x16x32_bf16 v[42:45], v[174:177], v[198:201], v[42:45]
	v_mfma_f32_16x16x32_bf16 v[34:37], v[182:185], v[198:201], v[34:37]
	v_mfma_f32_16x16x32_bf16 v[26:29], v[174:177], v[206:209], v[26:29]
	v_mfma_f32_16x16x32_bf16 v[18:21], v[182:185], v[206:209], v[18:21]
	v_mfma_f32_16x16x32_bf16 v[10:13], v[174:177], v[214:217], v[10:13]
	v_mfma_f32_16x16x32_bf16 v[2:5], v[182:185], v[214:217], v[2:5]
	v_mfma_f32_16x16x32_bf16 v[58:61], v[178:181], v[194:197], v[58:61]
	v_mfma_f32_16x16x32_bf16 v[50:53], v[186:189], v[194:197], v[50:53]
	v_mfma_f32_16x16x32_bf16 v[42:45], v[178:181], v[202:205], v[42:45]
	v_mfma_f32_16x16x32_bf16 v[34:37], v[186:189], v[202:205], v[34:37]
	v_mfma_f32_16x16x32_bf16 v[26:29], v[178:181], v[210:213], v[26:29]
	v_mfma_f32_16x16x32_bf16 v[18:21], v[186:189], v[210:213], v[18:21]
	v_mfma_f32_16x16x32_bf16 v[10:13], v[178:181], v[218:221], v[10:13]
	v_mfma_f32_16x16x32_bf16 v[2:5], v[186:189], v[218:221], v[2:5]
	s_barrier
	s_add_i32 s50, s50, 2
	s_add_u32 s24, s24, 0x100
	s_addc_u32 s25, s25, 0
	s_add_u32 s48, s48, 0x100
	s_addc_u32 s49, s49, 0
	s_cmp_gt_u32 s50, 13
	s_cbranch_scc0 .LBB0_691
	s_and_b64 vcc, exec, s[12:13]
	s_cbranch_vccz .LBB0_694
	s_barrier

; #define PG8_STAGE(bufoff, gbase, voff) do { _Pragma("unroll") for (int _i = 0; _i < 2; ++_i) \
;         __builtin_amdgcn_global_load_lds((const unsigned*)((const char*)(gbase) + (voff)[_i]), (PG8_LAS unsigned*)(lds + (bufoff) + ldsw + _i * 8192), 16, 0, 0); } while (0)
; #define PG8_LDA(dst, b, h) do { _Pragma("unroll") for (int m = 0; m < 4; ++m) _Pragma("unroll") for (int k = 0; k < 2; ++k) dst[m][k] = *(const PG8_LAS bf16x8*)(lds + PG8_SA(b, h) + aoff + m * 2048 + k * 1024); } while (0)
; #define PG8_LDB(dst, b, h) do { _Pragma("unroll") for (int n = 0; n < 2; ++n) _Pragma("unroll") for (int k = 0; k < 2; ++k) dst[n][k] = *(const PG8_LAS bf16x8*)(lds + PG8_SB(b, h) + boff + n * 2048 + k * 1024); } while (0)
; #define PG8_MMA(ai, bj, At, Bt) do { __builtin_amdgcn_s_setprio(1); _Pragma("unroll") for (int m = 0; m < 4; ++m) _Pragma("unroll") for (int n = 0; n < 2; ++n) _Pragma("unroll") for (int k = 0; k < 2; ++k) \
;         acc[ai][bj][m][n] = __builtin_amdgcn_mfma_f32_16x16x32_bf16(Bt[n][k], At[m][k], acc[ai][bj][m][n], 0, 0, 0); __builtin_amdgcn_s_setprio(0); } while (0)
; #define PG8_WAIT_V(n) asm volatile("s_waitcnt vmcnt(" #n ")" ::: "memory")
; #define PG8_WAIT_L(n) asm volatile("s_waitcnt lgkmcnt(" #n ")" ::: "memory")
; #define PG8_BAR __builtin_amdgcn_s_barrier()
; #define PG8_SCHED __builtin_amdgcn_sched_barrier(0)
; template <class Epi, class Sched, bool ALIGN_EPI = false, bool SP2 = false>
; __device__ __forceinline__ void gemm_phase(PG8_LAS unsigned char* lds, const Gemm g, const Sched& S, const Epi& E) {
;     ...
;             PG8_LDB(B0, 0, 0); PG8_LDB(B1, 0, 1); PG8_SCHED; PG8_LDA(At, 0, 0); PG8_STAGE(PG8_SA(1, 1), a1 + hstepA, voffA);
;             PG8_WAIT_V(8); PG8_WAIT_L(0); PG8_BAR; PG8_MMA(0, 0, At, B0); PG8_MMA(0, 1, At, B1); PG8_BAR; PG8_SCHED;
;             PG8_LDA(At, 0, 1); PG8_STAGE(PG8_SB(0, 0), b2, voffB); PG8_STAGE(PG8_SB(0, 1), b2 + hstepB, voffB); PG8_STAGE(PG8_SA(0, 0), a2, voffA);
.LBB0_776:
	ds_read_b128 v[130:133], v164
	ds_read_b128 v[134:137], v164 offset:1024
	ds_read_b128 v[154:157], v164 offset:2048
	ds_read_b128 v[158:161], v164 offset:3072
	ds_read_b128 v[168:171], v165
	ds_read_b128 v[172:175], v165 offset:1024
	ds_read_b128 v[176:179], v165 offset:2048
	ds_read_b128 v[180:183], v165 offset:3072
	s_add_u32 s28, s26, 0x100
	s_addc_u32 s29, s27, 0
	s_cmp_eq_u32 s54, 40
	s_cselect_b32 s35, s13, s29
	s_cselect_b32 s34, s12, s28
	s_cselect_b32 s31, s25, s53
	s_cselect_b32 s30, s24, s4
	v_lshl_add_u64 v[216:217], s[26:27], 0, v[146:147]
	s_add_i32 m0, s1, 0xc000
	ds_read_b128 v[184:187], v166
	ds_read_b128 v[188:191], v166 offset:1024
	ds_read_b128 v[192:195], v166 offset:2048
	ds_read_b128 v[196:199], v166 offset:3072
	ds_read_b128 v[200:203], v166 offset:4096
	ds_read_b128 v[204:207], v166 offset:5120
	ds_read_b128 v[208:211], v166 offset:6144
	ds_read_b128 v[212:215], v166 offset:7168
	global_load_lds_dwordx4 v[216:217], off
	v_lshl_add_u64 v[216:217], s[26:27], 0, v[148:149]
	s_add_i32 m0, s1, 0xe000
	s_nop 0
	global_load_lds_dwordx4 v[216:217], off
	s_waitcnt vmcnt(8)
	s_waitcnt lgkmcnt(0)
	s_barrier
	s_waitcnt lgkmcnt(0)
	v_mfma_f32_16x16x32_bf16 v[126:129], v[130:133], v[184:187], v[126:129]
	v_mfma_f32_16x16x32_bf16 v[122:125], v[154:157], v[184:187], v[122:125]
	v_mfma_f32_16x16x32_bf16 v[110:113], v[130:133], v[192:195], v[110:113]
	v_mfma_f32_16x16x32_bf16 v[106:109], v[154:157], v[192:195], v[106:109]
	v_mfma_f32_16x16x32_bf16 v[94:97], v[130:133], v[200:203], v[94:97]
	v_mfma_f32_16x16x32_bf16 v[90:93], v[154:157], v[200:203], v[90:93]
	v_mfma_f32_16x16x32_bf16 v[78:81], v[130:133], v[208:211], v[78:81]
	v_mfma_f32_16x16x32_bf16 v[74:77], v[154:157], v[208:211], v[74:77]
	v_mfma_f32_16x16x32_bf16 v[126:129], v[134:137], v[188:191], v[126:129]
	v_mfma_f32_16x16x32_bf16 v[122:125], v[158:161], v[188:191], v[122:125]
	v_mfma_f32_16x16x32_bf16 v[110:113], v[134:137], v[196:199], v[110:113]
	v_mfma_f32_16x16x32_bf16 v[106:109], v[158:161], v[196:199], v[106:109]
	v_mfma_f32_16x16x32_bf16 v[94:97], v[134:137], v[204:207], v[94:97]
	v_mfma_f32_16x16x32_bf16 v[90:93], v[158:161], v[204:207], v[90:93]
	v_mfma_f32_16x16x32_bf16 v[78:81], v[134:137], v[212:215], v[78:81]
	v_mfma_f32_16x16x32_bf16 v[74:77], v[158:161], v[212:215], v[74:77]
	v_mfma_f32_16x16x32_bf16 v[118:121], v[168:171], v[184:187], v[118:121]
	v_mfma_f32_16x16x32_bf16 v[114:117], v[176:179], v[184:187], v[114:117]
	v_mfma_f32_16x16x32_bf16 v[102:105], v[168:171], v[192:195], v[102:105]
	v_mfma_f32_16x16x32_bf16 v[98:101], v[176:179], v[192:195], v[98:101]
	v_mfma_f32_16x16x32_bf16 v[86:89], v[168:171], v[200:203], v[86:89]
	v_mfma_f32_16x16x32_bf16 v[82:85], v[176:179], v[200:203], v[82:85]
	v_mfma_f32_16x16x32_bf16 v[70:73], v[168:171], v[208:211], v[70:73]
	v_mfma_f32_16x16x32_bf16 v[66:69], v[176:179], v[208:211], v[66:69]
	v_mfma_f32_16x16x32_bf16 v[118:121], v[172:175], v[188:191], v[118:121]
	v_mfma_f32_16x16x32_bf16 v[114:117], v[180:183], v[188:191], v[114:117]
	v_mfma_f32_16x16x32_bf16 v[102:105], v[172:175], v[196:199], v[102:105]
	v_mfma_f32_16x16x32_bf16 v[98:101], v[180:183], v[196:199], v[98:101]
	v_mfma_f32_16x16x32_bf16 v[86:89], v[172:175], v[204:207], v[86:89]
	v_mfma_f32_16x16x32_bf16 v[82:85], v[180:183], v[204:207], v[82:85]
	v_mfma_f32_16x16x32_bf16 v[70:73], v[172:175], v[212:215], v[70:73]
	v_mfma_f32_16x16x32_bf16 v[66:69], v[180:183], v[212:215], v[66:69]
	s_barrier
	s_add_i32 s26, s46, s0
	v_lshl_add_u64 v[216:217], s[30:31], 0, v[140:141]
	s_mov_b32 m0, s26
	ds_read_b128 v[184:187], v166 offset:16384
	ds_read_b128 v[188:191], v166 offset:17408
	ds_read_b128 v[192:195], v166 offset:18432
	ds_read_b128 v[196:199], v166 offset:19456
	ds_read_b128 v[200:203], v166 offset:20480
	ds_read_b128 v[204:207], v166 offset:21504
	ds_read_b128 v[208:211], v166 offset:22528
	ds_read_b128 v[212:215], v166 offset:23552
	global_load_lds_dwordx4 v[216:217], off
	s_add_i32 m0, s26, 0x2000
	s_add_u32 s26, s30, 0xb0000
	v_lshl_add_u64 v[218:219], s[30:31], 0, v[144:145]
	s_addc_u32 s27, s31, 0
	s_add_i32 s55, s47, s0
	global_load_lds_dwordx4 v[218:219], off
	v_lshl_add_u64 v[220:221], s[26:27], 0, v[140:141]
	s_mov_b32 m0, s55
	v_lshl_add_u64 v[222:223], s[34:35], 0, v[142:143]
	global_load_lds_dwordx4 v[220:221], off
	v_lshl_add_u64 v[220:221], s[26:27], 0, v[144:145]
	s_add_i32 m0, s55, 0x2000
	s_nop 0
	global_load_lds_dwordx4 v[220:221], off
	v_lshl_add_u64 v[220:221], s[34:35], 0, v[138:139]
	s_mov_b32 m0, s1
	s_nop 0
	global_load_lds_dwordx4 v[220:221], off
	s_mov_b32 m0, s37
	s_nop 0
	global_load_lds_dwordx4 v[222:223], off
	s_waitcnt vmcnt(8)
	s_waitcnt lgkmcnt(0)
	s_barrier
; #define PG8_STAGE(bufoff, gbase, voff) do { _Pragma("unroll") for (int _i = 0; _i < 2; ++_i) \
;         __builtin_amdgcn_global_load_lds((const unsigned*)((const char*)(gbase) + (voff)[_i]), (PG8_LAS unsigned*)(lds + (bufoff) + ldsw + _i * 8192), 16, 0, 0); } while (0)
; #define PG8_LDA(dst, b, h) do { _Pragma("unroll") for (int m = 0; m < 4; ++m) _Pragma("unroll") for (int k = 0; k < 2; ++k) dst[m][k] = *(const PG8_LAS bf16x8*)(lds + PG8_SA(b, h) + aoff + m * 2048 + k * 1024); } while (0)
; #define PG8_LDB(dst, b, h) do { _Pragma("unroll") for (int n = 0; n < 2; ++n) _Pragma("unroll") for (int k = 0; k < 2; ++k) dst[n][k] = *(const PG8_LAS bf16x8*)(lds + PG8_SB(b, h) + boff + n * 2048 + k * 1024); } while (0)
; #define PG8_MMA(ai, bj, At, Bt) do { __builtin_amdgcn_s_setprio(1); _Pragma("unroll") for (int m = 0; m < 4; ++m) _Pragma("unroll") for (int n = 0; n < 2; ++n) _Pragma("unroll") for (int k = 0; k < 2; ++k) \
;         acc[ai][bj][m][n] = __builtin_amdgcn_mfma_f32_16x16x32_bf16(Bt[n][k], At[m][k], acc[ai][bj][m][n], 0, 0, 0); __builtin_amdgcn_s_setprio(0); } while (0)
; #define PG8_WAIT_V(n) asm volatile("s_waitcnt vmcnt(" #n ")" ::: "memory")
; #define PG8_WAIT_L(n) asm volatile("s_waitcnt lgkmcnt(" #n ")" ::: "memory")
; #define PG8_BAR __builtin_amdgcn_s_barrier()
; #define PG8_SCHED __builtin_amdgcn_sched_barrier(0)
; template <class Epi, class Sched, bool ALIGN_EPI = false, bool SP2 = false>
; __device__ __forceinline__ void gemm_phase(PG8_LAS unsigned char* lds, const Gemm g, const Sched& S, const Epi& E) {
;     ...
;             PG8_WAIT_V(8); PG8_WAIT_L(0); PG8_BAR; PG8_MMA(1, 0, At, B0); PG8_MMA(1, 1, At, B1); PG8_BAR; PG8_SCHED;
;             PG8_LDB(B0, 1, 0); PG8_LDB(B1, 1, 1); PG8_SCHED; PG8_LDA(At, 1, 0); PG8_STAGE(PG8_SA(0, 1), a2 + hstepA, voffA);
;             PG8_WAIT_V(8); PG8_WAIT_L(0); PG8_BAR; PG8_MMA(0, 0, At, B0); PG8_MMA(0, 1, At, B1); PG8_BAR; PG8_SCHED;
	s_waitcnt lgkmcnt(0)
	v_mfma_f32_16x16x32_bf16 v[62:65], v[130:133], v[184:187], v[62:65]
	v_mfma_f32_16x16x32_bf16 v[58:61], v[154:157], v[184:187], v[58:61]
	v_mfma_f32_16x16x32_bf16 v[46:49], v[130:133], v[192:195], v[46:49]
	v_mfma_f32_16x16x32_bf16 v[42:45], v[154:157], v[192:195], v[42:45]
	v_mfma_f32_16x16x32_bf16 v[30:33], v[130:133], v[200:203], v[30:33]
	v_mfma_f32_16x16x32_bf16 v[26:29], v[154:157], v[200:203], v[26:29]
	v_mfma_f32_16x16x32_bf16 v[14:17], v[130:133], v[208:211], v[14:17]
	v_mfma_f32_16x16x32_bf16 v[10:13], v[154:157], v[208:211], v[10:13]
	v_mfma_f32_16x16x32_bf16 v[62:65], v[134:137], v[188:191], v[62:65]
	v_mfma_f32_16x16x32_bf16 v[58:61], v[158:161], v[188:191], v[58:61]
	v_mfma_f32_16x16x32_bf16 v[46:49], v[134:137], v[196:199], v[46:49]
	v_mfma_f32_16x16x32_bf16 v[42:45], v[158:161], v[196:199], v[42:45]
	v_mfma_f32_16x16x32_bf16 v[30:33], v[134:137], v[204:207], v[30:33]
	v_mfma_f32_16x16x32_bf16 v[26:29], v[158:161], v[204:207], v[26:29]
	v_mfma_f32_16x16x32_bf16 v[14:17], v[134:137], v[212:215], v[14:17]
	v_mfma_f32_16x16x32_bf16 v[10:13], v[158:161], v[212:215], v[10:13]
	v_mfma_f32_16x16x32_bf16 v[54:57], v[168:171], v[184:187], v[54:57]
	v_mfma_f32_16x16x32_bf16 v[50:53], v[176:179], v[184:187], v[50:53]
	v_mfma_f32_16x16x32_bf16 v[38:41], v[168:171], v[192:195], v[38:41]
	v_mfma_f32_16x16x32_bf16 v[34:37], v[176:179], v[192:195], v[34:37]
	v_mfma_f32_16x16x32_bf16 v[22:25], v[168:171], v[200:203], v[22:25]
	v_mfma_f32_16x16x32_bf16 v[18:21], v[176:179], v[200:203], v[18:21]
	v_mfma_f32_16x16x32_bf16 v[6:9], v[168:171], v[208:211], v[6:9]
	v_mfma_f32_16x16x32_bf16 v[2:5], v[176:179], v[208:211], v[2:5]
	v_mfma_f32_16x16x32_bf16 v[54:57], v[172:175], v[188:191], v[54:57]
	v_mfma_f32_16x16x32_bf16 v[50:53], v[180:183], v[188:191], v[50:53]
	v_mfma_f32_16x16x32_bf16 v[38:41], v[172:175], v[196:199], v[38:41]
	v_mfma_f32_16x16x32_bf16 v[34:37], v[180:183], v[196:199], v[34:37]
	v_mfma_f32_16x16x32_bf16 v[22:25], v[172:175], v[204:207], v[22:25]
	v_mfma_f32_16x16x32_bf16 v[18:21], v[180:183], v[204:207], v[18:21]
	v_mfma_f32_16x16x32_bf16 v[6:9], v[172:175], v[212:215], v[6:9]
	v_mfma_f32_16x16x32_bf16 v[2:5], v[180:183], v[212:215], v[2:5]
	s_barrier
	s_add_i32 s55, 0, 0x18000
	s_add_i32 s56, 0, 0x1c000
	v_add_u32_e32 v158, s55, v162
	v_add_u32_e32 v180, s56, v162
	ds_read_b128 v[130:133], v158
	ds_read_b128 v[134:137], v158 offset:1024
	ds_read_b128 v[154:157], v158 offset:2048
	ds_read_b128 v[158:161], v158 offset:3072
	ds_read_b128 v[168:171], v180
	ds_read_b128 v[172:175], v180 offset:1024
	ds_read_b128 v[176:179], v180 offset:2048
	ds_read_b128 v[180:183], v180 offset:3072
	s_add_u32 s26, s34, 0xb0000
	s_addc_u32 s27, s35, 0
	s_mov_b32 m0, s38
	v_lshl_add_u64 v[224:225], s[26:27], 0, v[138:139]
	ds_read_b128 v[184:187], v166 offset:32768
	ds_read_b128 v[188:191], v166 offset:33792
	ds_read_b128 v[192:195], v166 offset:34816
	ds_read_b128 v[196:199], v166 offset:35840
	ds_read_b128 v[200:203], v166 offset:36864
	ds_read_b128 v[204:207], v166 offset:37888
	ds_read_b128 v[208:211], v166 offset:38912
	ds_read_b128 v[212:215], v166 offset:39936
	global_load_lds_dwordx4 v[224:225], off
	v_lshl_add_u64 v[224:225], s[26:27], 0, v[142:143]
	s_mov_b32 m0, s39
	s_nop 0
	global_load_lds_dwordx4 v[224:225], off
	s_waitcnt vmcnt(8)
	s_waitcnt lgkmcnt(0)
	s_barrier
	s_waitcnt lgkmcnt(0)
	v_mfma_f32_16x16x32_bf16 v[126:129], v[130:133], v[184:187], v[126:129]
	v_mfma_f32_16x16x32_bf16 v[122:125], v[154:157], v[184:187], v[122:125]
	v_mfma_f32_16x16x32_bf16 v[110:113], v[130:133], v[192:195], v[110:113]
	v_mfma_f32_16x16x32_bf16 v[106:109], v[154:157], v[192:195], v[106:109]
	v_mfma_f32_16x16x32_bf16 v[94:97], v[130:133], v[200:203], v[94:97]
	v_mfma_f32_16x16x32_bf16 v[90:93], v[154:157], v[200:203], v[90:93]
	v_mfma_f32_16x16x32_bf16 v[78:81], v[130:133], v[208:211], v[78:81]
	v_mfma_f32_16x16x32_bf16 v[74:77], v[154:157], v[208:211], v[74:77]
	v_mfma_f32_16x16x32_bf16 v[126:129], v[134:137], v[188:191], v[126:129]
	v_mfma_f32_16x16x32_bf16 v[122:125], v[158:161], v[188:191], v[122:125]
	v_mfma_f32_16x16x32_bf16 v[110:113], v[134:137], v[196:199], v[110:113]
	v_mfma_f32_16x16x32_bf16 v[106:109], v[158:161], v[196:199], v[106:109]
	v_mfma_f32_16x16x32_bf16 v[94:97], v[134:137], v[204:207], v[94:97]
	v_mfma_f32_16x16x32_bf16 v[90:93], v[158:161], v[204:207], v[90:93]
	v_mfma_f32_16x16x32_bf16 v[78:81], v[134:137], v[212:215], v[78:81]
	v_mfma_f32_16x16x32_bf16 v[74:77], v[158:161], v[212:215], v[74:77]
	v_mfma_f32_16x16x32_bf16 v[118:121], v[168:171], v[184:187], v[118:121]
	v_mfma_f32_16x16x32_bf16 v[114:117], v[176:179], v[184:187], v[114:117]
	v_mfma_f32_16x16x32_bf16 v[102:105], v[168:171], v[192:195], v[102:105]
	v_mfma_f32_16x16x32_bf16 v[98:101], v[176:179], v[192:195], v[98:101]
	v_mfma_f32_16x16x32_bf16 v[86:89], v[168:171], v[200:203], v[86:89]
	v_mfma_f32_16x16x32_bf16 v[82:85], v[176:179], v[200:203], v[82:85]
	v_mfma_f32_16x16x32_bf16 v[70:73], v[168:171], v[208:211], v[70:73]
	v_mfma_f32_16x16x32_bf16 v[66:69], v[176:179], v[208:211], v[66:69]
	v_mfma_f32_16x16x32_bf16 v[118:121], v[172:175], v[188:191], v[118:121]
	v_mfma_f32_16x16x32_bf16 v[114:117], v[180:183], v[188:191], v[114:117]
	v_mfma_f32_16x16x32_bf16 v[102:105], v[172:175], v[196:199], v[102:105]
	v_mfma_f32_16x16x32_bf16 v[98:101], v[180:183], v[196:199], v[98:101]
	v_mfma_f32_16x16x32_bf16 v[86:89], v[172:175], v[204:207], v[86:89]
	v_mfma_f32_16x16x32_bf16 v[82:85], v[180:183], v[204:207], v[82:85]
	v_mfma_f32_16x16x32_bf16 v[70:73], v[172:175], v[212:215], v[70:73]
	v_mfma_f32_16x16x32_bf16 v[66:69], v[180:183], v[212:215], v[66:69]
	s_barrier
; #define PG8_STAGE(bufoff, gbase, voff) do { _Pragma("unroll") for (int _i = 0; _i < 2; ++_i) \
;         __builtin_amdgcn_global_load_lds((const unsigned*)((const char*)(gbase) + (voff)[_i]), (PG8_LAS unsigned*)(lds + (bufoff) + ldsw + _i * 8192), 16, 0, 0); } while (0)
; #define PG8_LDA(dst, b, h) do { _Pragma("unroll") for (int m = 0; m < 4; ++m) _Pragma("unroll") for (int k = 0; k < 2; ++k) dst[m][k] = *(const PG8_LAS bf16x8*)(lds + PG8_SA(b, h) + aoff + m * 2048 + k * 1024); } while (0)
; #define PG8_WAIT_V(n) asm volatile("s_waitcnt vmcnt(" #n ")" ::: "memory")
; template <class Epi, class Sched, bool ALIGN_EPI = false, bool SP2 = false>
; __device__ __forceinline__ void gemm_phase(PG8_LAS unsigned char* lds, const Gemm g, const Sched& S, const Epi& E) {
;     ...
;             PG8_LDA(At, 1, 1); PG8_STAGE(PG8_SB(1, 0), b3, voffB); PG8_STAGE(PG8_SB(1, 1), b3 + hstepB, voffB); PG8_STAGE(PG8_SA(1, 0), a3, voffA);
;             PG8_WAIT_V(8); PG8_WAIT_L(0); PG8_BAR; PG8_MMA(1, 0, At, B0); PG8_MMA(1, 1, At, B1); PG8_BAR; PG8_SCHED;
;             } else {
;             PG8_LDB(B0, 0, 0); PG8_SCHED; PG8_LDA(At, 0, 0); PG8_STAGE(PG8_SA(1, 1), a1 + hstepA, voffA);
;             PG8_WAIT_L(8); PG8_BAR; PG8_WAIT_L(0); PG8_MMA(0, 0, At, B0); PG8_BAR; PG8_SCHED;
;             PG8_LDB(B1, 0, 1); PG8_STAGE(PG8_SB(0, 0), b2, voffB);
;             PG8_BAR; PG8_WAIT_L(0); PG8_MMA(0, 1, At, B1); PG8_BAR;
;             PG8_LDA(At, 0, 1); PG8_STAGE(PG8_SA(0, 0), a2, voffA);
;             PG8_BAR; PG8_WAIT_L(0); PG8_MMA(1, 0, At, B0); PG8_BAR; PG8_SCHED;
;             PG8_STAGE(PG8_SB(0, 1), b2 + hstepB, voffB);
;             PG8_WAIT_V(6); PG8_BAR; PG8_MMA(1, 1, At, B1); PG8_BAR;
;             PG8_LDB(B0, 1, 0); PG8_SCHED; PG8_LDA(At, 1, 0); PG8_STAGE(PG8_SA(0, 1), a2 + hstepA, voffA);
;             PG8_WAIT_L(8); PG8_BAR; PG8_WAIT_L(0); PG8_MMA(0, 0, At, B0); PG8_BAR; PG8_SCHED;
;             PG8_LDB(B1, 1, 1); PG8_STAGE(PG8_SB(1, 0), b3, voffB);
;             PG8_BAR; PG8_WAIT_L(0); PG8_MMA(0, 1, At, B1); PG8_BAR;
;             PG8_LDA(At, 1, 1); PG8_STAGE(PG8_SA(1, 0), a3, voffA);
;             PG8_BAR; PG8_WAIT_L(0); PG8_MMA(1, 0, At, B0); PG8_BAR; PG8_SCHED;
;             PG8_STAGE(PG8_SB(1, 1), b3 + hstepB, voffB);
;             PG8_WAIT_V(6); PG8_BAR; PG8_MMA(1, 1, At, B1); PG8_BAR;
;             }
;         }
;         if constexpr (ALIGN_EPI) { if (wr == 0) PG8_BAR; }
	s_add_i32 s26, s55, s0
	v_lshl_add_u64 v[216:217], v[216:217], 0, s[20:21]
	s_mov_b32 m0, s26
	ds_read_b128 v[184:187], v166 offset:49152
	ds_read_b128 v[188:191], v166 offset:50176
	ds_read_b128 v[192:195], v166 offset:51200
	ds_read_b128 v[196:199], v166 offset:52224
	ds_read_b128 v[200:203], v166 offset:53248
	ds_read_b128 v[204:207], v166 offset:54272
	ds_read_b128 v[208:211], v166 offset:55296
	ds_read_b128 v[212:215], v166 offset:56320
	global_load_lds_dwordx4 v[216:217], off
	s_add_i32 m0, s26, 0x2000
	s_add_u32 s26, s30, 0xb0080
	v_lshl_add_u64 v[216:217], v[218:219], 0, s[20:21]
	s_addc_u32 s27, s31, 0
	s_add_i32 s30, s56, s0
	global_load_lds_dwordx4 v[216:217], off
	v_lshl_add_u64 v[216:217], s[26:27], 0, v[140:141]
	s_mov_b32 m0, s30
	s_nop 0
	global_load_lds_dwordx4 v[216:217], off
	v_lshl_add_u64 v[216:217], s[26:27], 0, v[144:145]
	s_add_i32 m0, s30, 0x2000
	s_nop 0
	global_load_lds_dwordx4 v[216:217], off
	v_lshl_add_u64 v[216:217], v[220:221], 0, s[20:21]
	s_mov_b32 m0, s41
	s_nop 0
	global_load_lds_dwordx4 v[216:217], off
	v_lshl_add_u64 v[216:217], v[222:223], 0, s[20:21]
	s_mov_b32 m0, s42
	s_nop 0
	global_load_lds_dwordx4 v[216:217], off
	s_waitcnt vmcnt(8)
	s_waitcnt lgkmcnt(0)
	s_barrier
	s_waitcnt lgkmcnt(0)
	v_mfma_f32_16x16x32_bf16 v[62:65], v[130:133], v[184:187], v[62:65]
	v_mfma_f32_16x16x32_bf16 v[58:61], v[154:157], v[184:187], v[58:61]
	v_mfma_f32_16x16x32_bf16 v[46:49], v[130:133], v[192:195], v[46:49]
	v_mfma_f32_16x16x32_bf16 v[42:45], v[154:157], v[192:195], v[42:45]
	v_mfma_f32_16x16x32_bf16 v[30:33], v[130:133], v[200:203], v[30:33]
	v_mfma_f32_16x16x32_bf16 v[26:29], v[154:157], v[200:203], v[26:29]
	v_mfma_f32_16x16x32_bf16 v[14:17], v[130:133], v[208:211], v[14:17]
	v_mfma_f32_16x16x32_bf16 v[10:13], v[154:157], v[208:211], v[10:13]
	v_mfma_f32_16x16x32_bf16 v[62:65], v[134:137], v[188:191], v[62:65]
	v_mfma_f32_16x16x32_bf16 v[58:61], v[158:161], v[188:191], v[58:61]
	v_mfma_f32_16x16x32_bf16 v[46:49], v[134:137], v[196:199], v[46:49]
	v_mfma_f32_16x16x32_bf16 v[42:45], v[158:161], v[196:199], v[42:45]
	v_mfma_f32_16x16x32_bf16 v[30:33], v[134:137], v[204:207], v[30:33]
	v_mfma_f32_16x16x32_bf16 v[26:29], v[158:161], v[204:207], v[26:29]
	v_mfma_f32_16x16x32_bf16 v[14:17], v[134:137], v[212:215], v[14:17]
	v_mfma_f32_16x16x32_bf16 v[10:13], v[158:161], v[212:215], v[10:13]
	v_mfma_f32_16x16x32_bf16 v[54:57], v[168:171], v[184:187], v[54:57]
	v_mfma_f32_16x16x32_bf16 v[50:53], v[176:179], v[184:187], v[50:53]
	v_mfma_f32_16x16x32_bf16 v[38:41], v[168:171], v[192:195], v[38:41]
	v_mfma_f32_16x16x32_bf16 v[34:37], v[176:179], v[192:195], v[34:37]
	v_mfma_f32_16x16x32_bf16 v[22:25], v[168:171], v[200:203], v[22:25]
	v_mfma_f32_16x16x32_bf16 v[18:21], v[176:179], v[200:203], v[18:21]
	v_mfma_f32_16x16x32_bf16 v[6:9], v[168:171], v[208:211], v[6:9]
	v_mfma_f32_16x16x32_bf16 v[2:5], v[176:179], v[208:211], v[2:5]
	v_mfma_f32_16x16x32_bf16 v[54:57], v[172:175], v[188:191], v[54:57]
	v_mfma_f32_16x16x32_bf16 v[50:53], v[180:183], v[188:191], v[50:53]
	v_mfma_f32_16x16x32_bf16 v[38:41], v[172:175], v[196:199], v[38:41]
	v_mfma_f32_16x16x32_bf16 v[34:37], v[180:183], v[196:199], v[34:37]
	v_mfma_f32_16x16x32_bf16 v[22:25], v[172:175], v[204:207], v[22:25]
	v_mfma_f32_16x16x32_bf16 v[18:21], v[180:183], v[204:207], v[18:21]
	v_mfma_f32_16x16x32_bf16 v[6:9], v[172:175], v[212:215], v[6:9]
	v_mfma_f32_16x16x32_bf16 v[2:5], v[180:183], v[212:215], v[2:5]
	s_barrier
	s_add_i32 s54, s54, 2
	s_add_u32 s4, s4, 0x100
	s_addc_u32 s53, s53, 0
	s_cmp_gt_u32 s54, 41
	s_mov_b64 s[26:27], s[28:29]
	s_cbranch_scc0 .LBB0_776
	s_and_b64 vcc, exec, s[22:23]
	s_cbranch_vccz .LBB0_779
	s_barrier

; #define PG8_STAGE(bufoff, gbase, voff) do { _Pragma("unroll") for (int _i = 0; _i < 2; ++_i) \
;         __builtin_amdgcn_global_load_lds((const unsigned*)((const char*)(gbase) + (voff)[_i]), (PG8_LAS unsigned*)(lds + (bufoff) + ldsw + _i * 8192), 16, 0, 0); } while (0)
; #define PG8_LDA(dst, b, h) do { _Pragma("unroll") for (int m = 0; m < 4; ++m) _Pragma("unroll") for (int k = 0; k < 2; ++k) dst[m][k] = *(const PG8_LAS bf16x8*)(lds + PG8_SA(b, h) + aoff + m * 2048 + k * 1024); } while (0)
; #define PG8_LDB(dst, b, h) do { _Pragma("unroll") for (int n = 0; n < 2; ++n) _Pragma("unroll") for (int k = 0; k < 2; ++k) dst[n][k] = *(const PG8_LAS bf16x8*)(lds + PG8_SB(b, h) + boff + n * 2048 + k * 1024); } while (0)
; #define PG8_MMA(ai, bj, At, Bt) do { __builtin_amdgcn_s_setprio(1); _Pragma("unroll") for (int m = 0; m < 4; ++m) _Pragma("unroll") for (int n = 0; n < 2; ++n) _Pragma("unroll") for (int k = 0; k < 2; ++k) \
;         acc[ai][bj][m][n] = __builtin_amdgcn_mfma_f32_16x16x32_bf16(Bt[n][k], At[m][k], acc[ai][bj][m][n], 0, 0, 0); __builtin_amdgcn_s_setprio(0); } while (0)
; #define PG8_WAIT_V(n) asm volatile("s_waitcnt vmcnt(" #n ")" ::: "memory")
; #define PG8_WAIT_L(n) asm volatile("s_waitcnt lgkmcnt(" #n ")" ::: "memory")
; #define PG8_BAR __builtin_amdgcn_s_barrier()
; #define PG8_SCHED __builtin_amdgcn_sched_barrier(0)
; template <class Epi, class Sched, bool ALIGN_EPI = false, bool SP2 = false>
; __device__ __forceinline__ void gemm_phase(PG8_LAS unsigned char* lds, const Gemm g, const Sched& S, const Epi& E) {
;     ...
;             PG8_LDB(B0, 0, 0); PG8_LDB(B1, 0, 1); PG8_SCHED; PG8_LDA(At, 0, 0); PG8_STAGE(PG8_SA(1, 1), a1 + hstepA, voffA);
;             PG8_WAIT_V(8); PG8_WAIT_L(0); PG8_BAR; PG8_MMA(0, 0, At, B0); PG8_MMA(0, 1, At, B1); PG8_BAR; PG8_SCHED;
;             PG8_LDA(At, 0, 1); PG8_STAGE(PG8_SB(0, 0), b2, voffB); PG8_STAGE(PG8_SB(0, 1), b2 + hstepB, voffB); PG8_STAGE(PG8_SA(0, 0), a2, voffA);
.LBB0_821:
	ds_read_b128 v[152:155], v148
	ds_read_b128 v[156:159], v148 offset:1024
	ds_read_b128 v[160:163], v148 offset:2048
	ds_read_b128 v[164:167], v148 offset:3072
	ds_read_b128 v[168:171], v149
	ds_read_b128 v[172:175], v149 offset:1024
	ds_read_b128 v[176:179], v149 offset:2048
	ds_read_b128 v[180:183], v149 offset:3072
	s_add_i32 s65, s40, 2
	s_add_u32 s66, s38, 0x80
	s_addc_u32 s41, s39, 0
	s_cmp_eq_u32 s51, s40
	s_cselect_b32 s40, s8, s66
	s_cselect_b32 s41, s9, s41
	s_cselect_b32 s67, s37, s64
	s_cselect_b32 s66, s36, s63
	v_lshl_add_u64 v[216:217], s[38:39], 0, v[138:139]
	s_add_i32 m0, s43, 0xc000
	ds_read_b128 v[184:187], v150
	ds_read_b128 v[188:191], v150 offset:1024
	ds_read_b128 v[192:195], v150 offset:2048
	ds_read_b128 v[196:199], v150 offset:3072
	ds_read_b128 v[200:203], v150 offset:4096
	ds_read_b128 v[204:207], v150 offset:5120
	ds_read_b128 v[208:211], v150 offset:6144
	ds_read_b128 v[212:215], v150 offset:7168
	global_load_lds_dwordx4 v[216:217], off
	v_lshl_add_u64 v[216:217], s[38:39], 0, v[140:141]
	s_add_i32 m0, s43, 0xe000
	s_nop 0
	global_load_lds_dwordx4 v[216:217], off
	s_waitcnt vmcnt(8)
	s_waitcnt lgkmcnt(0)
	s_barrier
	s_waitcnt lgkmcnt(0)
	v_mfma_f32_16x16x32_bf16 v[122:125], v[152:155], v[184:187], v[122:125]
	v_mfma_f32_16x16x32_bf16 v[126:129], v[160:163], v[184:187], v[126:129]
	v_mfma_f32_16x16x32_bf16 v[110:113], v[152:155], v[192:195], v[110:113]
	v_mfma_f32_16x16x32_bf16 v[106:109], v[160:163], v[192:195], v[106:109]
	v_mfma_f32_16x16x32_bf16 v[94:97], v[152:155], v[200:203], v[94:97]
	v_mfma_f32_16x16x32_bf16 v[90:93], v[160:163], v[200:203], v[90:93]
	v_mfma_f32_16x16x32_bf16 v[78:81], v[152:155], v[208:211], v[78:81]
	v_mfma_f32_16x16x32_bf16 v[74:77], v[160:163], v[208:211], v[74:77]
	v_mfma_f32_16x16x32_bf16 v[122:125], v[156:159], v[188:191], v[122:125]
	v_mfma_f32_16x16x32_bf16 v[126:129], v[164:167], v[188:191], v[126:129]
	v_mfma_f32_16x16x32_bf16 v[110:113], v[156:159], v[196:199], v[110:113]
	v_mfma_f32_16x16x32_bf16 v[106:109], v[164:167], v[196:199], v[106:109]
	v_mfma_f32_16x16x32_bf16 v[94:97], v[156:159], v[204:207], v[94:97]
	v_mfma_f32_16x16x32_bf16 v[90:93], v[164:167], v[204:207], v[90:93]
	v_mfma_f32_16x16x32_bf16 v[78:81], v[156:159], v[212:215], v[78:81]
	v_mfma_f32_16x16x32_bf16 v[74:77], v[164:167], v[212:215], v[74:77]
	v_mfma_f32_16x16x32_bf16 v[118:121], v[168:171], v[184:187], v[118:121]
	v_mfma_f32_16x16x32_bf16 v[114:117], v[176:179], v[184:187], v[114:117]
	v_mfma_f32_16x16x32_bf16 v[102:105], v[168:171], v[192:195], v[102:105]
	v_mfma_f32_16x16x32_bf16 v[98:101], v[176:179], v[192:195], v[98:101]
	v_mfma_f32_16x16x32_bf16 v[86:89], v[168:171], v[200:203], v[86:89]
	v_mfma_f32_16x16x32_bf16 v[82:85], v[176:179], v[200:203], v[82:85]
	v_mfma_f32_16x16x32_bf16 v[70:73], v[168:171], v[208:211], v[70:73]
	v_mfma_f32_16x16x32_bf16 v[66:69], v[176:179], v[208:211], v[66:69]
	v_mfma_f32_16x16x32_bf16 v[118:121], v[172:175], v[188:191], v[118:121]
	v_mfma_f32_16x16x32_bf16 v[114:117], v[180:183], v[188:191], v[114:117]
	v_mfma_f32_16x16x32_bf16 v[102:105], v[172:175], v[196:199], v[102:105]
	v_mfma_f32_16x16x32_bf16 v[98:101], v[180:183], v[196:199], v[98:101]
	v_mfma_f32_16x16x32_bf16 v[86:89], v[172:175], v[204:207], v[86:89]
	v_mfma_f32_16x16x32_bf16 v[82:85], v[180:183], v[204:207], v[82:85]
	v_mfma_f32_16x16x32_bf16 v[70:73], v[172:175], v[212:215], v[70:73]
	v_mfma_f32_16x16x32_bf16 v[66:69], v[180:183], v[212:215], v[66:69]
	s_barrier
	s_add_i32 s68, s54, s42
	v_lshl_add_u64 v[216:217], s[66:67], 0, v[132:133]
	s_mov_b32 m0, s68
	ds_read_b128 v[184:187], v150 offset:16384
	ds_read_b128 v[188:191], v150 offset:17408
	ds_read_b128 v[192:195], v150 offset:18432
	ds_read_b128 v[196:199], v150 offset:19456
	ds_read_b128 v[200:203], v150 offset:20480
	ds_read_b128 v[204:207], v150 offset:21504
	ds_read_b128 v[208:211], v150 offset:22528
	ds_read_b128 v[212:215], v150 offset:23552
	global_load_lds_dwordx4 v[216:217], off
	s_add_i32 m0, s68, 0x2000
	v_lshl_add_u64 v[218:219], s[66:67], 0, v[136:137]
	s_add_u32 s66, s66, s10
	s_addc_u32 s67, s67, s11
	s_add_i32 s68, s55, s42
	global_load_lds_dwordx4 v[218:219], off
	v_lshl_add_u64 v[220:221], s[66:67], 0, v[132:133]
	s_mov_b32 m0, s68
	v_lshl_add_u64 v[222:223], s[66:67], 0, v[136:137]
	global_load_lds_dwordx4 v[220:221], off
	s_add_i32 m0, s68, 0x2000
	v_lshl_add_u64 v[224:225], s[40:41], 0, v[130:131]
	global_load_lds_dwordx4 v[222:223], off
	s_mov_b32 m0, s43
	v_lshl_add_u64 v[226:227], s[40:41], 0, v[134:135]
	global_load_lds_dwordx4 v[224:225], off
	s_mov_b32 m0, s44
	s_nop 0
	global_load_lds_dwordx4 v[226:227], off
	s_waitcnt vmcnt(8)
	s_waitcnt lgkmcnt(0)
	s_barrier
; #define PG8_STAGE(bufoff, gbase, voff) do { _Pragma("unroll") for (int _i = 0; _i < 2; ++_i) \
;         __builtin_amdgcn_global_load_lds((const unsigned*)((const char*)(gbase) + (voff)[_i]), (PG8_LAS unsigned*)(lds + (bufoff) + ldsw + _i * 8192), 16, 0, 0); } while (0)
; #define PG8_LDA(dst, b, h) do { _Pragma("unroll") for (int m = 0; m < 4; ++m) _Pragma("unroll") for (int k = 0; k < 2; ++k) dst[m][k] = *(const PG8_LAS bf16x8*)(lds + PG8_SA(b, h) + aoff + m * 2048 + k * 1024); } while (0)
; #define PG8_LDB(dst, b, h) do { _Pragma("unroll") for (int n = 0; n < 2; ++n) _Pragma("unroll") for (int k = 0; k < 2; ++k) dst[n][k] = *(const PG8_LAS bf16x8*)(lds + PG8_SB(b, h) + boff + n * 2048 + k * 1024); } while (0)
; #define PG8_MMA(ai, bj, At, Bt) do { __builtin_amdgcn_s_setprio(1); _Pragma("unroll") for (int m = 0; m < 4; ++m) _Pragma("unroll") for (int n = 0; n < 2; ++n) _Pragma("unroll") for (int k = 0; k < 2; ++k) \
;         acc[ai][bj][m][n] = __builtin_amdgcn_mfma_f32_16x16x32_bf16(Bt[n][k], At[m][k], acc[ai][bj][m][n], 0, 0, 0); __builtin_amdgcn_s_setprio(0); } while (0)
; #define PG8_WAIT_V(n) asm volatile("s_waitcnt vmcnt(" #n ")" ::: "memory")
; #define PG8_WAIT_L(n) asm volatile("s_waitcnt lgkmcnt(" #n ")" ::: "memory")
; #define PG8_BAR __builtin_amdgcn_s_barrier()
; #define PG8_SCHED __builtin_amdgcn_sched_barrier(0)
; template <class Epi, class Sched, bool ALIGN_EPI = false, bool SP2 = false>
; __device__ __forceinline__ void gemm_phase(PG8_LAS unsigned char* lds, const Gemm g, const Sched& S, const Epi& E) {
;     ...
;             PG8_WAIT_V(8); PG8_WAIT_L(0); PG8_BAR; PG8_MMA(1, 0, At, B0); PG8_MMA(1, 1, At, B1); PG8_BAR; PG8_SCHED;
;             PG8_LDB(B0, 1, 0); PG8_LDB(B1, 1, 1); PG8_SCHED; PG8_LDA(At, 1, 0); PG8_STAGE(PG8_SA(0, 1), a2 + hstepA, voffA);
;             PG8_WAIT_V(8); PG8_WAIT_L(0); PG8_BAR; PG8_MMA(0, 0, At, B0); PG8_MMA(0, 1, At, B1); PG8_BAR; PG8_SCHED;
	s_waitcnt lgkmcnt(0)
	v_mfma_f32_16x16x32_bf16 v[62:65], v[152:155], v[184:187], v[62:65]
	v_mfma_f32_16x16x32_bf16 v[58:61], v[160:163], v[184:187], v[58:61]
	v_mfma_f32_16x16x32_bf16 v[46:49], v[152:155], v[192:195], v[46:49]
	v_mfma_f32_16x16x32_bf16 v[42:45], v[160:163], v[192:195], v[42:45]
	v_mfma_f32_16x16x32_bf16 v[30:33], v[152:155], v[200:203], v[30:33]
	v_mfma_f32_16x16x32_bf16 v[26:29], v[160:163], v[200:203], v[26:29]
	v_mfma_f32_16x16x32_bf16 v[14:17], v[152:155], v[208:211], v[14:17]
	v_mfma_f32_16x16x32_bf16 v[10:13], v[160:163], v[208:211], v[10:13]
	v_mfma_f32_16x16x32_bf16 v[62:65], v[156:159], v[188:191], v[62:65]
	v_mfma_f32_16x16x32_bf16 v[58:61], v[164:167], v[188:191], v[58:61]
	v_mfma_f32_16x16x32_bf16 v[46:49], v[156:159], v[196:199], v[46:49]
	v_mfma_f32_16x16x32_bf16 v[42:45], v[164:167], v[196:199], v[42:45]
	v_mfma_f32_16x16x32_bf16 v[30:33], v[156:159], v[204:207], v[30:33]
	v_mfma_f32_16x16x32_bf16 v[26:29], v[164:167], v[204:207], v[26:29]
	v_mfma_f32_16x16x32_bf16 v[14:17], v[156:159], v[212:215], v[14:17]
	v_mfma_f32_16x16x32_bf16 v[10:13], v[164:167], v[212:215], v[10:13]
	v_mfma_f32_16x16x32_bf16 v[54:57], v[168:171], v[184:187], v[54:57]
	v_mfma_f32_16x16x32_bf16 v[50:53], v[176:179], v[184:187], v[50:53]
	v_mfma_f32_16x16x32_bf16 v[38:41], v[168:171], v[192:195], v[38:41]
	v_mfma_f32_16x16x32_bf16 v[34:37], v[176:179], v[192:195], v[34:37]
	v_mfma_f32_16x16x32_bf16 v[22:25], v[168:171], v[200:203], v[22:25]
	v_mfma_f32_16x16x32_bf16 v[18:21], v[176:179], v[200:203], v[18:21]
	v_mfma_f32_16x16x32_bf16 v[6:9], v[168:171], v[208:211], v[6:9]
	v_mfma_f32_16x16x32_bf16 v[2:5], v[176:179], v[208:211], v[2:5]
	v_mfma_f32_16x16x32_bf16 v[54:57], v[172:175], v[188:191], v[54:57]
	v_mfma_f32_16x16x32_bf16 v[50:53], v[180:183], v[188:191], v[50:53]
	v_mfma_f32_16x16x32_bf16 v[38:41], v[172:175], v[196:199], v[38:41]
	v_mfma_f32_16x16x32_bf16 v[34:37], v[180:183], v[196:199], v[34:37]
	v_mfma_f32_16x16x32_bf16 v[22:25], v[172:175], v[204:207], v[22:25]
	v_mfma_f32_16x16x32_bf16 v[18:21], v[180:183], v[204:207], v[18:21]
	v_mfma_f32_16x16x32_bf16 v[6:9], v[172:175], v[212:215], v[6:9]
	v_mfma_f32_16x16x32_bf16 v[2:5], v[180:183], v[212:215], v[2:5]
	s_barrier
	s_add_i32 s66, 0, 0x18000
	v_add_u32_e32 v151, s66, v146
	s_add_i32 s67, 0, 0x1c000
	ds_read_b128 v[152:155], v151
	ds_read_b128 v[156:159], v151 offset:1024
	ds_read_b128 v[160:163], v151 offset:2048
	ds_read_b128 v[164:167], v151 offset:3072
	v_add_u32_e32 v151, s67, v146
	ds_read_b128 v[168:171], v151
	ds_read_b128 v[172:175], v151 offset:1024
	ds_read_b128 v[176:179], v151 offset:2048
	ds_read_b128 v[180:183], v151 offset:3072
	s_add_u32 s40, s40, s4
	s_addc_u32 s41, s41, s5
	s_mov_b32 m0, s45
	v_lshl_add_u64 v[228:229], s[40:41], 0, v[130:131]
	ds_read_b128 v[184:187], v150 offset:32768
	ds_read_b128 v[188:191], v150 offset:33792
	ds_read_b128 v[192:195], v150 offset:34816
	ds_read_b128 v[196:199], v150 offset:35840
	ds_read_b128 v[200:203], v150 offset:36864
	ds_read_b128 v[204:207], v150 offset:37888
	ds_read_b128 v[208:211], v150 offset:38912
	ds_read_b128 v[212:215], v150 offset:39936
	global_load_lds_dwordx4 v[228:229], off
	v_lshl_add_u64 v[228:229], s[40:41], 0, v[134:135]
	s_mov_b32 m0, s46
	s_nop 0
	global_load_lds_dwordx4 v[228:229], off
	s_waitcnt vmcnt(8)
	s_waitcnt lgkmcnt(0)
	s_barrier
	s_waitcnt lgkmcnt(0)
	v_mfma_f32_16x16x32_bf16 v[122:125], v[152:155], v[184:187], v[122:125]
	v_mfma_f32_16x16x32_bf16 v[126:129], v[160:163], v[184:187], v[126:129]
	v_mfma_f32_16x16x32_bf16 v[110:113], v[152:155], v[192:195], v[110:113]
	v_mfma_f32_16x16x32_bf16 v[106:109], v[160:163], v[192:195], v[106:109]
	v_mfma_f32_16x16x32_bf16 v[94:97], v[152:155], v[200:203], v[94:97]
	v_mfma_f32_16x16x32_bf16 v[90:93], v[160:163], v[200:203], v[90:93]
	v_mfma_f32_16x16x32_bf16 v[78:81], v[152:155], v[208:211], v[78:81]
	v_mfma_f32_16x16x32_bf16 v[74:77], v[160:163], v[208:211], v[74:77]
	v_mfma_f32_16x16x32_bf16 v[122:125], v[156:159], v[188:191], v[122:125]
	v_mfma_f32_16x16x32_bf16 v[126:129], v[164:167], v[188:191], v[126:129]
	v_mfma_f32_16x16x32_bf16 v[110:113], v[156:159], v[196:199], v[110:113]
	v_mfma_f32_16x16x32_bf16 v[106:109], v[164:167], v[196:199], v[106:109]
	v_mfma_f32_16x16x32_bf16 v[94:97], v[156:159], v[204:207], v[94:97]
	v_mfma_f32_16x16x32_bf16 v[90:93], v[164:167], v[204:207], v[90:93]
	v_mfma_f32_16x16x32_bf16 v[78:81], v[156:159], v[212:215], v[78:81]
	v_mfma_f32_16x16x32_bf16 v[74:77], v[164:167], v[212:215], v[74:77]
	v_mfma_f32_16x16x32_bf16 v[118:121], v[168:171], v[184:187], v[118:121]
	v_mfma_f32_16x16x32_bf16 v[114:117], v[176:179], v[184:187], v[114:117]
	v_mfma_f32_16x16x32_bf16 v[102:105], v[168:171], v[192:195], v[102:105]
	v_mfma_f32_16x16x32_bf16 v[98:101], v[176:179], v[192:195], v[98:101]
	v_mfma_f32_16x16x32_bf16 v[86:89], v[168:171], v[200:203], v[86:89]
	v_mfma_f32_16x16x32_bf16 v[82:85], v[176:179], v[200:203], v[82:85]
	v_mfma_f32_16x16x32_bf16 v[70:73], v[168:171], v[208:211], v[70:73]
	v_mfma_f32_16x16x32_bf16 v[66:69], v[176:179], v[208:211], v[66:69]
	v_mfma_f32_16x16x32_bf16 v[118:121], v[172:175], v[188:191], v[118:121]
	v_mfma_f32_16x16x32_bf16 v[114:117], v[180:183], v[188:191], v[114:117]
	v_mfma_f32_16x16x32_bf16 v[102:105], v[172:175], v[196:199], v[102:105]
	v_mfma_f32_16x16x32_bf16 v[98:101], v[180:183], v[196:199], v[98:101]
	v_mfma_f32_16x16x32_bf16 v[86:89], v[172:175], v[204:207], v[86:89]
	v_mfma_f32_16x16x32_bf16 v[82:85], v[180:183], v[204:207], v[82:85]
	v_mfma_f32_16x16x32_bf16 v[70:73], v[172:175], v[212:215], v[70:73]
	v_mfma_f32_16x16x32_bf16 v[66:69], v[180:183], v[212:215], v[66:69]
	s_barrier
; #define PG8_STAGE(bufoff, gbase, voff) do { _Pragma("unroll") for (int _i = 0; _i < 2; ++_i) \
;         __builtin_amdgcn_global_load_lds((const unsigned*)((const char*)(gbase) + (voff)[_i]), (PG8_LAS unsigned*)(lds + (bufoff) + ldsw + _i * 8192), 16, 0, 0); } while (0)
; #define PG8_LDA(dst, b, h) do { _Pragma("unroll") for (int m = 0; m < 4; ++m) _Pragma("unroll") for (int k = 0; k < 2; ++k) dst[m][k] = *(const PG8_LAS bf16x8*)(lds + PG8_SA(b, h) + aoff + m * 2048 + k * 1024); } while (0)
; #define PG8_MMA(ai, bj, At, Bt) do { __builtin_amdgcn_s_setprio(1); _Pragma("unroll") for (int m = 0; m < 4; ++m) _Pragma("unroll") for (int n = 0; n < 2; ++n) _Pragma("unroll") for (int k = 0; k < 2; ++k) \
;         acc[ai][bj][m][n] = __builtin_amdgcn_mfma_f32_16x16x32_bf16(Bt[n][k], At[m][k], acc[ai][bj][m][n], 0, 0, 0); __builtin_amdgcn_s_setprio(0); } while (0)
; #define PG8_WAIT_V(n) asm volatile("s_waitcnt vmcnt(" #n ")" ::: "memory")
; #define PG8_WAIT_L(n) asm volatile("s_waitcnt lgkmcnt(" #n ")" ::: "memory")
; #define PG8_BAR __builtin_amdgcn_s_barrier()
; #define PG8_SCHED __builtin_amdgcn_sched_barrier(0)
; template <class Epi, class Sched, bool ALIGN_EPI = false, bool SP2 = false>
; __device__ __forceinline__ void gemm_phase(PG8_LAS unsigned char* lds, const Gemm g, const Sched& S, const Epi& E) {
;     ...
;             PG8_LDA(At, 1, 1); PG8_STAGE(PG8_SB(1, 0), b3, voffB); PG8_STAGE(PG8_SB(1, 1), b3 + hstepB, voffB); PG8_STAGE(PG8_SA(1, 0), a3, voffA);
;             PG8_WAIT_V(8); PG8_WAIT_L(0); PG8_BAR; PG8_MMA(1, 0, At, B0); PG8_MMA(1, 1, At, B1); PG8_BAR; PG8_SCHED;
	s_add_i32 s40, s66, s42
	v_lshl_add_u64 v[216:217], v[216:217], 0, s[20:21]
	s_mov_b32 m0, s40
	ds_read_b128 v[184:187], v150 offset:49152
	ds_read_b128 v[188:191], v150 offset:50176
	ds_read_b128 v[192:195], v150 offset:51200
	ds_read_b128 v[196:199], v150 offset:52224
	ds_read_b128 v[200:203], v150 offset:53248
	ds_read_b128 v[204:207], v150 offset:54272
	ds_read_b128 v[208:211], v150 offset:55296
	ds_read_b128 v[212:215], v150 offset:56320
	global_load_lds_dwordx4 v[216:217], off
	v_lshl_add_u64 v[216:217], v[218:219], 0, s[20:21]
	s_add_i32 m0, s40, 0x2000
	s_add_i32 s40, s67, s42
	global_load_lds_dwordx4 v[216:217], off
	v_lshl_add_u64 v[216:217], v[220:221], 0, s[20:21]
	s_mov_b32 m0, s40
	s_nop 0
	global_load_lds_dwordx4 v[216:217], off
	v_lshl_add_u64 v[216:217], v[222:223], 0, s[20:21]
	s_add_i32 m0, s40, 0x2000
	s_nop 0
	global_load_lds_dwordx4 v[216:217], off
	v_lshl_add_u64 v[216:217], v[224:225], 0, s[20:21]
	s_mov_b32 m0, s48
	s_nop 0
	global_load_lds_dwordx4 v[216:217], off
	v_lshl_add_u64 v[216:217], v[226:227], 0, s[20:21]
	s_mov_b32 m0, s49
	s_nop 0
	global_load_lds_dwordx4 v[216:217], off
	s_waitcnt vmcnt(8)
	s_waitcnt lgkmcnt(0)
	s_barrier
	s_waitcnt lgkmcnt(0)
	v_mfma_f32_16x16x32_bf16 v[62:65], v[152:155], v[184:187], v[62:65]
	v_mfma_f32_16x16x32_bf16 v[58:61], v[160:163], v[184:187], v[58:61]
	v_mfma_f32_16x16x32_bf16 v[46:49], v[152:155], v[192:195], v[46:49]
	v_mfma_f32_16x16x32_bf16 v[42:45], v[160:163], v[192:195], v[42:45]
	v_mfma_f32_16x16x32_bf16 v[30:33], v[152:155], v[200:203], v[30:33]
	v_mfma_f32_16x16x32_bf16 v[26:29], v[160:163], v[200:203], v[26:29]
	v_mfma_f32_16x16x32_bf16 v[14:17], v[152:155], v[208:211], v[14:17]
	v_mfma_f32_16x16x32_bf16 v[10:13], v[160:163], v[208:211], v[10:13]
	v_mfma_f32_16x16x32_bf16 v[62:65], v[156:159], v[188:191], v[62:65]
	v_mfma_f32_16x16x32_bf16 v[58:61], v[164:167], v[188:191], v[58:61]
	v_mfma_f32_16x16x32_bf16 v[46:49], v[156:159], v[196:199], v[46:49]
	v_mfma_f32_16x16x32_bf16 v[42:45], v[164:167], v[196:199], v[42:45]
	v_mfma_f32_16x16x32_bf16 v[30:33], v[156:159], v[204:207], v[30:33]
	v_mfma_f32_16x16x32_bf16 v[26:29], v[164:167], v[204:207], v[26:29]
	v_mfma_f32_16x16x32_bf16 v[14:17], v[156:159], v[212:215], v[14:17]
	v_mfma_f32_16x16x32_bf16 v[10:13], v[164:167], v[212:215], v[10:13]
	v_mfma_f32_16x16x32_bf16 v[54:57], v[168:171], v[184:187], v[54:57]
	v_mfma_f32_16x16x32_bf16 v[50:53], v[176:179], v[184:187], v[50:53]
	v_mfma_f32_16x16x32_bf16 v[38:41], v[168:171], v[192:195], v[38:41]
	v_mfma_f32_16x16x32_bf16 v[34:37], v[176:179], v[192:195], v[34:37]
	v_mfma_f32_16x16x32_bf16 v[22:25], v[168:171], v[200:203], v[22:25]
	v_mfma_f32_16x16x32_bf16 v[18:21], v[176:179], v[200:203], v[18:21]
	v_mfma_f32_16x16x32_bf16 v[6:9], v[168:171], v[208:211], v[6:9]
	v_mfma_f32_16x16x32_bf16 v[2:5], v[176:179], v[208:211], v[2:5]
	v_mfma_f32_16x16x32_bf16 v[54:57], v[172:175], v[188:191], v[54:57]
	v_mfma_f32_16x16x32_bf16 v[50:53], v[180:183], v[188:191], v[50:53]
	v_mfma_f32_16x16x32_bf16 v[38:41], v[172:175], v[196:199], v[38:41]
	v_mfma_f32_16x16x32_bf16 v[34:37], v[180:183], v[196:199], v[34:37]
	v_mfma_f32_16x16x32_bf16 v[22:25], v[172:175], v[204:207], v[22:25]
	v_mfma_f32_16x16x32_bf16 v[18:21], v[180:183], v[204:207], v[18:21]
	v_mfma_f32_16x16x32_bf16 v[6:9], v[172:175], v[212:215], v[6:9]
	v_mfma_f32_16x16x32_bf16 v[2:5], v[180:183], v[212:215], v[2:5]
	s_barrier
	s_add_u32 s38, s38, 0x100
	s_addc_u32 s39, s39, 0
	s_add_u32 s63, s63, 0x100
	s_addc_u32 s64, s64, 0
	s_cmp_ge_i32 s65, s50
	s_mov_b32 s40, s65
	s_cbranch_scc0 .LBB0_821

; #define PG8_STAGE(bufoff, gbase, voff) do { _Pragma("unroll") for (int _i = 0; _i < 2; ++_i) \
;         __builtin_amdgcn_global_load_lds((const unsigned*)((const char*)(gbase) + (voff)[_i]), (PG8_LAS unsigned*)(lds + (bufoff) + ldsw + _i * 8192), 16, 0, 0); } while (0)
; #define PG8_LDA(dst, b, h) do { _Pragma("unroll") for (int m = 0; m < 4; ++m) _Pragma("unroll") for (int k = 0; k < 2; ++k) dst[m][k] = *(const PG8_LAS bf16x8*)(lds + PG8_SA(b, h) + aoff + m * 2048 + k * 1024); } while (0)
; #define PG8_LDB(dst, b, h) do { _Pragma("unroll") for (int n = 0; n < 2; ++n) _Pragma("unroll") for (int k = 0; k < 2; ++k) dst[n][k] = *(const PG8_LAS bf16x8*)(lds + PG8_SB(b, h) + boff + n * 2048 + k * 1024); } while (0)
; #define PG8_MMA(ai, bj, At, Bt) do { __builtin_amdgcn_s_setprio(1); _Pragma("unroll") for (int m = 0; m < 4; ++m) _Pragma("unroll") for (int n = 0; n < 2; ++n) _Pragma("unroll") for (int k = 0; k < 2; ++k) \
;         acc[ai][bj][m][n] = __builtin_amdgcn_mfma_f32_16x16x32_bf16(Bt[n][k], At[m][k], acc[ai][bj][m][n], 0, 0, 0); __builtin_amdgcn_s_setprio(0); } while (0)
; #define PG8_WAIT_V(n) asm volatile("s_waitcnt vmcnt(" #n ")" ::: "memory")
; #define PG8_WAIT_L(n) asm volatile("s_waitcnt lgkmcnt(" #n ")" ::: "memory")
; #define PG8_BAR __builtin_amdgcn_s_barrier()
; #define PG8_SCHED __builtin_amdgcn_sched_barrier(0)
; template <class Epi, class Sched, bool ALIGN_EPI = false, bool SP2 = false>
; __device__ __forceinline__ void gemm_phase(PG8_LAS unsigned char* lds, const Gemm g, const Sched& S, const Epi& E) {
;     ...
;             PG8_LDB(B0, 0, 0); PG8_LDB(B1, 0, 1); PG8_SCHED; PG8_LDA(At, 0, 0); PG8_STAGE(PG8_SA(1, 1), a1 + hstepA, voffA);
;             PG8_WAIT_V(8); PG8_WAIT_L(0); PG8_BAR; PG8_MMA(0, 0, At, B0); PG8_MMA(0, 1, At, B1); PG8_BAR; PG8_SCHED;
;             PG8_LDA(At, 0, 1); PG8_STAGE(PG8_SB(0, 0), b2, voffB); PG8_STAGE(PG8_SB(0, 1), b2 + hstepB, voffB); PG8_STAGE(PG8_SA(0, 0), a2, voffA);
.LBB0_903:
	ds_read_b128 v[130:133], v186
	ds_read_b128 v[134:137], v186 offset:1024
	ds_read_b128 v[138:141], v186 offset:2048
	ds_read_b128 v[142:145], v186 offset:3072
	ds_read_b128 v[164:167], v187
	ds_read_b128 v[168:171], v187 offset:1024
	ds_read_b128 v[172:175], v187 offset:2048
	ds_read_b128 v[176:179], v187 offset:3072
	s_add_u32 s38, s36, 0xfffc0080
	s_addc_u32 s39, s37, -1
	s_cmp_eq_u32 s33, 12
	s_cselect_b32 s41, s0, s39
	s_cselect_b32 s40, s1, s38
	s_cselect_b32 s39, s2, s29
	s_cselect_b32 s38, s5, s27
	v_lshl_add_u64 v[220:221], s[36:37], 0, v[156:157]
	s_add_i32 m0, s44, 0xc000
	ds_read_b128 v[180:183], v188
	ds_read_b128 v[192:195], v188 offset:1024
	ds_read_b128 v[196:199], v188 offset:2048
	ds_read_b128 v[200:203], v188 offset:3072
	ds_read_b128 v[204:207], v188 offset:4096
	ds_read_b128 v[208:211], v188 offset:5120
	ds_read_b128 v[212:215], v188 offset:6144
	ds_read_b128 v[216:219], v188 offset:7168
	global_load_lds_dwordx4 v[220:221], off
	v_lshl_add_u64 v[220:221], s[36:37], 0, v[158:159]
	s_add_i32 m0, s44, 0xe000
	s_nop 0
	global_load_lds_dwordx4 v[220:221], off
	s_waitcnt vmcnt(8)
	s_waitcnt lgkmcnt(0)
	s_barrier
	s_waitcnt lgkmcnt(0)
	v_mfma_f32_16x16x32_bf16 v[126:129], v[130:133], v[180:183], v[126:129]
	v_mfma_f32_16x16x32_bf16 v[122:125], v[138:141], v[180:183], v[122:125]
	v_mfma_f32_16x16x32_bf16 v[110:113], v[130:133], v[196:199], v[110:113]
	v_mfma_f32_16x16x32_bf16 v[106:109], v[138:141], v[196:199], v[106:109]
	v_mfma_f32_16x16x32_bf16 v[94:97], v[130:133], v[204:207], v[94:97]
	v_mfma_f32_16x16x32_bf16 v[90:93], v[138:141], v[204:207], v[90:93]
	v_mfma_f32_16x16x32_bf16 v[78:81], v[130:133], v[212:215], v[78:81]
	v_mfma_f32_16x16x32_bf16 v[74:77], v[138:141], v[212:215], v[74:77]
	v_mfma_f32_16x16x32_bf16 v[126:129], v[134:137], v[192:195], v[126:129]
	v_mfma_f32_16x16x32_bf16 v[122:125], v[142:145], v[192:195], v[122:125]
	v_mfma_f32_16x16x32_bf16 v[110:113], v[134:137], v[200:203], v[110:113]
	v_mfma_f32_16x16x32_bf16 v[106:109], v[142:145], v[200:203], v[106:109]
	v_mfma_f32_16x16x32_bf16 v[94:97], v[134:137], v[208:211], v[94:97]
	v_mfma_f32_16x16x32_bf16 v[90:93], v[142:145], v[208:211], v[90:93]
	v_mfma_f32_16x16x32_bf16 v[78:81], v[134:137], v[216:219], v[78:81]
	v_mfma_f32_16x16x32_bf16 v[74:77], v[142:145], v[216:219], v[74:77]
	v_mfma_f32_16x16x32_bf16 v[118:121], v[164:167], v[180:183], v[118:121]
	v_mfma_f32_16x16x32_bf16 v[114:117], v[172:175], v[180:183], v[114:117]
	v_mfma_f32_16x16x32_bf16 v[102:105], v[164:167], v[196:199], v[102:105]
	v_mfma_f32_16x16x32_bf16 v[98:101], v[172:175], v[196:199], v[98:101]
	v_mfma_f32_16x16x32_bf16 v[86:89], v[164:167], v[204:207], v[86:89]
	v_mfma_f32_16x16x32_bf16 v[82:85], v[172:175], v[204:207], v[82:85]
	v_mfma_f32_16x16x32_bf16 v[70:73], v[164:167], v[212:215], v[70:73]
	v_mfma_f32_16x16x32_bf16 v[66:69], v[172:175], v[212:215], v[66:69]
	v_mfma_f32_16x16x32_bf16 v[118:121], v[168:171], v[192:195], v[118:121]
	v_mfma_f32_16x16x32_bf16 v[114:117], v[176:179], v[192:195], v[114:117]
	v_mfma_f32_16x16x32_bf16 v[102:105], v[168:171], v[200:203], v[102:105]
	v_mfma_f32_16x16x32_bf16 v[98:101], v[176:179], v[200:203], v[98:101]
	v_mfma_f32_16x16x32_bf16 v[86:89], v[168:171], v[208:211], v[86:89]
	v_mfma_f32_16x16x32_bf16 v[82:85], v[176:179], v[208:211], v[82:85]
	v_mfma_f32_16x16x32_bf16 v[70:73], v[168:171], v[216:219], v[70:73]
	v_mfma_f32_16x16x32_bf16 v[66:69], v[176:179], v[216:219], v[66:69]
	s_barrier
	s_add_i32 s58, s55, s43
	v_lshl_add_u64 v[220:221], s[38:39], 0, v[148:149]
	s_mov_b32 m0, s58
	ds_read_b128 v[180:183], v188 offset:16384
	ds_read_b128 v[192:195], v188 offset:17408
	ds_read_b128 v[196:199], v188 offset:18432
	ds_read_b128 v[200:203], v188 offset:19456
	ds_read_b128 v[204:207], v188 offset:20480
	ds_read_b128 v[208:211], v188 offset:21504
	ds_read_b128 v[212:215], v188 offset:22528
	ds_read_b128 v[216:219], v188 offset:23552
	global_load_lds_dwordx4 v[220:221], off
	s_add_i32 m0, s58, 0x2000
	s_add_u32 s58, s38, 0x40000
	v_lshl_add_u64 v[222:223], s[38:39], 0, v[152:153]
	s_addc_u32 s59, s39, 0
	s_add_i32 s60, s56, s43
	global_load_lds_dwordx4 v[222:223], off
	v_lshl_add_u64 v[224:225], s[58:59], 0, v[148:149]
	s_mov_b32 m0, s60
	v_lshl_add_u64 v[226:227], s[40:41], 0, v[150:151]
	global_load_lds_dwordx4 v[224:225], off
	v_lshl_add_u64 v[224:225], s[58:59], 0, v[152:153]
	s_add_i32 m0, s60, 0x2000
	s_nop 0
	global_load_lds_dwordx4 v[224:225], off
	v_lshl_add_u64 v[224:225], s[40:41], 0, v[146:147]
	s_mov_b32 m0, s44
	s_nop 0
	global_load_lds_dwordx4 v[224:225], off
	s_mov_b32 m0, s45
	s_nop 0
	global_load_lds_dwordx4 v[226:227], off
	s_waitcnt vmcnt(8)
	s_waitcnt lgkmcnt(0)
	s_barrier
; #define PG8_STAGE(bufoff, gbase, voff) do { _Pragma("unroll") for (int _i = 0; _i < 2; ++_i) \
;         __builtin_amdgcn_global_load_lds((const unsigned*)((const char*)(gbase) + (voff)[_i]), (PG8_LAS unsigned*)(lds + (bufoff) + ldsw + _i * 8192), 16, 0, 0); } while (0)
; #define PG8_LDA(dst, b, h) do { _Pragma("unroll") for (int m = 0; m < 4; ++m) _Pragma("unroll") for (int k = 0; k < 2; ++k) dst[m][k] = *(const PG8_LAS bf16x8*)(lds + PG8_SA(b, h) + aoff + m * 2048 + k * 1024); } while (0)
; #define PG8_LDB(dst, b, h) do { _Pragma("unroll") for (int n = 0; n < 2; ++n) _Pragma("unroll") for (int k = 0; k < 2; ++k) dst[n][k] = *(const PG8_LAS bf16x8*)(lds + PG8_SB(b, h) + boff + n * 2048 + k * 1024); } while (0)
; #define PG8_MMA(ai, bj, At, Bt) do { __builtin_amdgcn_s_setprio(1); _Pragma("unroll") for (int m = 0; m < 4; ++m) _Pragma("unroll") for (int n = 0; n < 2; ++n) _Pragma("unroll") for (int k = 0; k < 2; ++k) \
;         acc[ai][bj][m][n] = __builtin_amdgcn_mfma_f32_16x16x32_bf16(Bt[n][k], At[m][k], acc[ai][bj][m][n], 0, 0, 0); __builtin_amdgcn_s_setprio(0); } while (0)
; #define PG8_WAIT_V(n) asm volatile("s_waitcnt vmcnt(" #n ")" ::: "memory")
; #define PG8_WAIT_L(n) asm volatile("s_waitcnt lgkmcnt(" #n ")" ::: "memory")
; #define PG8_BAR __builtin_amdgcn_s_barrier()
; #define PG8_SCHED __builtin_amdgcn_sched_barrier(0)
; template <class Epi, class Sched, bool ALIGN_EPI = false, bool SP2 = false>
; __device__ __forceinline__ void gemm_phase(PG8_LAS unsigned char* lds, const Gemm g, const Sched& S, const Epi& E) {
;     ...
;             PG8_WAIT_V(8); PG8_WAIT_L(0); PG8_BAR; PG8_MMA(0, 0, At, B0); PG8_MMA(0, 1, At, B1); PG8_BAR; PG8_SCHED;
;             PG8_LDA(At, 0, 1); PG8_STAGE(PG8_SB(0, 0), b2, voffB); PG8_STAGE(PG8_SB(0, 1), b2 + hstepB, voffB); PG8_STAGE(PG8_SA(0, 0), a2, voffA);
;             PG8_WAIT_V(8); PG8_WAIT_L(0); PG8_BAR; PG8_MMA(1, 0, At, B0); PG8_MMA(1, 1, At, B1); PG8_BAR; PG8_SCHED;
;             PG8_LDB(B0, 1, 0); PG8_LDB(B1, 1, 1); PG8_SCHED; PG8_LDA(At, 1, 0); PG8_STAGE(PG8_SA(0, 1), a2 + hstepA, voffA);
;             PG8_WAIT_V(8); PG8_WAIT_L(0); PG8_BAR; PG8_MMA(0, 0, At, B0); PG8_MMA(0, 1, At, B1); PG8_BAR; PG8_SCHED;
	s_waitcnt lgkmcnt(0)
	v_mfma_f32_16x16x32_bf16 v[62:65], v[130:133], v[180:183], v[62:65]
	v_mfma_f32_16x16x32_bf16 v[58:61], v[138:141], v[180:183], v[58:61]
	v_mfma_f32_16x16x32_bf16 v[46:49], v[130:133], v[196:199], v[46:49]
	v_mfma_f32_16x16x32_bf16 v[42:45], v[138:141], v[196:199], v[42:45]
	v_mfma_f32_16x16x32_bf16 v[30:33], v[130:133], v[204:207], v[30:33]
	v_mfma_f32_16x16x32_bf16 v[26:29], v[138:141], v[204:207], v[26:29]
	v_mfma_f32_16x16x32_bf16 v[14:17], v[130:133], v[212:215], v[14:17]
	v_mfma_f32_16x16x32_bf16 v[10:13], v[138:141], v[212:215], v[10:13]
	v_mfma_f32_16x16x32_bf16 v[62:65], v[134:137], v[192:195], v[62:65]
	v_mfma_f32_16x16x32_bf16 v[58:61], v[142:145], v[192:195], v[58:61]
	v_mfma_f32_16x16x32_bf16 v[46:49], v[134:137], v[200:203], v[46:49]
	v_mfma_f32_16x16x32_bf16 v[42:45], v[142:145], v[200:203], v[42:45]
	v_mfma_f32_16x16x32_bf16 v[30:33], v[134:137], v[208:211], v[30:33]
	v_mfma_f32_16x16x32_bf16 v[26:29], v[142:145], v[208:211], v[26:29]
	v_mfma_f32_16x16x32_bf16 v[14:17], v[134:137], v[216:219], v[14:17]
	v_mfma_f32_16x16x32_bf16 v[10:13], v[142:145], v[216:219], v[10:13]
	v_mfma_f32_16x16x32_bf16 v[54:57], v[164:167], v[180:183], v[54:57]
	v_mfma_f32_16x16x32_bf16 v[50:53], v[172:175], v[180:183], v[50:53]
	v_mfma_f32_16x16x32_bf16 v[38:41], v[164:167], v[196:199], v[38:41]
	v_mfma_f32_16x16x32_bf16 v[34:37], v[172:175], v[196:199], v[34:37]
	v_mfma_f32_16x16x32_bf16 v[22:25], v[164:167], v[204:207], v[22:25]
	v_mfma_f32_16x16x32_bf16 v[18:21], v[172:175], v[204:207], v[18:21]
	v_mfma_f32_16x16x32_bf16 v[6:9], v[164:167], v[212:215], v[6:9]
	v_mfma_f32_16x16x32_bf16 v[2:5], v[172:175], v[212:215], v[2:5]
	v_mfma_f32_16x16x32_bf16 v[54:57], v[168:171], v[192:195], v[54:57]
	v_mfma_f32_16x16x32_bf16 v[50:53], v[176:179], v[192:195], v[50:53]
	v_mfma_f32_16x16x32_bf16 v[38:41], v[168:171], v[200:203], v[38:41]
	v_mfma_f32_16x16x32_bf16 v[34:37], v[176:179], v[200:203], v[34:37]
	v_mfma_f32_16x16x32_bf16 v[22:25], v[168:171], v[208:211], v[22:25]
	v_mfma_f32_16x16x32_bf16 v[18:21], v[176:179], v[208:211], v[18:21]
	v_mfma_f32_16x16x32_bf16 v[6:9], v[168:171], v[216:219], v[6:9]
	v_mfma_f32_16x16x32_bf16 v[2:5], v[176:179], v[216:219], v[2:5]
	s_barrier
	s_add_i32 s58, 0, 0x18000
	s_add_i32 s59, 0, 0x1c000
	v_add_u32_e32 v142, s58, v184
	v_add_u32_e32 v176, s59, v184
	ds_read_b128 v[130:133], v142
	ds_read_b128 v[134:137], v142 offset:1024
	ds_read_b128 v[138:141], v142 offset:2048
	ds_read_b128 v[142:145], v142 offset:3072
	ds_read_b128 v[164:167], v176
	ds_read_b128 v[168:171], v176 offset:1024
	ds_read_b128 v[172:175], v176 offset:2048
	ds_read_b128 v[176:179], v176 offset:3072
	s_add_u32 s40, s40, 0x40000
	s_addc_u32 s41, s41, 0
	s_mov_b32 m0, s46
	v_lshl_add_u64 v[228:229], s[40:41], 0, v[146:147]
	ds_read_b128 v[180:183], v188 offset:32768
	ds_read_b128 v[192:195], v188 offset:33792
	ds_read_b128 v[196:199], v188 offset:34816
	ds_read_b128 v[200:203], v188 offset:35840
	ds_read_b128 v[204:207], v188 offset:36864
	ds_read_b128 v[208:211], v188 offset:37888
	ds_read_b128 v[212:215], v188 offset:38912
	ds_read_b128 v[216:219], v188 offset:39936
	global_load_lds_dwordx4 v[228:229], off
	v_lshl_add_u64 v[228:229], s[40:41], 0, v[150:151]
	s_mov_b32 m0, s47
	s_nop 0
	global_load_lds_dwordx4 v[228:229], off
	s_waitcnt vmcnt(8)
	s_waitcnt lgkmcnt(0)
	s_barrier
	s_waitcnt lgkmcnt(0)
	v_mfma_f32_16x16x32_bf16 v[126:129], v[130:133], v[180:183], v[126:129]
	v_mfma_f32_16x16x32_bf16 v[122:125], v[138:141], v[180:183], v[122:125]
	v_mfma_f32_16x16x32_bf16 v[110:113], v[130:133], v[196:199], v[110:113]
	v_mfma_f32_16x16x32_bf16 v[106:109], v[138:141], v[196:199], v[106:109]
	v_mfma_f32_16x16x32_bf16 v[94:97], v[130:133], v[204:207], v[94:97]
	v_mfma_f32_16x16x32_bf16 v[90:93], v[138:141], v[204:207], v[90:93]
	v_mfma_f32_16x16x32_bf16 v[78:81], v[130:133], v[212:215], v[78:81]
	v_mfma_f32_16x16x32_bf16 v[74:77], v[138:141], v[212:215], v[74:77]
	v_mfma_f32_16x16x32_bf16 v[126:129], v[134:137], v[192:195], v[126:129]
	v_mfma_f32_16x16x32_bf16 v[122:125], v[142:145], v[192:195], v[122:125]
	v_mfma_f32_16x16x32_bf16 v[110:113], v[134:137], v[200:203], v[110:113]
	v_mfma_f32_16x16x32_bf16 v[106:109], v[142:145], v[200:203], v[106:109]
	v_mfma_f32_16x16x32_bf16 v[94:97], v[134:137], v[208:211], v[94:97]
	v_mfma_f32_16x16x32_bf16 v[90:93], v[142:145], v[208:211], v[90:93]
	v_mfma_f32_16x16x32_bf16 v[78:81], v[134:137], v[216:219], v[78:81]
	v_mfma_f32_16x16x32_bf16 v[74:77], v[142:145], v[216:219], v[74:77]
	v_mfma_f32_16x16x32_bf16 v[118:121], v[164:167], v[180:183], v[118:121]
	v_mfma_f32_16x16x32_bf16 v[114:117], v[172:175], v[180:183], v[114:117]
	v_mfma_f32_16x16x32_bf16 v[102:105], v[164:167], v[196:199], v[102:105]
	v_mfma_f32_16x16x32_bf16 v[98:101], v[172:175], v[196:199], v[98:101]
	v_mfma_f32_16x16x32_bf16 v[86:89], v[164:167], v[204:207], v[86:89]
	v_mfma_f32_16x16x32_bf16 v[82:85], v[172:175], v[204:207], v[82:85]
	v_mfma_f32_16x16x32_bf16 v[70:73], v[164:167], v[212:215], v[70:73]
	v_mfma_f32_16x16x32_bf16 v[66:69], v[172:175], v[212:215], v[66:69]
	v_mfma_f32_16x16x32_bf16 v[118:121], v[168:171], v[192:195], v[118:121]
	v_mfma_f32_16x16x32_bf16 v[114:117], v[176:179], v[192:195], v[114:117]
	v_mfma_f32_16x16x32_bf16 v[102:105], v[168:171], v[200:203], v[102:105]
	v_mfma_f32_16x16x32_bf16 v[98:101], v[176:179], v[200:203], v[98:101]
	v_mfma_f32_16x16x32_bf16 v[86:89], v[168:171], v[208:211], v[86:89]
	v_mfma_f32_16x16x32_bf16 v[82:85], v[176:179], v[208:211], v[82:85]
	v_mfma_f32_16x16x32_bf16 v[70:73], v[168:171], v[216:219], v[70:73]
	v_mfma_f32_16x16x32_bf16 v[66:69], v[176:179], v[216:219], v[66:69]
	s_barrier
; #define PG8_STAGE(bufoff, gbase, voff) do { _Pragma("unroll") for (int _i = 0; _i < 2; ++_i) \
;         __builtin_amdgcn_global_load_lds((const unsigned*)((const char*)(gbase) + (voff)[_i]), (PG8_LAS unsigned*)(lds + (bufoff) + ldsw + _i * 8192), 16, 0, 0); } while (0)
; #define PG8_LDA(dst, b, h) do { _Pragma("unroll") for (int m = 0; m < 4; ++m) _Pragma("unroll") for (int k = 0; k < 2; ++k) dst[m][k] = *(const PG8_LAS bf16x8*)(lds + PG8_SA(b, h) + aoff + m * 2048 + k * 1024); } while (0)
; #define PG8_MMA(ai, bj, At, Bt) do { __builtin_amdgcn_s_setprio(1); _Pragma("unroll") for (int m = 0; m < 4; ++m) _Pragma("unroll") for (int n = 0; n < 2; ++n) _Pragma("unroll") for (int k = 0; k < 2; ++k) \
;         acc[ai][bj][m][n] = __builtin_amdgcn_mfma_f32_16x16x32_bf16(Bt[n][k], At[m][k], acc[ai][bj][m][n], 0, 0, 0); __builtin_amdgcn_s_setprio(0); } while (0)
; #define PG8_WAIT_V(n) asm volatile("s_waitcnt vmcnt(" #n ")" ::: "memory")
; #define PG8_WAIT_L(n) asm volatile("s_waitcnt lgkmcnt(" #n ")" ::: "memory")
; #define PG8_BAR __builtin_amdgcn_s_barrier()
; #define PG8_SCHED __builtin_amdgcn_sched_barrier(0)
; template <class Epi, class Sched, bool ALIGN_EPI = false, bool SP2 = false>
; __device__ __forceinline__ void gemm_phase(PG8_LAS unsigned char* lds, const Gemm g, const Sched& S, const Epi& E) {
;     ...
;             PG8_LDA(At, 1, 1); PG8_STAGE(PG8_SB(1, 0), b3, voffB); PG8_STAGE(PG8_SB(1, 1), b3 + hstepB, voffB); PG8_STAGE(PG8_SA(1, 0), a3, voffA);
;             PG8_WAIT_V(8); PG8_WAIT_L(0); PG8_BAR; PG8_MMA(1, 0, At, B0); PG8_MMA(1, 1, At, B1); PG8_BAR; PG8_SCHED;
;     ...
;         }
;         if constexpr (ALIGN_EPI) { if (wr == 0) PG8_BAR; }
	s_add_i32 s40, s58, s43
	v_lshl_add_u64 v[220:221], v[220:221], 0, s[22:23]
	s_mov_b32 m0, s40
	ds_read_b128 v[180:183], v188 offset:49152
	ds_read_b128 v[192:195], v188 offset:50176
	ds_read_b128 v[196:199], v188 offset:51200
	ds_read_b128 v[200:203], v188 offset:52224
	ds_read_b128 v[204:207], v188 offset:53248
	ds_read_b128 v[208:211], v188 offset:54272
	ds_read_b128 v[212:215], v188 offset:55296
	ds_read_b128 v[216:219], v188 offset:56320
	global_load_lds_dwordx4 v[220:221], off
	s_add_i32 m0, s40, 0x2000
	s_add_u32 s38, s38, 0x40080
	v_lshl_add_u64 v[220:221], v[222:223], 0, s[22:23]
	s_addc_u32 s39, s39, 0
	s_add_i32 s40, s59, s43
	global_load_lds_dwordx4 v[220:221], off
	v_lshl_add_u64 v[220:221], s[38:39], 0, v[148:149]
	s_mov_b32 m0, s40
	s_nop 0
	global_load_lds_dwordx4 v[220:221], off
	v_lshl_add_u64 v[220:221], s[38:39], 0, v[152:153]
	s_add_i32 m0, s40, 0x2000
	s_nop 0
	global_load_lds_dwordx4 v[220:221], off
	v_lshl_add_u64 v[220:221], v[224:225], 0, s[22:23]
	s_mov_b32 m0, s50
	s_nop 0
	global_load_lds_dwordx4 v[220:221], off
	v_lshl_add_u64 v[220:221], v[226:227], 0, s[22:23]
	s_mov_b32 m0, s51
	s_nop 0
	global_load_lds_dwordx4 v[220:221], off
	s_waitcnt vmcnt(8)
	s_waitcnt lgkmcnt(0)
	s_barrier
	s_waitcnt lgkmcnt(0)
	v_mfma_f32_16x16x32_bf16 v[62:65], v[130:133], v[180:183], v[62:65]
	v_mfma_f32_16x16x32_bf16 v[58:61], v[138:141], v[180:183], v[58:61]
	v_mfma_f32_16x16x32_bf16 v[46:49], v[130:133], v[196:199], v[46:49]
	v_mfma_f32_16x16x32_bf16 v[42:45], v[138:141], v[196:199], v[42:45]
	v_mfma_f32_16x16x32_bf16 v[30:33], v[130:133], v[204:207], v[30:33]
	v_mfma_f32_16x16x32_bf16 v[26:29], v[138:141], v[204:207], v[26:29]
	v_mfma_f32_16x16x32_bf16 v[14:17], v[130:133], v[212:215], v[14:17]
	v_mfma_f32_16x16x32_bf16 v[10:13], v[138:141], v[212:215], v[10:13]
	v_mfma_f32_16x16x32_bf16 v[62:65], v[134:137], v[192:195], v[62:65]
	v_mfma_f32_16x16x32_bf16 v[58:61], v[142:145], v[192:195], v[58:61]
	v_mfma_f32_16x16x32_bf16 v[46:49], v[134:137], v[200:203], v[46:49]
	v_mfma_f32_16x16x32_bf16 v[42:45], v[142:145], v[200:203], v[42:45]
	v_mfma_f32_16x16x32_bf16 v[30:33], v[134:137], v[208:211], v[30:33]
	v_mfma_f32_16x16x32_bf16 v[26:29], v[142:145], v[208:211], v[26:29]
	v_mfma_f32_16x16x32_bf16 v[14:17], v[134:137], v[216:219], v[14:17]
	v_mfma_f32_16x16x32_bf16 v[10:13], v[142:145], v[216:219], v[10:13]
	v_mfma_f32_16x16x32_bf16 v[54:57], v[164:167], v[180:183], v[54:57]
	v_mfma_f32_16x16x32_bf16 v[50:53], v[172:175], v[180:183], v[50:53]
	v_mfma_f32_16x16x32_bf16 v[38:41], v[164:167], v[196:199], v[38:41]
	v_mfma_f32_16x16x32_bf16 v[34:37], v[172:175], v[196:199], v[34:37]
	v_mfma_f32_16x16x32_bf16 v[22:25], v[164:167], v[204:207], v[22:25]
	v_mfma_f32_16x16x32_bf16 v[18:21], v[172:175], v[204:207], v[18:21]
	v_mfma_f32_16x16x32_bf16 v[6:9], v[164:167], v[212:215], v[6:9]
	v_mfma_f32_16x16x32_bf16 v[2:5], v[172:175], v[212:215], v[2:5]
	v_mfma_f32_16x16x32_bf16 v[54:57], v[168:171], v[192:195], v[54:57]
	v_mfma_f32_16x16x32_bf16 v[50:53], v[176:179], v[192:195], v[50:53]
	v_mfma_f32_16x16x32_bf16 v[38:41], v[168:171], v[200:203], v[38:41]
	v_mfma_f32_16x16x32_bf16 v[34:37], v[176:179], v[200:203], v[34:37]
	v_mfma_f32_16x16x32_bf16 v[22:25], v[168:171], v[208:211], v[22:25]
	v_mfma_f32_16x16x32_bf16 v[18:21], v[176:179], v[208:211], v[18:21]
	v_mfma_f32_16x16x32_bf16 v[6:9], v[168:171], v[216:219], v[6:9]
	v_mfma_f32_16x16x32_bf16 v[2:5], v[176:179], v[216:219], v[2:5]
	s_barrier
	s_add_i32 s33, s33, 2
	s_add_u32 s36, s36, 0x100
	s_addc_u32 s37, s37, 0
	s_add_u32 s27, s27, 0x100
	s_addc_u32 s29, s29, 0
	s_cmp_gt_u32 s33, 13
	s_cbranch_scc0 .LBB0_903
	s_and_b64 vcc, exec, s[24:25]
	s_cbranch_vccz .LBB0_906
	s_barrier

; #define PG8_STAGE(bufoff, gbase, voff) do { _Pragma("unroll") for (int _i = 0; _i < 2; ++_i) \
;         __builtin_amdgcn_global_load_lds((const unsigned*)((const char*)(gbase) + (voff)[_i]), (PG8_LAS unsigned*)(lds + (bufoff) + ldsw + _i * 8192), 16, 0, 0); } while (0)
; #define PG8_LDA(dst, b, h) do { _Pragma("unroll") for (int m = 0; m < 4; ++m) _Pragma("unroll") for (int k = 0; k < 2; ++k) dst[m][k] = *(const PG8_LAS bf16x8*)(lds + PG8_SA(b, h) + aoff + m * 2048 + k * 1024); } while (0)
; #define PG8_LDB(dst, b, h) do { _Pragma("unroll") for (int n = 0; n < 2; ++n) _Pragma("unroll") for (int k = 0; k < 2; ++k) dst[n][k] = *(const PG8_LAS bf16x8*)(lds + PG8_SB(b, h) + boff + n * 2048 + k * 1024); } while (0)
; #define PG8_MMA(ai, bj, At, Bt) do { __builtin_amdgcn_s_setprio(1); _Pragma("unroll") for (int m = 0; m < 4; ++m) _Pragma("unroll") for (int n = 0; n < 2; ++n) _Pragma("unroll") for (int k = 0; k < 2; ++k) \
;         acc[ai][bj][m][n] = __builtin_amdgcn_mfma_f32_16x16x32_bf16(Bt[n][k], At[m][k], acc[ai][bj][m][n], 0, 0, 0); __builtin_amdgcn_s_setprio(0); } while (0)
; #define PG8_WAIT_V(n) asm volatile("s_waitcnt vmcnt(" #n ")" ::: "memory")
; #define PG8_BAR __builtin_amdgcn_s_barrier()
; template <class Epi, class Sched, bool ALIGN_EPI = false, bool SP2 = false>
; __device__ __forceinline__ void gemm_phase(PG8_LAS unsigned char* lds, const Gemm g, const Sched& S, const Epi& E) {
;     ...
;         for (int t = 0; t < nt; t += 2) {
;             const bool last = (t == nt - 2);
;             const char* a1 = cA + (size_t)(t + 1) * kstep;
;             const char* a2 = last ? nA : cA + (size_t)(t + 2) * kstep; const char* b2 = last ? nB : cB + (size_t)(t + 2) * kstep;
;             const char* a3 = a2 + kstep; const char* b3 = b2 + kstep;
;             if (last && has_next) S.a_ready(nxt);
;             if constexpr (SP2) {
;             PG8_LDB(B0, 0, 0); PG8_LDB(B1, 0, 1); PG8_SCHED; PG8_LDA(At, 0, 0); PG8_STAGE(PG8_SA(1, 1), a1 + hstepA, voffA);
;             PG8_WAIT_V(8); PG8_WAIT_L(0); PG8_BAR; PG8_MMA(0, 0, At, B0); PG8_MMA(0, 1, At, B1); PG8_BAR; PG8_SCHED;
;             PG8_LDA(At, 0, 1); PG8_STAGE(PG8_SB(0, 0), b2, voffB); PG8_STAGE(PG8_SB(0, 1), b2 + hstepB, voffB); PG8_STAGE(PG8_SA(0, 0), a2, voffA);
;             PG8_WAIT_V(8); PG8_WAIT_L(0); PG8_BAR; PG8_MMA(1, 0, At, B0); PG8_MMA(1, 1, At, B1); PG8_BAR; PG8_SCHED;
.LBB0_989:
	ds_read_b128 v[164:167], v157
	ds_read_b128 v[174:177], v157 offset:1024
	ds_read_b128 v[178:181], v157 offset:2048
	ds_read_b128 v[182:185], v157 offset:3072
	ds_read_b128 v[186:189], v159
	ds_read_b128 v[190:193], v159 offset:1024
	ds_read_b128 v[194:197], v159 offset:2048
	ds_read_b128 v[198:201], v159 offset:3072
	s_add_u32 s26, s24, 0xfffc0080
	s_addc_u32 s27, s25, -1
	s_cmp_eq_u32 s57, 12
	s_cselect_b32 s29, s1, s27
	s_cselect_b32 s28, s5, s26
	s_cselect_b32 s27, s17, s56
	s_cselect_b32 s26, s19, s55
	v_lshl_add_u64 v[154:155], s[24:25], 0, v[144:145]
	s_add_i32 m0, s38, 0xc000
	ds_read_b128 v[202:205], v161
	ds_read_b128 v[206:209], v161 offset:1024
	ds_read_b128 v[210:213], v161 offset:2048
	ds_read_b128 v[214:217], v161 offset:3072
	ds_read_b128 v[218:221], v161 offset:4096
	ds_read_b128 v[222:225], v161 offset:5120
	ds_read_b128 v[226:229], v161 offset:6144
	ds_read_b128 v[230:233], v161 offset:7168
	global_load_lds_dwordx4 v[154:155], off
	v_lshl_add_u64 v[154:155], s[24:25], 0, v[146:147]
	s_add_i32 m0, s38, 0xe000
	s_nop 0
	global_load_lds_dwordx4 v[154:155], off
	s_waitcnt vmcnt(8)
	s_waitcnt lgkmcnt(0)
	s_barrier
	s_waitcnt lgkmcnt(0)
	v_mfma_f32_16x16x32_bf16 v[126:129], v[164:167], v[202:205], v[126:129]
	v_mfma_f32_16x16x32_bf16 v[122:125], v[178:181], v[202:205], v[122:125]
	v_mfma_f32_16x16x32_bf16 v[110:113], v[164:167], v[210:213], v[110:113]
	v_mfma_f32_16x16x32_bf16 v[106:109], v[178:181], v[210:213], v[106:109]
	v_mfma_f32_16x16x32_bf16 v[94:97], v[164:167], v[218:221], v[94:97]
	v_mfma_f32_16x16x32_bf16 v[90:93], v[178:181], v[218:221], v[90:93]
	v_mfma_f32_16x16x32_bf16 v[78:81], v[164:167], v[226:229], v[78:81]
	v_mfma_f32_16x16x32_bf16 v[74:77], v[178:181], v[226:229], v[74:77]
	v_mfma_f32_16x16x32_bf16 v[126:129], v[174:177], v[206:209], v[126:129]
	v_mfma_f32_16x16x32_bf16 v[122:125], v[182:185], v[206:209], v[122:125]
	v_mfma_f32_16x16x32_bf16 v[110:113], v[174:177], v[214:217], v[110:113]
	v_mfma_f32_16x16x32_bf16 v[106:109], v[182:185], v[214:217], v[106:109]
	v_mfma_f32_16x16x32_bf16 v[94:97], v[174:177], v[222:225], v[94:97]
	v_mfma_f32_16x16x32_bf16 v[90:93], v[182:185], v[222:225], v[90:93]
	v_mfma_f32_16x16x32_bf16 v[78:81], v[174:177], v[230:233], v[78:81]
	v_mfma_f32_16x16x32_bf16 v[74:77], v[182:185], v[230:233], v[74:77]
	v_mfma_f32_16x16x32_bf16 v[118:121], v[186:189], v[202:205], v[118:121]
	v_mfma_f32_16x16x32_bf16 v[114:117], v[194:197], v[202:205], v[114:117]
	v_mfma_f32_16x16x32_bf16 v[102:105], v[186:189], v[210:213], v[102:105]
	v_mfma_f32_16x16x32_bf16 v[98:101], v[194:197], v[210:213], v[98:101]
	v_mfma_f32_16x16x32_bf16 v[86:89], v[186:189], v[218:221], v[86:89]
	v_mfma_f32_16x16x32_bf16 v[82:85], v[194:197], v[218:221], v[82:85]
	v_mfma_f32_16x16x32_bf16 v[70:73], v[186:189], v[226:229], v[70:73]
	v_mfma_f32_16x16x32_bf16 v[66:69], v[194:197], v[226:229], v[66:69]
	v_mfma_f32_16x16x32_bf16 v[118:121], v[190:193], v[206:209], v[118:121]
	v_mfma_f32_16x16x32_bf16 v[114:117], v[198:201], v[206:209], v[114:117]
	v_mfma_f32_16x16x32_bf16 v[102:105], v[190:193], v[214:217], v[102:105]
	v_mfma_f32_16x16x32_bf16 v[98:101], v[198:201], v[214:217], v[98:101]
	v_mfma_f32_16x16x32_bf16 v[86:89], v[190:193], v[222:225], v[86:89]
	v_mfma_f32_16x16x32_bf16 v[82:85], v[198:201], v[222:225], v[82:85]
	v_mfma_f32_16x16x32_bf16 v[70:73], v[190:193], v[230:233], v[70:73]
	v_mfma_f32_16x16x32_bf16 v[66:69], v[198:201], v[230:233], v[66:69]
	s_barrier
	s_add_i32 s58, s49, s35
	v_lshl_add_u64 v[154:155], s[26:27], 0, v[134:135]
	s_mov_b32 m0, s58
	ds_read_b128 v[202:205], v161 offset:16384
	ds_read_b128 v[206:209], v161 offset:17408
	ds_read_b128 v[210:213], v161 offset:18432
	ds_read_b128 v[214:217], v161 offset:19456
	ds_read_b128 v[218:221], v161 offset:20480
	ds_read_b128 v[222:225], v161 offset:21504
	ds_read_b128 v[226:229], v161 offset:22528
	ds_read_b128 v[230:233], v161 offset:23552
	global_load_lds_dwordx4 v[154:155], off
	s_add_i32 m0, s58, 0x2000
	s_add_u32 s58, s26, 0x40000
	v_lshl_add_u64 v[168:169], s[26:27], 0, v[130:131]
	s_addc_u32 s59, s27, 0
	s_add_i32 s60, s50, s35
	global_load_lds_dwordx4 v[168:169], off
	v_lshl_add_u64 v[234:235], s[58:59], 0, v[134:135]
	s_mov_b32 m0, s60
	v_lshl_add_u64 v[236:237], s[28:29], 0, v[132:133]
	global_load_lds_dwordx4 v[234:235], off
	v_lshl_add_u64 v[234:235], s[58:59], 0, v[130:131]
	s_add_i32 m0, s60, 0x2000
	s_nop 0
	global_load_lds_dwordx4 v[234:235], off
	v_lshl_add_u64 v[234:235], s[28:29], 0, v[136:137]
	s_mov_b32 m0, s38
	s_nop 0
	global_load_lds_dwordx4 v[234:235], off
	s_mov_b32 m0, s39
	s_nop 0
	global_load_lds_dwordx4 v[236:237], off
	s_waitcnt vmcnt(8)
	s_waitcnt lgkmcnt(0)
	s_barrier
; #define PG8_STAGE(bufoff, gbase, voff) do { _Pragma("unroll") for (int _i = 0; _i < 2; ++_i) \
;         __builtin_amdgcn_global_load_lds((const unsigned*)((const char*)(gbase) + (voff)[_i]), (PG8_LAS unsigned*)(lds + (bufoff) + ldsw + _i * 8192), 16, 0, 0); } while (0)
; #define PG8_LDA(dst, b, h) do { _Pragma("unroll") for (int m = 0; m < 4; ++m) _Pragma("unroll") for (int k = 0; k < 2; ++k) dst[m][k] = *(const PG8_LAS bf16x8*)(lds + PG8_SA(b, h) + aoff + m * 2048 + k * 1024); } while (0)
; #define PG8_LDB(dst, b, h) do { _Pragma("unroll") for (int n = 0; n < 2; ++n) _Pragma("unroll") for (int k = 0; k < 2; ++k) dst[n][k] = *(const PG8_LAS bf16x8*)(lds + PG8_SB(b, h) + boff + n * 2048 + k * 1024); } while (0)
; #define PG8_MMA(ai, bj, At, Bt) do { __builtin_amdgcn_s_setprio(1); _Pragma("unroll") for (int m = 0; m < 4; ++m) _Pragma("unroll") for (int n = 0; n < 2; ++n) _Pragma("unroll") for (int k = 0; k < 2; ++k) \
;         acc[ai][bj][m][n] = __builtin_amdgcn_mfma_f32_16x16x32_bf16(Bt[n][k], At[m][k], acc[ai][bj][m][n], 0, 0, 0); __builtin_amdgcn_s_setprio(0); } while (0)
; #define PG8_WAIT_V(n) asm volatile("s_waitcnt vmcnt(" #n ")" ::: "memory")
; #define PG8_WAIT_L(n) asm volatile("s_waitcnt lgkmcnt(" #n ")" ::: "memory")
; #define PG8_BAR __builtin_amdgcn_s_barrier()
; #define PG8_SCHED __builtin_amdgcn_sched_barrier(0)
; template <class Epi, class Sched, bool ALIGN_EPI = false, bool SP2 = false>
; __device__ __forceinline__ void gemm_phase(PG8_LAS unsigned char* lds, const Gemm g, const Sched& S, const Epi& E) {
;     ...
;             PG8_WAIT_V(8); PG8_WAIT_L(0); PG8_BAR; PG8_MMA(1, 0, At, B0); PG8_MMA(1, 1, At, B1); PG8_BAR; PG8_SCHED;
;             PG8_LDB(B0, 1, 0); PG8_LDB(B1, 1, 1); PG8_SCHED; PG8_LDA(At, 1, 0); PG8_STAGE(PG8_SA(0, 1), a2 + hstepA, voffA);
;             PG8_WAIT_V(8); PG8_WAIT_L(0); PG8_BAR; PG8_MMA(0, 0, At, B0); PG8_MMA(0, 1, At, B1); PG8_BAR; PG8_SCHED;
	s_waitcnt lgkmcnt(0)
	v_mfma_f32_16x16x32_bf16 v[62:65], v[164:167], v[202:205], v[62:65]
	v_mfma_f32_16x16x32_bf16 v[58:61], v[178:181], v[202:205], v[58:61]
	v_mfma_f32_16x16x32_bf16 v[46:49], v[164:167], v[210:213], v[46:49]
	v_mfma_f32_16x16x32_bf16 v[42:45], v[178:181], v[210:213], v[42:45]
	v_mfma_f32_16x16x32_bf16 v[30:33], v[164:167], v[218:221], v[30:33]
	v_mfma_f32_16x16x32_bf16 v[26:29], v[178:181], v[218:221], v[26:29]
	v_mfma_f32_16x16x32_bf16 v[14:17], v[164:167], v[226:229], v[14:17]
	v_mfma_f32_16x16x32_bf16 v[10:13], v[178:181], v[226:229], v[10:13]
	v_mfma_f32_16x16x32_bf16 v[62:65], v[174:177], v[206:209], v[62:65]
	v_mfma_f32_16x16x32_bf16 v[58:61], v[182:185], v[206:209], v[58:61]
	v_mfma_f32_16x16x32_bf16 v[46:49], v[174:177], v[214:217], v[46:49]
	v_mfma_f32_16x16x32_bf16 v[42:45], v[182:185], v[214:217], v[42:45]
	v_mfma_f32_16x16x32_bf16 v[30:33], v[174:177], v[222:225], v[30:33]
	v_mfma_f32_16x16x32_bf16 v[26:29], v[182:185], v[222:225], v[26:29]
	v_mfma_f32_16x16x32_bf16 v[14:17], v[174:177], v[230:233], v[14:17]
	v_mfma_f32_16x16x32_bf16 v[10:13], v[182:185], v[230:233], v[10:13]
	v_mfma_f32_16x16x32_bf16 v[54:57], v[186:189], v[202:205], v[54:57]
	v_mfma_f32_16x16x32_bf16 v[50:53], v[194:197], v[202:205], v[50:53]
	v_mfma_f32_16x16x32_bf16 v[38:41], v[186:189], v[210:213], v[38:41]
	v_mfma_f32_16x16x32_bf16 v[34:37], v[194:197], v[210:213], v[34:37]
	v_mfma_f32_16x16x32_bf16 v[22:25], v[186:189], v[218:221], v[22:25]
	v_mfma_f32_16x16x32_bf16 v[18:21], v[194:197], v[218:221], v[18:21]
	v_mfma_f32_16x16x32_bf16 v[6:9], v[186:189], v[226:229], v[6:9]
	v_mfma_f32_16x16x32_bf16 v[2:5], v[194:197], v[226:229], v[2:5]
	v_mfma_f32_16x16x32_bf16 v[54:57], v[190:193], v[206:209], v[54:57]
	v_mfma_f32_16x16x32_bf16 v[50:53], v[198:201], v[206:209], v[50:53]
	v_mfma_f32_16x16x32_bf16 v[38:41], v[190:193], v[214:217], v[38:41]
	v_mfma_f32_16x16x32_bf16 v[34:37], v[198:201], v[214:217], v[34:37]
	v_mfma_f32_16x16x32_bf16 v[22:25], v[190:193], v[222:225], v[22:25]
	v_mfma_f32_16x16x32_bf16 v[18:21], v[198:201], v[222:225], v[18:21]
	v_mfma_f32_16x16x32_bf16 v[6:9], v[190:193], v[230:233], v[6:9]
	v_mfma_f32_16x16x32_bf16 v[2:5], v[198:201], v[230:233], v[2:5]
	s_barrier
	s_add_i32 s58, 0, 0x18000
	v_add_u32_e32 v138, s58, v141
	s_add_i32 s59, 0, 0x1c000
	ds_read_b128 v[164:167], v138
	ds_read_b128 v[174:177], v138 offset:1024
	ds_read_b128 v[178:181], v138 offset:2048
	ds_read_b128 v[182:185], v138 offset:3072
	v_add_u32_e32 v138, s59, v141
	ds_read_b128 v[186:189], v138
	ds_read_b128 v[190:193], v138 offset:1024
	ds_read_b128 v[194:197], v138 offset:2048
	ds_read_b128 v[198:201], v138 offset:3072
	s_add_u32 s28, s28, 0x40000
	s_addc_u32 s29, s29, 0
	s_mov_b32 m0, s40
	v_lshl_add_u64 v[238:239], s[28:29], 0, v[136:137]
	ds_read_b128 v[202:205], v161 offset:32768
	ds_read_b128 v[206:209], v161 offset:33792
	ds_read_b128 v[210:213], v161 offset:34816
	ds_read_b128 v[214:217], v161 offset:35840
	ds_read_b128 v[218:221], v161 offset:36864
	ds_read_b128 v[222:225], v161 offset:37888
	ds_read_b128 v[226:229], v161 offset:38912
	ds_read_b128 v[230:233], v161 offset:39936
	global_load_lds_dwordx4 v[238:239], off
	v_lshl_add_u64 v[238:239], s[28:29], 0, v[132:133]
	s_mov_b32 m0, s41
	s_nop 0
	global_load_lds_dwordx4 v[238:239], off
	s_waitcnt vmcnt(8)
	s_waitcnt lgkmcnt(0)
	s_barrier
	s_waitcnt lgkmcnt(0)
	v_mfma_f32_16x16x32_bf16 v[126:129], v[164:167], v[202:205], v[126:129]
	v_mfma_f32_16x16x32_bf16 v[122:125], v[178:181], v[202:205], v[122:125]
	v_mfma_f32_16x16x32_bf16 v[110:113], v[164:167], v[210:213], v[110:113]
	v_mfma_f32_16x16x32_bf16 v[106:109], v[178:181], v[210:213], v[106:109]
	v_mfma_f32_16x16x32_bf16 v[94:97], v[164:167], v[218:221], v[94:97]
	v_mfma_f32_16x16x32_bf16 v[90:93], v[178:181], v[218:221], v[90:93]
	v_mfma_f32_16x16x32_bf16 v[78:81], v[164:167], v[226:229], v[78:81]
	v_mfma_f32_16x16x32_bf16 v[74:77], v[178:181], v[226:229], v[74:77]
	v_mfma_f32_16x16x32_bf16 v[126:129], v[174:177], v[206:209], v[126:129]
	v_mfma_f32_16x16x32_bf16 v[122:125], v[182:185], v[206:209], v[122:125]
	v_mfma_f32_16x16x32_bf16 v[110:113], v[174:177], v[214:217], v[110:113]
	v_mfma_f32_16x16x32_bf16 v[106:109], v[182:185], v[214:217], v[106:109]
	v_mfma_f32_16x16x32_bf16 v[94:97], v[174:177], v[222:225], v[94:97]
	v_mfma_f32_16x16x32_bf16 v[90:93], v[182:185], v[222:225], v[90:93]
	v_mfma_f32_16x16x32_bf16 v[78:81], v[174:177], v[230:233], v[78:81]
	v_mfma_f32_16x16x32_bf16 v[74:77], v[182:185], v[230:233], v[74:77]
	v_mfma_f32_16x16x32_bf16 v[118:121], v[186:189], v[202:205], v[118:121]
	v_mfma_f32_16x16x32_bf16 v[114:117], v[194:197], v[202:205], v[114:117]
	v_mfma_f32_16x16x32_bf16 v[102:105], v[186:189], v[210:213], v[102:105]
	v_mfma_f32_16x16x32_bf16 v[98:101], v[194:197], v[210:213], v[98:101]
	v_mfma_f32_16x16x32_bf16 v[86:89], v[186:189], v[218:221], v[86:89]
	v_mfma_f32_16x16x32_bf16 v[82:85], v[194:197], v[218:221], v[82:85]
	v_mfma_f32_16x16x32_bf16 v[70:73], v[186:189], v[226:229], v[70:73]
	v_mfma_f32_16x16x32_bf16 v[66:69], v[194:197], v[226:229], v[66:69]
	v_mfma_f32_16x16x32_bf16 v[118:121], v[190:193], v[206:209], v[118:121]
	v_mfma_f32_16x16x32_bf16 v[114:117], v[198:201], v[206:209], v[114:117]
	v_mfma_f32_16x16x32_bf16 v[102:105], v[190:193], v[214:217], v[102:105]
	v_mfma_f32_16x16x32_bf16 v[98:101], v[198:201], v[214:217], v[98:101]
	v_mfma_f32_16x16x32_bf16 v[86:89], v[190:193], v[222:225], v[86:89]
	v_mfma_f32_16x16x32_bf16 v[82:85], v[198:201], v[222:225], v[82:85]
	v_mfma_f32_16x16x32_bf16 v[70:73], v[190:193], v[230:233], v[70:73]
	v_mfma_f32_16x16x32_bf16 v[66:69], v[198:201], v[230:233], v[66:69]
	s_barrier
; #define PG8_STAGE(bufoff, gbase, voff) do { _Pragma("unroll") for (int _i = 0; _i < 2; ++_i) \
;         __builtin_amdgcn_global_load_lds((const unsigned*)((const char*)(gbase) + (voff)[_i]), (PG8_LAS unsigned*)(lds + (bufoff) + ldsw + _i * 8192), 16, 0, 0); } while (0)
; #define PG8_LDA(dst, b, h) do { _Pragma("unroll") for (int m = 0; m < 4; ++m) _Pragma("unroll") for (int k = 0; k < 2; ++k) dst[m][k] = *(const PG8_LAS bf16x8*)(lds + PG8_SA(b, h) + aoff + m * 2048 + k * 1024); } while (0)
; #define PG8_MMA(ai, bj, At, Bt) do { __builtin_amdgcn_s_setprio(1); _Pragma("unroll") for (int m = 0; m < 4; ++m) _Pragma("unroll") for (int n = 0; n < 2; ++n) _Pragma("unroll") for (int k = 0; k < 2; ++k) \
;         acc[ai][bj][m][n] = __builtin_amdgcn_mfma_f32_16x16x32_bf16(Bt[n][k], At[m][k], acc[ai][bj][m][n], 0, 0, 0); __builtin_amdgcn_s_setprio(0); } while (0)
; #define PG8_WAIT_V(n) asm volatile("s_waitcnt vmcnt(" #n ")" ::: "memory")
; #define PG8_WAIT_L(n) asm volatile("s_waitcnt lgkmcnt(" #n ")" ::: "memory")
; #define PG8_BAR __builtin_amdgcn_s_barrier()
; #define PG8_SCHED __builtin_amdgcn_sched_barrier(0)
; template <class Epi, class Sched, bool ALIGN_EPI = false, bool SP2 = false>
; __device__ __forceinline__ void gemm_phase(PG8_LAS unsigned char* lds, const Gemm g, const Sched& S, const Epi& E) {
;     ...
;             PG8_LDA(At, 1, 1); PG8_STAGE(PG8_SB(1, 0), b3, voffB); PG8_STAGE(PG8_SB(1, 1), b3 + hstepB, voffB); PG8_STAGE(PG8_SA(1, 0), a3, voffA);
;             PG8_WAIT_V(8); PG8_WAIT_L(0); PG8_BAR; PG8_MMA(1, 0, At, B0); PG8_MMA(1, 1, At, B1); PG8_BAR; PG8_SCHED;
;     ...
;         }
;         if constexpr (ALIGN_EPI) { if (wr == 0) PG8_BAR; }
	s_add_i32 s28, s58, s35
	v_lshl_add_u64 v[154:155], v[154:155], 0, s[12:13]
	s_mov_b32 m0, s28
	ds_read_b128 v[202:205], v161 offset:49152
	ds_read_b128 v[206:209], v161 offset:50176
	ds_read_b128 v[210:213], v161 offset:51200
	ds_read_b128 v[214:217], v161 offset:52224
	ds_read_b128 v[218:221], v161 offset:53248
	ds_read_b128 v[222:225], v161 offset:54272
	ds_read_b128 v[226:229], v161 offset:55296
	ds_read_b128 v[230:233], v161 offset:56320
	global_load_lds_dwordx4 v[154:155], off
	s_add_i32 m0, s28, 0x2000
	s_add_u32 s26, s26, 0x40080
	v_lshl_add_u64 v[154:155], v[168:169], 0, s[12:13]
	s_addc_u32 s27, s27, 0
	s_add_i32 s28, s59, s35
	global_load_lds_dwordx4 v[154:155], off
	v_lshl_add_u64 v[154:155], s[26:27], 0, v[134:135]
	s_mov_b32 m0, s28
	s_nop 0
	global_load_lds_dwordx4 v[154:155], off
	v_lshl_add_u64 v[154:155], s[26:27], 0, v[130:131]
	s_add_i32 m0, s28, 0x2000
	s_nop 0
	global_load_lds_dwordx4 v[154:155], off
	v_lshl_add_u64 v[154:155], v[234:235], 0, s[12:13]
	s_mov_b32 m0, s2
	s_nop 0
	global_load_lds_dwordx4 v[154:155], off
	v_lshl_add_u64 v[154:155], v[236:237], 0, s[12:13]
	s_mov_b32 m0, s33
	s_nop 0
	global_load_lds_dwordx4 v[154:155], off
	s_waitcnt vmcnt(8)
	s_waitcnt lgkmcnt(0)
	s_barrier
	s_waitcnt lgkmcnt(0)
	v_mfma_f32_16x16x32_bf16 v[62:65], v[164:167], v[202:205], v[62:65]
	v_mfma_f32_16x16x32_bf16 v[58:61], v[178:181], v[202:205], v[58:61]
	v_mfma_f32_16x16x32_bf16 v[46:49], v[164:167], v[210:213], v[46:49]
	v_mfma_f32_16x16x32_bf16 v[42:45], v[178:181], v[210:213], v[42:45]
	v_mfma_f32_16x16x32_bf16 v[30:33], v[164:167], v[218:221], v[30:33]
	v_mfma_f32_16x16x32_bf16 v[26:29], v[178:181], v[218:221], v[26:29]
	v_mfma_f32_16x16x32_bf16 v[14:17], v[164:167], v[226:229], v[14:17]
	v_mfma_f32_16x16x32_bf16 v[10:13], v[178:181], v[226:229], v[10:13]
	v_mfma_f32_16x16x32_bf16 v[62:65], v[174:177], v[206:209], v[62:65]
	v_mfma_f32_16x16x32_bf16 v[58:61], v[182:185], v[206:209], v[58:61]
	v_mfma_f32_16x16x32_bf16 v[46:49], v[174:177], v[214:217], v[46:49]
	v_mfma_f32_16x16x32_bf16 v[42:45], v[182:185], v[214:217], v[42:45]
	v_mfma_f32_16x16x32_bf16 v[30:33], v[174:177], v[222:225], v[30:33]
	v_mfma_f32_16x16x32_bf16 v[26:29], v[182:185], v[222:225], v[26:29]
	v_mfma_f32_16x16x32_bf16 v[14:17], v[174:177], v[230:233], v[14:17]
	v_mfma_f32_16x16x32_bf16 v[10:13], v[182:185], v[230:233], v[10:13]
	v_mfma_f32_16x16x32_bf16 v[54:57], v[186:189], v[202:205], v[54:57]
	v_mfma_f32_16x16x32_bf16 v[50:53], v[194:197], v[202:205], v[50:53]
	v_mfma_f32_16x16x32_bf16 v[38:41], v[186:189], v[210:213], v[38:41]
	v_mfma_f32_16x16x32_bf16 v[34:37], v[194:197], v[210:213], v[34:37]
	v_mfma_f32_16x16x32_bf16 v[22:25], v[186:189], v[218:221], v[22:25]
	v_mfma_f32_16x16x32_bf16 v[18:21], v[194:197], v[218:221], v[18:21]
	v_mfma_f32_16x16x32_bf16 v[6:9], v[186:189], v[226:229], v[6:9]
	v_mfma_f32_16x16x32_bf16 v[2:5], v[194:197], v[226:229], v[2:5]
	v_mfma_f32_16x16x32_bf16 v[54:57], v[190:193], v[206:209], v[54:57]
	v_mfma_f32_16x16x32_bf16 v[50:53], v[198:201], v[206:209], v[50:53]
	v_mfma_f32_16x16x32_bf16 v[38:41], v[190:193], v[214:217], v[38:41]
	v_mfma_f32_16x16x32_bf16 v[34:37], v[198:201], v[214:217], v[34:37]
	v_mfma_f32_16x16x32_bf16 v[22:25], v[190:193], v[222:225], v[22:25]
	v_mfma_f32_16x16x32_bf16 v[18:21], v[198:201], v[222:225], v[18:21]
	v_mfma_f32_16x16x32_bf16 v[6:9], v[190:193], v[230:233], v[6:9]
	v_mfma_f32_16x16x32_bf16 v[2:5], v[198:201], v[230:233], v[2:5]
	s_barrier
	s_add_i32 s57, s57, 2
	s_add_u32 s24, s24, 0x100
	s_addc_u32 s25, s25, 0
	s_add_u32 s55, s55, 0x100
	s_addc_u32 s56, s56, 0
	s_cmp_gt_u32 s57, 13
	s_cbranch_scc0 .LBB0_989
	s_and_b64 vcc, exec, s[14:15]
	s_cbranch_vccz .LBB0_992
	s_barrier

; #define PG8_STAGE(bufoff, gbase, voff) do { _Pragma("unroll") for (int _i = 0; _i < 2; ++_i) \
;         __builtin_amdgcn_global_load_lds((const unsigned*)((const char*)(gbase) + (voff)[_i]), (PG8_LAS unsigned*)(lds + (bufoff) + ldsw + _i * 8192), 16, 0, 0); } while (0)
; #define PG8_LDA(dst, b, h) do { _Pragma("unroll") for (int m = 0; m < 4; ++m) _Pragma("unroll") for (int k = 0; k < 2; ++k) dst[m][k] = *(const PG8_LAS bf16x8*)(lds + PG8_SA(b, h) + aoff + m * 2048 + k * 1024); } while (0)
; #define PG8_LDB(dst, b, h) do { _Pragma("unroll") for (int n = 0; n < 2; ++n) _Pragma("unroll") for (int k = 0; k < 2; ++k) dst[n][k] = *(const PG8_LAS bf16x8*)(lds + PG8_SB(b, h) + boff + n * 2048 + k * 1024); } while (0)
; #define PG8_MMA(ai, bj, At, Bt) do { __builtin_amdgcn_s_setprio(1); _Pragma("unroll") for (int m = 0; m < 4; ++m) _Pragma("unroll") for (int n = 0; n < 2; ++n) _Pragma("unroll") for (int k = 0; k < 2; ++k) \
;         acc[ai][bj][m][n] = __builtin_amdgcn_mfma_f32_16x16x32_bf16(Bt[n][k], At[m][k], acc[ai][bj][m][n], 0, 0, 0); __builtin_amdgcn_s_setprio(0); } while (0)
; #define PG8_WAIT_V(n) asm volatile("s_waitcnt vmcnt(" #n ")" ::: "memory")
; #define PG8_BAR __builtin_amdgcn_s_barrier()
; template <class Epi, class Sched, bool ALIGN_EPI = false, bool SP2 = false>
; __device__ __forceinline__ void gemm_phase(PG8_LAS unsigned char* lds, const Gemm g, const Sched& S, const Epi& E) {
;     ...
;         for (int t = 0; t < nt; t += 2) {
;             const bool last = (t == nt - 2);
;             const char* a1 = cA + (size_t)(t + 1) * kstep;
;             const char* a2 = last ? nA : cA + (size_t)(t + 2) * kstep; const char* b2 = last ? nB : cB + (size_t)(t + 2) * kstep;
;             const char* a3 = a2 + kstep; const char* b3 = b2 + kstep;
;             if (last && has_next) S.a_ready(nxt);
;             if constexpr (SP2) {
;             PG8_LDB(B0, 0, 0); PG8_LDB(B1, 0, 1); PG8_SCHED; PG8_LDA(At, 0, 0); PG8_STAGE(PG8_SA(1, 1), a1 + hstepA, voffA);
;             PG8_WAIT_V(8); PG8_WAIT_L(0); PG8_BAR; PG8_MMA(0, 0, At, B0); PG8_MMA(0, 1, At, B1); PG8_BAR; PG8_SCHED;
;             PG8_LDA(At, 0, 1); PG8_STAGE(PG8_SB(0, 0), b2, voffB); PG8_STAGE(PG8_SB(0, 1), b2 + hstepB, voffB); PG8_STAGE(PG8_SA(0, 0), a2, voffA);
;             PG8_WAIT_V(8); PG8_WAIT_L(0); PG8_BAR; PG8_MMA(1, 0, At, B0); PG8_MMA(1, 1, At, B1); PG8_BAR; PG8_SCHED;
.LBB0_1467:
	ds_read_b128 v[130:133], v164
	ds_read_b128 v[134:137], v164 offset:1024
	ds_read_b128 v[154:157], v164 offset:2048
	ds_read_b128 v[158:161], v164 offset:3072
	ds_read_b128 v[168:171], v165
	ds_read_b128 v[172:175], v165 offset:1024
	ds_read_b128 v[176:179], v165 offset:2048
	ds_read_b128 v[180:183], v165 offset:3072
	s_add_u32 s34, s30, 0xfffc0080
	s_addc_u32 s35, s31, -1
	s_cmp_eq_u32 s54, 12
	s_cselect_b32 s37, s23, s35
	s_cselect_b32 s36, s29, s34
	s_cselect_b32 s35, s21, s53
	s_cselect_b32 s34, s51, s52
	v_lshl_add_u64 v[216:217], s[30:31], 0, v[146:147]
	s_add_i32 m0, s1, 0xc000
	ds_read_b128 v[184:187], v166
	ds_read_b128 v[188:191], v166 offset:1024
	ds_read_b128 v[192:195], v166 offset:2048
	ds_read_b128 v[196:199], v166 offset:3072
	ds_read_b128 v[200:203], v166 offset:4096
	ds_read_b128 v[204:207], v166 offset:5120
	ds_read_b128 v[208:211], v166 offset:6144
	ds_read_b128 v[212:215], v166 offset:7168
	global_load_lds_dwordx4 v[216:217], off
	v_lshl_add_u64 v[216:217], s[30:31], 0, v[148:149]
	s_add_i32 m0, s1, 0xe000
	s_nop 0
	global_load_lds_dwordx4 v[216:217], off
	s_waitcnt vmcnt(8)
	s_waitcnt lgkmcnt(0)
	s_barrier
	s_waitcnt lgkmcnt(0)
	v_mfma_f32_16x16x32_bf16 v[126:129], v[130:133], v[184:187], v[126:129]
	v_mfma_f32_16x16x32_bf16 v[122:125], v[154:157], v[184:187], v[122:125]
	v_mfma_f32_16x16x32_bf16 v[110:113], v[130:133], v[192:195], v[110:113]
	v_mfma_f32_16x16x32_bf16 v[106:109], v[154:157], v[192:195], v[106:109]
	v_mfma_f32_16x16x32_bf16 v[94:97], v[130:133], v[200:203], v[94:97]
	v_mfma_f32_16x16x32_bf16 v[90:93], v[154:157], v[200:203], v[90:93]
	v_mfma_f32_16x16x32_bf16 v[78:81], v[130:133], v[208:211], v[78:81]
	v_mfma_f32_16x16x32_bf16 v[74:77], v[154:157], v[208:211], v[74:77]
	v_mfma_f32_16x16x32_bf16 v[126:129], v[134:137], v[188:191], v[126:129]
	v_mfma_f32_16x16x32_bf16 v[122:125], v[158:161], v[188:191], v[122:125]
	v_mfma_f32_16x16x32_bf16 v[110:113], v[134:137], v[196:199], v[110:113]
	v_mfma_f32_16x16x32_bf16 v[106:109], v[158:161], v[196:199], v[106:109]
	v_mfma_f32_16x16x32_bf16 v[94:97], v[134:137], v[204:207], v[94:97]
	v_mfma_f32_16x16x32_bf16 v[90:93], v[158:161], v[204:207], v[90:93]
	v_mfma_f32_16x16x32_bf16 v[78:81], v[134:137], v[212:215], v[78:81]
	v_mfma_f32_16x16x32_bf16 v[74:77], v[158:161], v[212:215], v[74:77]
	v_mfma_f32_16x16x32_bf16 v[118:121], v[168:171], v[184:187], v[118:121]
	v_mfma_f32_16x16x32_bf16 v[114:117], v[176:179], v[184:187], v[114:117]
	v_mfma_f32_16x16x32_bf16 v[102:105], v[168:171], v[192:195], v[102:105]
	v_mfma_f32_16x16x32_bf16 v[98:101], v[176:179], v[192:195], v[98:101]
	v_mfma_f32_16x16x32_bf16 v[86:89], v[168:171], v[200:203], v[86:89]
	v_mfma_f32_16x16x32_bf16 v[82:85], v[176:179], v[200:203], v[82:85]
	v_mfma_f32_16x16x32_bf16 v[70:73], v[168:171], v[208:211], v[70:73]
	v_mfma_f32_16x16x32_bf16 v[66:69], v[176:179], v[208:211], v[66:69]
	v_mfma_f32_16x16x32_bf16 v[118:121], v[172:175], v[188:191], v[118:121]
	v_mfma_f32_16x16x32_bf16 v[114:117], v[180:183], v[188:191], v[114:117]
	v_mfma_f32_16x16x32_bf16 v[102:105], v[172:175], v[196:199], v[102:105]
	v_mfma_f32_16x16x32_bf16 v[98:101], v[180:183], v[196:199], v[98:101]
	v_mfma_f32_16x16x32_bf16 v[86:89], v[172:175], v[204:207], v[86:89]
	v_mfma_f32_16x16x32_bf16 v[82:85], v[180:183], v[204:207], v[82:85]
	v_mfma_f32_16x16x32_bf16 v[70:73], v[172:175], v[212:215], v[70:73]
	v_mfma_f32_16x16x32_bf16 v[66:69], v[180:183], v[212:215], v[66:69]
	s_barrier
	s_add_i32 s55, s48, s0
	v_lshl_add_u64 v[216:217], s[34:35], 0, v[140:141]
	s_mov_b32 m0, s55
	ds_read_b128 v[184:187], v166 offset:16384
	ds_read_b128 v[188:191], v166 offset:17408
	ds_read_b128 v[192:195], v166 offset:18432
	ds_read_b128 v[196:199], v166 offset:19456
	ds_read_b128 v[200:203], v166 offset:20480
	ds_read_b128 v[204:207], v166 offset:21504
	ds_read_b128 v[208:211], v166 offset:22528
	ds_read_b128 v[212:215], v166 offset:23552
	global_load_lds_dwordx4 v[216:217], off
	s_add_i32 m0, s55, 0x2000
	s_add_u32 s56, s34, 0x40000
	v_lshl_add_u64 v[218:219], s[34:35], 0, v[144:145]
	s_addc_u32 s57, s35, 0
	s_add_i32 s55, s49, s0
	global_load_lds_dwordx4 v[218:219], off
	v_lshl_add_u64 v[220:221], s[56:57], 0, v[140:141]
	s_mov_b32 m0, s55
	v_lshl_add_u64 v[222:223], s[36:37], 0, v[142:143]
	global_load_lds_dwordx4 v[220:221], off
	v_lshl_add_u64 v[220:221], s[56:57], 0, v[144:145]
	s_add_i32 m0, s55, 0x2000
	s_nop 0
	global_load_lds_dwordx4 v[220:221], off
	v_lshl_add_u64 v[220:221], s[36:37], 0, v[138:139]
	s_mov_b32 m0, s1
	s_nop 0
	global_load_lds_dwordx4 v[220:221], off
	s_mov_b32 m0, s39
	s_nop 0
	global_load_lds_dwordx4 v[222:223], off
	s_waitcnt vmcnt(8)
	s_waitcnt lgkmcnt(0)
	s_barrier
; #define PG8_STAGE(bufoff, gbase, voff) do { _Pragma("unroll") for (int _i = 0; _i < 2; ++_i) \
;         __builtin_amdgcn_global_load_lds((const unsigned*)((const char*)(gbase) + (voff)[_i]), (PG8_LAS unsigned*)(lds + (bufoff) + ldsw + _i * 8192), 16, 0, 0); } while (0)
; #define PG8_LDA(dst, b, h) do { _Pragma("unroll") for (int m = 0; m < 4; ++m) _Pragma("unroll") for (int k = 0; k < 2; ++k) dst[m][k] = *(const PG8_LAS bf16x8*)(lds + PG8_SA(b, h) + aoff + m * 2048 + k * 1024); } while (0)
; #define PG8_LDB(dst, b, h) do { _Pragma("unroll") for (int n = 0; n < 2; ++n) _Pragma("unroll") for (int k = 0; k < 2; ++k) dst[n][k] = *(const PG8_LAS bf16x8*)(lds + PG8_SB(b, h) + boff + n * 2048 + k * 1024); } while (0)
; #define PG8_MMA(ai, bj, At, Bt) do { __builtin_amdgcn_s_setprio(1); _Pragma("unroll") for (int m = 0; m < 4; ++m) _Pragma("unroll") for (int n = 0; n < 2; ++n) _Pragma("unroll") for (int k = 0; k < 2; ++k) \
;         acc[ai][bj][m][n] = __builtin_amdgcn_mfma_f32_16x16x32_bf16(Bt[n][k], At[m][k], acc[ai][bj][m][n], 0, 0, 0); __builtin_amdgcn_s_setprio(0); } while (0)
; #define PG8_WAIT_V(n) asm volatile("s_waitcnt vmcnt(" #n ")" ::: "memory")
; #define PG8_WAIT_L(n) asm volatile("s_waitcnt lgkmcnt(" #n ")" ::: "memory")
; #define PG8_BAR __builtin_amdgcn_s_barrier()
; #define PG8_SCHED __builtin_amdgcn_sched_barrier(0)
; template <class Epi, class Sched, bool ALIGN_EPI = false, bool SP2 = false>
; __device__ __forceinline__ void gemm_phase(PG8_LAS unsigned char* lds, const Gemm g, const Sched& S, const Epi& E) {
;     ...
;             PG8_WAIT_V(8); PG8_WAIT_L(0); PG8_BAR; PG8_MMA(1, 0, At, B0); PG8_MMA(1, 1, At, B1); PG8_BAR; PG8_SCHED;
;             PG8_LDB(B0, 1, 0); PG8_LDB(B1, 1, 1); PG8_SCHED; PG8_LDA(At, 1, 0); PG8_STAGE(PG8_SA(0, 1), a2 + hstepA, voffA);
;             PG8_WAIT_V(8); PG8_WAIT_L(0); PG8_BAR; PG8_MMA(0, 0, At, B0); PG8_MMA(0, 1, At, B1); PG8_BAR; PG8_SCHED;
	s_waitcnt lgkmcnt(0)
	v_mfma_f32_16x16x32_bf16 v[62:65], v[130:133], v[184:187], v[62:65]
	v_mfma_f32_16x16x32_bf16 v[58:61], v[154:157], v[184:187], v[58:61]
	v_mfma_f32_16x16x32_bf16 v[46:49], v[130:133], v[192:195], v[46:49]
	v_mfma_f32_16x16x32_bf16 v[42:45], v[154:157], v[192:195], v[42:45]
	v_mfma_f32_16x16x32_bf16 v[30:33], v[130:133], v[200:203], v[30:33]
	v_mfma_f32_16x16x32_bf16 v[26:29], v[154:157], v[200:203], v[26:29]
	v_mfma_f32_16x16x32_bf16 v[14:17], v[130:133], v[208:211], v[14:17]
	v_mfma_f32_16x16x32_bf16 v[10:13], v[154:157], v[208:211], v[10:13]
	v_mfma_f32_16x16x32_bf16 v[62:65], v[134:137], v[188:191], v[62:65]
	v_mfma_f32_16x16x32_bf16 v[58:61], v[158:161], v[188:191], v[58:61]
	v_mfma_f32_16x16x32_bf16 v[46:49], v[134:137], v[196:199], v[46:49]
	v_mfma_f32_16x16x32_bf16 v[42:45], v[158:161], v[196:199], v[42:45]
	v_mfma_f32_16x16x32_bf16 v[30:33], v[134:137], v[204:207], v[30:33]
	v_mfma_f32_16x16x32_bf16 v[26:29], v[158:161], v[204:207], v[26:29]
	v_mfma_f32_16x16x32_bf16 v[14:17], v[134:137], v[212:215], v[14:17]
	v_mfma_f32_16x16x32_bf16 v[10:13], v[158:161], v[212:215], v[10:13]
	v_mfma_f32_16x16x32_bf16 v[54:57], v[168:171], v[184:187], v[54:57]
	v_mfma_f32_16x16x32_bf16 v[50:53], v[176:179], v[184:187], v[50:53]
	v_mfma_f32_16x16x32_bf16 v[38:41], v[168:171], v[192:195], v[38:41]
	v_mfma_f32_16x16x32_bf16 v[34:37], v[176:179], v[192:195], v[34:37]
	v_mfma_f32_16x16x32_bf16 v[22:25], v[168:171], v[200:203], v[22:25]
	v_mfma_f32_16x16x32_bf16 v[18:21], v[176:179], v[200:203], v[18:21]
	v_mfma_f32_16x16x32_bf16 v[6:9], v[168:171], v[208:211], v[6:9]
	v_mfma_f32_16x16x32_bf16 v[2:5], v[176:179], v[208:211], v[2:5]
	v_mfma_f32_16x16x32_bf16 v[54:57], v[172:175], v[188:191], v[54:57]
	v_mfma_f32_16x16x32_bf16 v[50:53], v[180:183], v[188:191], v[50:53]
	v_mfma_f32_16x16x32_bf16 v[38:41], v[172:175], v[196:199], v[38:41]
	v_mfma_f32_16x16x32_bf16 v[34:37], v[180:183], v[196:199], v[34:37]
	v_mfma_f32_16x16x32_bf16 v[22:25], v[172:175], v[204:207], v[22:25]
	v_mfma_f32_16x16x32_bf16 v[18:21], v[180:183], v[204:207], v[18:21]
	v_mfma_f32_16x16x32_bf16 v[6:9], v[172:175], v[212:215], v[6:9]
	v_mfma_f32_16x16x32_bf16 v[2:5], v[180:183], v[212:215], v[2:5]
	s_barrier
	s_add_i32 s55, 0, 0x18000
	s_add_i32 s56, 0, 0x1c000
	v_add_u32_e32 v158, s55, v162
	v_add_u32_e32 v180, s56, v162
	ds_read_b128 v[130:133], v158
	ds_read_b128 v[134:137], v158 offset:1024
	ds_read_b128 v[154:157], v158 offset:2048
	ds_read_b128 v[158:161], v158 offset:3072
	ds_read_b128 v[168:171], v180
	ds_read_b128 v[172:175], v180 offset:1024
	ds_read_b128 v[176:179], v180 offset:2048
	ds_read_b128 v[180:183], v180 offset:3072
	s_add_u32 s36, s36, 0x40000
	s_addc_u32 s37, s37, 0
	s_mov_b32 m0, s40
	v_lshl_add_u64 v[224:225], s[36:37], 0, v[138:139]
	ds_read_b128 v[184:187], v166 offset:32768
	ds_read_b128 v[188:191], v166 offset:33792
	ds_read_b128 v[192:195], v166 offset:34816
	ds_read_b128 v[196:199], v166 offset:35840
	ds_read_b128 v[200:203], v166 offset:36864
	ds_read_b128 v[204:207], v166 offset:37888
	ds_read_b128 v[208:211], v166 offset:38912
	ds_read_b128 v[212:215], v166 offset:39936
	global_load_lds_dwordx4 v[224:225], off
	v_lshl_add_u64 v[224:225], s[36:37], 0, v[142:143]
	s_mov_b32 m0, s41
	s_nop 0
	global_load_lds_dwordx4 v[224:225], off
	s_waitcnt vmcnt(8)
	s_waitcnt lgkmcnt(0)
	s_barrier
	s_waitcnt lgkmcnt(0)
	v_mfma_f32_16x16x32_bf16 v[126:129], v[130:133], v[184:187], v[126:129]
	v_mfma_f32_16x16x32_bf16 v[122:125], v[154:157], v[184:187], v[122:125]
	v_mfma_f32_16x16x32_bf16 v[110:113], v[130:133], v[192:195], v[110:113]
	v_mfma_f32_16x16x32_bf16 v[106:109], v[154:157], v[192:195], v[106:109]
	v_mfma_f32_16x16x32_bf16 v[94:97], v[130:133], v[200:203], v[94:97]
	v_mfma_f32_16x16x32_bf16 v[90:93], v[154:157], v[200:203], v[90:93]
	v_mfma_f32_16x16x32_bf16 v[78:81], v[130:133], v[208:211], v[78:81]
	v_mfma_f32_16x16x32_bf16 v[74:77], v[154:157], v[208:211], v[74:77]
	v_mfma_f32_16x16x32_bf16 v[126:129], v[134:137], v[188:191], v[126:129]
	v_mfma_f32_16x16x32_bf16 v[122:125], v[158:161], v[188:191], v[122:125]
	v_mfma_f32_16x16x32_bf16 v[110:113], v[134:137], v[196:199], v[110:113]
	v_mfma_f32_16x16x32_bf16 v[106:109], v[158:161], v[196:199], v[106:109]
	v_mfma_f32_16x16x32_bf16 v[94:97], v[134:137], v[204:207], v[94:97]
	v_mfma_f32_16x16x32_bf16 v[90:93], v[158:161], v[204:207], v[90:93]
	v_mfma_f32_16x16x32_bf16 v[78:81], v[134:137], v[212:215], v[78:81]
	v_mfma_f32_16x16x32_bf16 v[74:77], v[158:161], v[212:215], v[74:77]
	v_mfma_f32_16x16x32_bf16 v[118:121], v[168:171], v[184:187], v[118:121]
	v_mfma_f32_16x16x32_bf16 v[114:117], v[176:179], v[184:187], v[114:117]
	v_mfma_f32_16x16x32_bf16 v[102:105], v[168:171], v[192:195], v[102:105]
	v_mfma_f32_16x16x32_bf16 v[98:101], v[176:179], v[192:195], v[98:101]
	v_mfma_f32_16x16x32_bf16 v[86:89], v[168:171], v[200:203], v[86:89]
	v_mfma_f32_16x16x32_bf16 v[82:85], v[176:179], v[200:203], v[82:85]
	v_mfma_f32_16x16x32_bf16 v[70:73], v[168:171], v[208:211], v[70:73]
	v_mfma_f32_16x16x32_bf16 v[66:69], v[176:179], v[208:211], v[66:69]
	v_mfma_f32_16x16x32_bf16 v[118:121], v[172:175], v[188:191], v[118:121]
	v_mfma_f32_16x16x32_bf16 v[114:117], v[180:183], v[188:191], v[114:117]
	v_mfma_f32_16x16x32_bf16 v[102:105], v[172:175], v[196:199], v[102:105]
	v_mfma_f32_16x16x32_bf16 v[98:101], v[180:183], v[196:199], v[98:101]
	v_mfma_f32_16x16x32_bf16 v[86:89], v[172:175], v[204:207], v[86:89]
	v_mfma_f32_16x16x32_bf16 v[82:85], v[180:183], v[204:207], v[82:85]
	v_mfma_f32_16x16x32_bf16 v[70:73], v[172:175], v[212:215], v[70:73]
	v_mfma_f32_16x16x32_bf16 v[66:69], v[180:183], v[212:215], v[66:69]
	s_barrier
; #define PG8_STAGE(bufoff, gbase, voff) do { _Pragma("unroll") for (int _i = 0; _i < 2; ++_i) \
;         __builtin_amdgcn_global_load_lds((const unsigned*)((const char*)(gbase) + (voff)[_i]), (PG8_LAS unsigned*)(lds + (bufoff) + ldsw + _i * 8192), 16, 0, 0); } while (0)
; #define PG8_LDA(dst, b, h) do { _Pragma("unroll") for (int m = 0; m < 4; ++m) _Pragma("unroll") for (int k = 0; k < 2; ++k) dst[m][k] = *(const PG8_LAS bf16x8*)(lds + PG8_SA(b, h) + aoff + m * 2048 + k * 1024); } while (0)
; #define PG8_MMA(ai, bj, At, Bt) do { __builtin_amdgcn_s_setprio(1); _Pragma("unroll") for (int m = 0; m < 4; ++m) _Pragma("unroll") for (int n = 0; n < 2; ++n) _Pragma("unroll") for (int k = 0; k < 2; ++k) \
;         acc[ai][bj][m][n] = __builtin_amdgcn_mfma_f32_16x16x32_bf16(Bt[n][k], At[m][k], acc[ai][bj][m][n], 0, 0, 0); __builtin_amdgcn_s_setprio(0); } while (0)
; #define PG8_WAIT_V(n) asm volatile("s_waitcnt vmcnt(" #n ")" ::: "memory")
; #define PG8_WAIT_L(n) asm volatile("s_waitcnt lgkmcnt(" #n ")" ::: "memory")
; #define PG8_BAR __builtin_amdgcn_s_barrier()
; #define PG8_SCHED __builtin_amdgcn_sched_barrier(0)
; template <class Epi, class Sched, bool ALIGN_EPI = false, bool SP2 = false>
; __device__ __forceinline__ void gemm_phase(PG8_LAS unsigned char* lds, const Gemm g, const Sched& S, const Epi& E) {
;     ...
;             PG8_LDA(At, 1, 1); PG8_STAGE(PG8_SB(1, 0), b3, voffB); PG8_STAGE(PG8_SB(1, 1), b3 + hstepB, voffB); PG8_STAGE(PG8_SA(1, 0), a3, voffA);
;             PG8_WAIT_V(8); PG8_WAIT_L(0); PG8_BAR; PG8_MMA(1, 0, At, B0); PG8_MMA(1, 1, At, B1); PG8_BAR; PG8_SCHED;
;     ...
;         }
;         if constexpr (ALIGN_EPI) { if (wr == 0) PG8_BAR; }
	s_add_i32 s36, s55, s0
	v_lshl_add_u64 v[216:217], v[216:217], 0, s[16:17]
	s_mov_b32 m0, s36
	ds_read_b128 v[184:187], v166 offset:49152
	ds_read_b128 v[188:191], v166 offset:50176
	ds_read_b128 v[192:195], v166 offset:51200
	ds_read_b128 v[196:199], v166 offset:52224
	ds_read_b128 v[200:203], v166 offset:53248
	ds_read_b128 v[204:207], v166 offset:54272
	ds_read_b128 v[208:211], v166 offset:55296
	ds_read_b128 v[212:215], v166 offset:56320
	global_load_lds_dwordx4 v[216:217], off
	s_add_i32 m0, s36, 0x2000
	s_add_u32 s34, s34, 0x40080
	v_lshl_add_u64 v[216:217], v[218:219], 0, s[16:17]
	s_addc_u32 s35, s35, 0
	s_add_i32 s36, s56, s0
	global_load_lds_dwordx4 v[216:217], off
	v_lshl_add_u64 v[216:217], s[34:35], 0, v[140:141]
	s_mov_b32 m0, s36
	s_nop 0
	global_load_lds_dwordx4 v[216:217], off
	v_lshl_add_u64 v[216:217], s[34:35], 0, v[144:145]
	s_add_i32 m0, s36, 0x2000
	s_nop 0
	global_load_lds_dwordx4 v[216:217], off
	v_lshl_add_u64 v[216:217], v[220:221], 0, s[16:17]
	s_mov_b32 m0, s43
	s_nop 0
	global_load_lds_dwordx4 v[216:217], off
	v_lshl_add_u64 v[216:217], v[222:223], 0, s[16:17]
	s_mov_b32 m0, s44
	s_nop 0
	global_load_lds_dwordx4 v[216:217], off
	s_waitcnt vmcnt(8)
	s_waitcnt lgkmcnt(0)
	s_barrier
	s_waitcnt lgkmcnt(0)
	v_mfma_f32_16x16x32_bf16 v[62:65], v[130:133], v[184:187], v[62:65]
	v_mfma_f32_16x16x32_bf16 v[58:61], v[154:157], v[184:187], v[58:61]
	v_mfma_f32_16x16x32_bf16 v[46:49], v[130:133], v[192:195], v[46:49]
	v_mfma_f32_16x16x32_bf16 v[42:45], v[154:157], v[192:195], v[42:45]
	v_mfma_f32_16x16x32_bf16 v[30:33], v[130:133], v[200:203], v[30:33]
	v_mfma_f32_16x16x32_bf16 v[26:29], v[154:157], v[200:203], v[26:29]
	v_mfma_f32_16x16x32_bf16 v[14:17], v[130:133], v[208:211], v[14:17]
	v_mfma_f32_16x16x32_bf16 v[10:13], v[154:157], v[208:211], v[10:13]
	v_mfma_f32_16x16x32_bf16 v[62:65], v[134:137], v[188:191], v[62:65]
	v_mfma_f32_16x16x32_bf16 v[58:61], v[158:161], v[188:191], v[58:61]
	v_mfma_f32_16x16x32_bf16 v[46:49], v[134:137], v[196:199], v[46:49]
	v_mfma_f32_16x16x32_bf16 v[42:45], v[158:161], v[196:199], v[42:45]
	v_mfma_f32_16x16x32_bf16 v[30:33], v[134:137], v[204:207], v[30:33]
	v_mfma_f32_16x16x32_bf16 v[26:29], v[158:161], v[204:207], v[26:29]
	v_mfma_f32_16x16x32_bf16 v[14:17], v[134:137], v[212:215], v[14:17]
	v_mfma_f32_16x16x32_bf16 v[10:13], v[158:161], v[212:215], v[10:13]
	v_mfma_f32_16x16x32_bf16 v[54:57], v[168:171], v[184:187], v[54:57]
	v_mfma_f32_16x16x32_bf16 v[50:53], v[176:179], v[184:187], v[50:53]
	v_mfma_f32_16x16x32_bf16 v[38:41], v[168:171], v[192:195], v[38:41]
	v_mfma_f32_16x16x32_bf16 v[34:37], v[176:179], v[192:195], v[34:37]
	v_mfma_f32_16x16x32_bf16 v[22:25], v[168:171], v[200:203], v[22:25]
	v_mfma_f32_16x16x32_bf16 v[18:21], v[176:179], v[200:203], v[18:21]
	v_mfma_f32_16x16x32_bf16 v[6:9], v[168:171], v[208:211], v[6:9]
	v_mfma_f32_16x16x32_bf16 v[2:5], v[176:179], v[208:211], v[2:5]
	v_mfma_f32_16x16x32_bf16 v[54:57], v[172:175], v[188:191], v[54:57]
	v_mfma_f32_16x16x32_bf16 v[50:53], v[180:183], v[188:191], v[50:53]
	v_mfma_f32_16x16x32_bf16 v[38:41], v[172:175], v[196:199], v[38:41]
	v_mfma_f32_16x16x32_bf16 v[34:37], v[180:183], v[196:199], v[34:37]
	v_mfma_f32_16x16x32_bf16 v[22:25], v[172:175], v[204:207], v[22:25]
	v_mfma_f32_16x16x32_bf16 v[18:21], v[180:183], v[204:207], v[18:21]
	v_mfma_f32_16x16x32_bf16 v[6:9], v[172:175], v[212:215], v[6:9]
	v_mfma_f32_16x16x32_bf16 v[2:5], v[180:183], v[212:215], v[2:5]
	s_barrier
	s_add_i32 s54, s54, 2
	s_add_u32 s30, s30, 0x100
	s_addc_u32 s31, s31, 0
	s_add_u32 s52, s52, 0x100
	s_addc_u32 s53, s53, 0
	s_cmp_gt_u32 s54, 13
	s_cbranch_scc0 .LBB0_1467
	s_and_b64 vcc, exec, s[18:19]
	s_cbranch_vccz .LBB0_1470
	s_barrier
